# v36: v25 with GEMM K-loop priority toggling replaced by one static priority raise per GEMM phase for waves 4-7
# baseline (speedup 1.0000x reference)
.Lxb1_done:
.LBB0_391:
	s_or_b64 exec, exec, s[2:3]
	s_waitcnt lgkmcnt(0)
	s_barrier
	s_cmp_gt_u32 s68, 3
	s_cbranch_scc0 .Lprio2
	s_setprio 1
.Lprio2:
.LBB0_392:
	s_cmp_gt_i32 s58, 2
	s_cselect_b64 s[2:3], -1, 0
	s_cmp_lt_i32 s59, 3
	s_cselect_b64 s[4:5], -1, 0
	s_or_b64 s[2:3], s[2:3], s[4:5]
	s_and_b64 vcc, exec, s[2:3]
	s_cbranch_vccnz .LBB0_641
	v_mov_b32_e32 v131, 0
	s_waitcnt vmcnt(0)
	ds_read_b64 v[2:3], v131 offset:416
	s_cmpk_gt_i32 s30, 0xbf
	v_lshlrev_b32_e32 v1, 2, v0
	s_waitcnt lgkmcnt(0)
	v_readfirstlane_b32 s3, v2
	v_readfirstlane_b32 s5, v3
	s_cbranch_scc0 .LBB0_396
	s_cmpk_lg_i32 s56, 0x100
	s_mov_b64 s[2:3], -1
	s_cbranch_scc1 .LBB0_411

.LBB0_404:
	ds_read_b128 v[148:151], v145
	ds_read_b128 v[152:155], v145 offset:1024
	ds_read_b128 v[156:159], v145 offset:2048
	ds_read_b128 v[160:163], v145 offset:3072
	ds_read_b128 v[164:167], v146
	ds_read_b128 v[168:171], v146 offset:1024
	ds_read_b128 v[172:175], v146 offset:2048
	ds_read_b128 v[176:179], v146 offset:3072
	s_add_u32 s24, s22, 0x100
	s_addc_u32 s25, s23, 0
	s_cmp_eq_u32 s64, 12
	s_cselect_b32 s29, s17, s25
	s_cselect_b32 s28, s52, s24
	s_cselect_b32 s27, s53, s57
	s_cselect_b32 s26, s54, s55
	v_lshl_add_u64 v[196:197], s[22:23], 0, v[136:137]
	s_add_i32 m0, s11, 0xc400
	ds_read_b128 v[180:183], v147 offset:1024
	ds_read_b128 v[184:187], v147 offset:2048
	ds_read_b128 v[188:191], v147 offset:3072
	ds_read_b128 v[192:195], v147 offset:4096
	ds_read_b128 v[200:203], v147 offset:5120
	ds_read_b128 v[204:207], v147 offset:6144
	ds_read_b128 v[208:211], v147 offset:7168
	ds_read_b128 v[212:215], v147 offset:8192
	global_load_lds_dwordx4 v[196:197], off
	v_lshl_add_u64 v[196:197], s[22:23], 0, v[134:135]
	s_add_i32 m0, s11, 0xe400
	s_nop 0
	global_load_lds_dwordx4 v[196:197], off
	s_waitcnt vmcnt(8)
	s_waitcnt lgkmcnt(0)
	s_barrier
	s_waitcnt lgkmcnt(0)
	v_mfma_f32_16x16x32_bf16 v[126:129], v[148:151], v[180:183], v[126:129]
	v_mfma_f32_16x16x32_bf16 v[122:125], v[156:159], v[180:183], v[122:125]
	v_mfma_f32_16x16x32_bf16 v[118:121], v[148:151], v[188:191], v[118:121]
	v_mfma_f32_16x16x32_bf16 v[114:117], v[156:159], v[188:191], v[114:117]
	v_mfma_f32_16x16x32_bf16 v[110:113], v[148:151], v[200:203], v[110:113]
	v_mfma_f32_16x16x32_bf16 v[106:109], v[156:159], v[200:203], v[106:109]
	v_mfma_f32_16x16x32_bf16 v[98:101], v[148:151], v[208:211], v[98:101]
	v_mfma_f32_16x16x32_bf16 v[90:93], v[156:159], v[208:211], v[90:93]
	v_mfma_f32_16x16x32_bf16 v[126:129], v[152:155], v[184:187], v[126:129]
	v_mfma_f32_16x16x32_bf16 v[122:125], v[160:163], v[184:187], v[122:125]
	v_mfma_f32_16x16x32_bf16 v[118:121], v[152:155], v[192:195], v[118:121]
	v_mfma_f32_16x16x32_bf16 v[114:117], v[160:163], v[192:195], v[114:117]
	v_mfma_f32_16x16x32_bf16 v[110:113], v[152:155], v[204:207], v[110:113]
	v_mfma_f32_16x16x32_bf16 v[106:109], v[160:163], v[204:207], v[106:109]
	v_mfma_f32_16x16x32_bf16 v[98:101], v[152:155], v[212:215], v[98:101]
	v_mfma_f32_16x16x32_bf16 v[90:93], v[160:163], v[212:215], v[90:93]
	v_mfma_f32_16x16x32_bf16 v[102:105], v[164:167], v[180:183], v[102:105]
	v_mfma_f32_16x16x32_bf16 v[94:97], v[172:175], v[180:183], v[94:97]
	v_mfma_f32_16x16x32_bf16 v[86:89], v[164:167], v[188:191], v[86:89]
	v_mfma_f32_16x16x32_bf16 v[82:85], v[172:175], v[188:191], v[82:85]
	v_mfma_f32_16x16x32_bf16 v[78:81], v[164:167], v[200:203], v[78:81]
	v_mfma_f32_16x16x32_bf16 v[74:77], v[172:175], v[200:203], v[74:77]
	v_mfma_f32_16x16x32_bf16 v[70:73], v[164:167], v[208:211], v[70:73]
	v_mfma_f32_16x16x32_bf16 v[66:69], v[172:175], v[208:211], v[66:69]
	v_mfma_f32_16x16x32_bf16 v[102:105], v[168:171], v[184:187], v[102:105]
	v_mfma_f32_16x16x32_bf16 v[94:97], v[176:179], v[184:187], v[94:97]
	v_mfma_f32_16x16x32_bf16 v[86:89], v[168:171], v[192:195], v[86:89]
	v_mfma_f32_16x16x32_bf16 v[82:85], v[176:179], v[192:195], v[82:85]
	v_mfma_f32_16x16x32_bf16 v[78:81], v[168:171], v[204:207], v[78:81]
	v_mfma_f32_16x16x32_bf16 v[74:77], v[176:179], v[204:207], v[74:77]
	v_mfma_f32_16x16x32_bf16 v[70:73], v[168:171], v[212:215], v[70:73]
	v_mfma_f32_16x16x32_bf16 v[66:69], v[176:179], v[212:215], v[66:69]
	s_barrier
	s_add_i32 s22, s49, s38
	v_lshl_add_u64 v[196:197], s[26:27], 0, v[130:131]
	s_mov_b32 m0, s22
	ds_read_b128 v[180:183], v147 offset:17408
	ds_read_b128 v[184:187], v147 offset:18432
	ds_read_b128 v[188:191], v147 offset:19456
	ds_read_b128 v[192:195], v147 offset:20480
	ds_read_b128 v[200:203], v147 offset:21504
	ds_read_b128 v[204:207], v147 offset:22528
	ds_read_b128 v[208:211], v147 offset:23552
	ds_read_b128 v[212:215], v147 offset:24576
	global_load_lds_dwordx4 v[196:197], off
	s_add_i32 m0, s22, 0x2000
	s_add_u32 s22, s26, 0x40000
	v_lshl_add_u64 v[216:217], s[26:27], 0, v[132:133]
	s_addc_u32 s23, s27, 0
	s_add_i32 s65, s50, s38
	global_load_lds_dwordx4 v[216:217], off
	v_lshl_add_u64 v[218:219], s[22:23], 0, v[130:131]
	s_mov_b32 m0, s65
	v_lshl_add_u64 v[220:221], s[28:29], 0, v[132:133]
	global_load_lds_dwordx4 v[218:219], off
	v_lshl_add_u64 v[218:219], s[22:23], 0, v[132:133]
	s_add_i32 m0, s65, 0x2000
	s_nop 0
	global_load_lds_dwordx4 v[218:219], off
	v_lshl_add_u64 v[218:219], s[28:29], 0, v[130:131]
	s_mov_b32 m0, s40
	s_nop 0
	global_load_lds_dwordx4 v[218:219], off
	s_mov_b32 m0, s41
	s_nop 0
	global_load_lds_dwordx4 v[220:221], off
	s_waitcnt vmcnt(8)
	s_waitcnt lgkmcnt(0)
	s_barrier
	s_waitcnt lgkmcnt(0)
	v_mfma_f32_16x16x32_bf16 v[62:65], v[148:151], v[180:183], v[62:65]
	v_mfma_f32_16x16x32_bf16 v[58:61], v[156:159], v[180:183], v[58:61]
	v_mfma_f32_16x16x32_bf16 v[54:57], v[148:151], v[188:191], v[54:57]
	v_mfma_f32_16x16x32_bf16 v[50:53], v[156:159], v[188:191], v[50:53]
	v_mfma_f32_16x16x32_bf16 v[46:49], v[148:151], v[200:203], v[46:49]
	v_mfma_f32_16x16x32_bf16 v[42:45], v[156:159], v[200:203], v[42:45]
	v_mfma_f32_16x16x32_bf16 v[34:37], v[148:151], v[208:211], v[34:37]
	v_mfma_f32_16x16x32_bf16 v[26:29], v[156:159], v[208:211], v[26:29]
	v_mfma_f32_16x16x32_bf16 v[62:65], v[152:155], v[184:187], v[62:65]
	v_mfma_f32_16x16x32_bf16 v[58:61], v[160:163], v[184:187], v[58:61]
	v_mfma_f32_16x16x32_bf16 v[54:57], v[152:155], v[192:195], v[54:57]
	v_mfma_f32_16x16x32_bf16 v[50:53], v[160:163], v[192:195], v[50:53]
	v_mfma_f32_16x16x32_bf16 v[46:49], v[152:155], v[204:207], v[46:49]
	v_mfma_f32_16x16x32_bf16 v[42:45], v[160:163], v[204:207], v[42:45]
	v_mfma_f32_16x16x32_bf16 v[34:37], v[152:155], v[212:215], v[34:37]
	v_mfma_f32_16x16x32_bf16 v[26:29], v[160:163], v[212:215], v[26:29]
	v_mfma_f32_16x16x32_bf16 v[38:41], v[164:167], v[180:183], v[38:41]
	v_mfma_f32_16x16x32_bf16 v[30:33], v[172:175], v[180:183], v[30:33]
	v_mfma_f32_16x16x32_bf16 v[22:25], v[164:167], v[188:191], v[22:25]
	v_mfma_f32_16x16x32_bf16 v[18:21], v[172:175], v[188:191], v[18:21]
	v_mfma_f32_16x16x32_bf16 v[14:17], v[164:167], v[200:203], v[14:17]
	v_mfma_f32_16x16x32_bf16 v[10:13], v[172:175], v[200:203], v[10:13]
	v_mfma_f32_16x16x32_bf16 v[6:9], v[164:167], v[208:211], v[6:9]
	v_mfma_f32_16x16x32_bf16 v[2:5], v[172:175], v[208:211], v[2:5]
	v_mfma_f32_16x16x32_bf16 v[38:41], v[168:171], v[184:187], v[38:41]
	v_mfma_f32_16x16x32_bf16 v[30:33], v[176:179], v[184:187], v[30:33]
	v_mfma_f32_16x16x32_bf16 v[22:25], v[168:171], v[192:195], v[22:25]
	v_mfma_f32_16x16x32_bf16 v[18:21], v[176:179], v[192:195], v[18:21]
	v_mfma_f32_16x16x32_bf16 v[14:17], v[168:171], v[204:207], v[14:17]
	v_mfma_f32_16x16x32_bf16 v[10:13], v[176:179], v[204:207], v[10:13]
	v_mfma_f32_16x16x32_bf16 v[6:9], v[168:171], v[212:215], v[6:9]
	v_mfma_f32_16x16x32_bf16 v[2:5], v[176:179], v[212:215], v[2:5]
	s_barrier
	s_add_i32 s65, 0, 0x18400
	s_add_i32 s66, 0, 0x1c400
	v_add_u32_e32 v160, s65, v142
	v_add_u32_e32 v176, s66, v142
	ds_read_b128 v[148:151], v160
	ds_read_b128 v[152:155], v160 offset:1024
	ds_read_b128 v[156:159], v160 offset:2048
	ds_read_b128 v[160:163], v160 offset:3072
	ds_read_b128 v[164:167], v176
	ds_read_b128 v[168:171], v176 offset:1024
	ds_read_b128 v[172:175], v176 offset:2048
	ds_read_b128 v[176:179], v176 offset:3072
	s_add_u32 s22, s28, 0x40000
	s_addc_u32 s23, s29, 0
	s_mov_b32 m0, s42
	v_lshl_add_u64 v[222:223], s[22:23], 0, v[130:131]
	ds_read_b128 v[180:183], v147 offset:33792
	ds_read_b128 v[184:187], v147 offset:34816
	ds_read_b128 v[188:191], v147 offset:35840
	ds_read_b128 v[192:195], v147 offset:36864
	ds_read_b128 v[200:203], v147 offset:37888
	ds_read_b128 v[204:207], v147 offset:38912
	ds_read_b128 v[208:211], v147 offset:39936
	ds_read_b128 v[212:215], v147 offset:40960
	global_load_lds_dwordx4 v[222:223], off
	v_lshl_add_u64 v[222:223], s[22:23], 0, v[132:133]
	s_mov_b32 m0, s43
	s_nop 0
	global_load_lds_dwordx4 v[222:223], off
	s_waitcnt vmcnt(8)
	s_waitcnt lgkmcnt(0)
	s_barrier
	s_waitcnt lgkmcnt(0)
	v_mfma_f32_16x16x32_bf16 v[126:129], v[148:151], v[180:183], v[126:129]
	v_mfma_f32_16x16x32_bf16 v[122:125], v[156:159], v[180:183], v[122:125]
	v_mfma_f32_16x16x32_bf16 v[118:121], v[148:151], v[188:191], v[118:121]
	v_mfma_f32_16x16x32_bf16 v[114:117], v[156:159], v[188:191], v[114:117]
	v_mfma_f32_16x16x32_bf16 v[110:113], v[148:151], v[200:203], v[110:113]
	v_mfma_f32_16x16x32_bf16 v[106:109], v[156:159], v[200:203], v[106:109]
	v_mfma_f32_16x16x32_bf16 v[98:101], v[148:151], v[208:211], v[98:101]
	v_mfma_f32_16x16x32_bf16 v[90:93], v[156:159], v[208:211], v[90:93]
	v_mfma_f32_16x16x32_bf16 v[126:129], v[152:155], v[184:187], v[126:129]
	v_mfma_f32_16x16x32_bf16 v[122:125], v[160:163], v[184:187], v[122:125]
	v_mfma_f32_16x16x32_bf16 v[118:121], v[152:155], v[192:195], v[118:121]
	v_mfma_f32_16x16x32_bf16 v[114:117], v[160:163], v[192:195], v[114:117]
	v_mfma_f32_16x16x32_bf16 v[110:113], v[152:155], v[204:207], v[110:113]
	v_mfma_f32_16x16x32_bf16 v[106:109], v[160:163], v[204:207], v[106:109]
	v_mfma_f32_16x16x32_bf16 v[98:101], v[152:155], v[212:215], v[98:101]
	v_mfma_f32_16x16x32_bf16 v[90:93], v[160:163], v[212:215], v[90:93]
	v_mfma_f32_16x16x32_bf16 v[102:105], v[164:167], v[180:183], v[102:105]
	v_mfma_f32_16x16x32_bf16 v[94:97], v[172:175], v[180:183], v[94:97]
	v_mfma_f32_16x16x32_bf16 v[86:89], v[164:167], v[188:191], v[86:89]
	v_mfma_f32_16x16x32_bf16 v[82:85], v[172:175], v[188:191], v[82:85]
	v_mfma_f32_16x16x32_bf16 v[78:81], v[164:167], v[200:203], v[78:81]
	v_mfma_f32_16x16x32_bf16 v[74:77], v[172:175], v[200:203], v[74:77]
	v_mfma_f32_16x16x32_bf16 v[70:73], v[164:167], v[208:211], v[70:73]
	v_mfma_f32_16x16x32_bf16 v[66:69], v[172:175], v[208:211], v[66:69]
	v_mfma_f32_16x16x32_bf16 v[102:105], v[168:171], v[184:187], v[102:105]
	v_mfma_f32_16x16x32_bf16 v[94:97], v[176:179], v[184:187], v[94:97]
	v_mfma_f32_16x16x32_bf16 v[86:89], v[168:171], v[192:195], v[86:89]
	v_mfma_f32_16x16x32_bf16 v[82:85], v[176:179], v[192:195], v[82:85]
	v_mfma_f32_16x16x32_bf16 v[78:81], v[168:171], v[204:207], v[78:81]
	v_mfma_f32_16x16x32_bf16 v[74:77], v[176:179], v[204:207], v[74:77]
	v_mfma_f32_16x16x32_bf16 v[70:73], v[168:171], v[212:215], v[70:73]
	v_mfma_f32_16x16x32_bf16 v[66:69], v[176:179], v[212:215], v[66:69]
	s_barrier
	s_add_i32 s22, s65, s38
	v_lshl_add_u64 v[196:197], v[196:197], 0, s[12:13]
	s_mov_b32 m0, s22
	ds_read_b128 v[180:183], v147 offset:50176
	ds_read_b128 v[184:187], v147 offset:51200
	ds_read_b128 v[188:191], v147 offset:52224
	ds_read_b128 v[192:195], v147 offset:53248
	ds_read_b128 v[200:203], v147 offset:54272
	ds_read_b128 v[204:207], v147 offset:55296
	ds_read_b128 v[208:211], v147 offset:56320
	ds_read_b128 v[212:215], v147 offset:57344
	global_load_lds_dwordx4 v[196:197], off
	s_add_i32 m0, s22, 0x2000
	s_add_u32 s22, s26, 0x40080
	v_lshl_add_u64 v[196:197], v[216:217], 0, s[12:13]
	s_addc_u32 s23, s27, 0
	s_add_i32 s26, s66, s38
	global_load_lds_dwordx4 v[196:197], off
	v_lshl_add_u64 v[196:197], s[22:23], 0, v[130:131]
	s_mov_b32 m0, s26
	s_nop 0
	global_load_lds_dwordx4 v[196:197], off
	v_lshl_add_u64 v[196:197], s[22:23], 0, v[132:133]
	s_add_i32 m0, s26, 0x2000
	s_nop 0
	global_load_lds_dwordx4 v[196:197], off
	v_lshl_add_u64 v[196:197], v[218:219], 0, s[12:13]
	s_mov_b32 m0, s45
	s_nop 0
	global_load_lds_dwordx4 v[196:197], off
	v_lshl_add_u64 v[196:197], v[220:221], 0, s[12:13]
	s_mov_b32 m0, s46
	s_nop 0
	global_load_lds_dwordx4 v[196:197], off
	s_waitcnt vmcnt(8)
	s_waitcnt lgkmcnt(0)
	s_barrier
	s_waitcnt lgkmcnt(0)
	v_mfma_f32_16x16x32_bf16 v[62:65], v[148:151], v[180:183], v[62:65]
	v_mfma_f32_16x16x32_bf16 v[58:61], v[156:159], v[180:183], v[58:61]
	v_mfma_f32_16x16x32_bf16 v[54:57], v[148:151], v[188:191], v[54:57]
	v_mfma_f32_16x16x32_bf16 v[50:53], v[156:159], v[188:191], v[50:53]
	v_mfma_f32_16x16x32_bf16 v[46:49], v[148:151], v[200:203], v[46:49]
	v_mfma_f32_16x16x32_bf16 v[42:45], v[156:159], v[200:203], v[42:45]
	v_mfma_f32_16x16x32_bf16 v[34:37], v[148:151], v[208:211], v[34:37]
	v_mfma_f32_16x16x32_bf16 v[26:29], v[156:159], v[208:211], v[26:29]
	v_mfma_f32_16x16x32_bf16 v[62:65], v[152:155], v[184:187], v[62:65]
	v_mfma_f32_16x16x32_bf16 v[58:61], v[160:163], v[184:187], v[58:61]
	v_mfma_f32_16x16x32_bf16 v[54:57], v[152:155], v[192:195], v[54:57]
	v_mfma_f32_16x16x32_bf16 v[50:53], v[160:163], v[192:195], v[50:53]
	v_mfma_f32_16x16x32_bf16 v[46:49], v[152:155], v[204:207], v[46:49]
	v_mfma_f32_16x16x32_bf16 v[42:45], v[160:163], v[204:207], v[42:45]
	v_mfma_f32_16x16x32_bf16 v[34:37], v[152:155], v[212:215], v[34:37]
	v_mfma_f32_16x16x32_bf16 v[26:29], v[160:163], v[212:215], v[26:29]
	v_mfma_f32_16x16x32_bf16 v[38:41], v[164:167], v[180:183], v[38:41]
	v_mfma_f32_16x16x32_bf16 v[30:33], v[172:175], v[180:183], v[30:33]
	v_mfma_f32_16x16x32_bf16 v[22:25], v[164:167], v[188:191], v[22:25]
	v_mfma_f32_16x16x32_bf16 v[18:21], v[172:175], v[188:191], v[18:21]
	v_mfma_f32_16x16x32_bf16 v[14:17], v[164:167], v[200:203], v[14:17]
	v_mfma_f32_16x16x32_bf16 v[10:13], v[172:175], v[200:203], v[10:13]
	v_mfma_f32_16x16x32_bf16 v[6:9], v[164:167], v[208:211], v[6:9]
	v_mfma_f32_16x16x32_bf16 v[2:5], v[172:175], v[208:211], v[2:5]
	v_mfma_f32_16x16x32_bf16 v[38:41], v[168:171], v[184:187], v[38:41]
	v_mfma_f32_16x16x32_bf16 v[30:33], v[176:179], v[184:187], v[30:33]
	v_mfma_f32_16x16x32_bf16 v[22:25], v[168:171], v[192:195], v[22:25]
	v_mfma_f32_16x16x32_bf16 v[18:21], v[176:179], v[192:195], v[18:21]
	v_mfma_f32_16x16x32_bf16 v[14:17], v[168:171], v[204:207], v[14:17]
	v_mfma_f32_16x16x32_bf16 v[10:13], v[176:179], v[204:207], v[10:13]
	v_mfma_f32_16x16x32_bf16 v[6:9], v[168:171], v[212:215], v[6:9]
	v_mfma_f32_16x16x32_bf16 v[2:5], v[176:179], v[212:215], v[2:5]
	s_barrier
	s_add_i32 s64, s64, 2
	s_add_u32 s55, s55, 0x100
	s_addc_u32 s57, s57, 0
	s_cmp_gt_u32 s64, 13
	s_mov_b64 s[22:23], s[24:25]
	s_cbranch_scc0 .LBB0_404
	s_and_b64 vcc, exec, s[14:15]
	s_cbranch_vccz .LBB0_407
	s_barrier

.LBB0_587:
	s_cmp_lt_i32 s59, 4
	s_waitcnt vmcnt(0)
	s_barrier
	s_cbranch_scc1 .LBB0_641
	s_waitcnt vmcnt(0)
	s_setprio 0
	s_barrier
	s_and_saveexec_b64 s[2:3], s[0:1]
	s_cbranch_execz .LBB0_640
	s_waitcnt vmcnt(0) lgkmcnt(0)
	v_mov_b32_e32 v241, 0
	v_lshlrev_b32_e64 v254, 8, s31
	v_mov_b32_e32 v247, 1
	v_mov_b32_e32 v246, 0x3600
	global_atomic_add v248, v246, v247, s[60:61] sc0

.Lprio7:
.LBB0_1160:
	s_cmp_gt_i32 s58, 8
	s_cselect_b64 s[2:3], -1, 0
	s_cmp_lt_i32 s59, 9
	s_cselect_b64 s[4:5], -1, 0
	s_or_b64 s[2:3], s[2:3], s[4:5]
	s_and_b64 vcc, exec, s[2:3]
	s_cbranch_vccnz .LBB0_1339
	v_mov_b32_e32 v131, 0
	s_waitcnt vmcnt(0)
	ds_read_b64 v[2:3], v131 offset:416
	s_cmpk_gt_i32 s30, 0xbf
	v_lshlrev_b32_e32 v1, 2, v0
	s_waitcnt lgkmcnt(0)
	v_readfirstlane_b32 s3, v2
	v_readfirstlane_b32 s4, v3
	s_cbranch_scc0 .LBB0_1164
	s_cmpk_lg_i32 s56, 0x100
	s_mov_b64 s[2:3], -1
	s_cbranch_scc1 .LBB0_1181

.LBB0_1174:
	ds_read_b128 v[152:155], v149
	ds_read_b128 v[156:159], v149 offset:1024
	ds_read_b128 v[160:163], v149 offset:2048
	ds_read_b128 v[164:167], v149 offset:3072
	ds_read_b128 v[168:171], v150
	ds_read_b128 v[172:175], v150 offset:1024
	ds_read_b128 v[176:179], v150 offset:2048
	ds_read_b128 v[180:183], v150 offset:3072
	s_add_u32 s4, s24, 0x100
	s_addc_u32 s5, s25, 0
	s_cmp_eq_u32 s64, 4
	s_cselect_b32 s29, s19, s5
	s_cselect_b32 s28, s54, s4
	s_cselect_b32 s27, s21, s57
	s_cselect_b32 s26, s20, s55
	v_lshl_add_u64 v[196:197], s[24:25], 0, v[140:141]
	s_add_i32 m0, s17, 0xc400
	ds_read_b128 v[184:187], v151 offset:1024
	ds_read_b128 v[188:191], v151 offset:2048
	ds_read_b128 v[192:195], v151 offset:3072
	ds_read_b128 v[200:203], v151 offset:4096
	ds_read_b128 v[204:207], v151 offset:5120
	ds_read_b128 v[208:211], v151 offset:6144
	ds_read_b128 v[212:215], v151 offset:7168
	ds_read_b128 v[216:219], v151 offset:8192
	global_load_lds_dwordx4 v[196:197], off
	v_lshl_add_u64 v[196:197], s[24:25], 0, v[138:139]
	s_add_i32 m0, s17, 0xe400
	s_nop 0
	global_load_lds_dwordx4 v[196:197], off
	s_waitcnt vmcnt(8)
	s_waitcnt lgkmcnt(0)
	s_barrier
	s_waitcnt lgkmcnt(0)
	v_mfma_f32_16x16x32_bf16 v[126:129], v[152:155], v[184:187], v[126:129]
	v_mfma_f32_16x16x32_bf16 v[122:125], v[160:163], v[184:187], v[122:125]
	v_mfma_f32_16x16x32_bf16 v[118:121], v[152:155], v[192:195], v[118:121]
	v_mfma_f32_16x16x32_bf16 v[114:117], v[160:163], v[192:195], v[114:117]
	v_mfma_f32_16x16x32_bf16 v[102:105], v[152:155], v[204:207], v[102:105]
	v_mfma_f32_16x16x32_bf16 v[98:101], v[160:163], v[204:207], v[98:101]
	v_mfma_f32_16x16x32_bf16 v[86:89], v[152:155], v[212:215], v[86:89]
	v_mfma_f32_16x16x32_bf16 v[82:85], v[160:163], v[212:215], v[82:85]
	v_mfma_f32_16x16x32_bf16 v[126:129], v[156:159], v[188:191], v[126:129]
	v_mfma_f32_16x16x32_bf16 v[122:125], v[164:167], v[188:191], v[122:125]
	v_mfma_f32_16x16x32_bf16 v[118:121], v[156:159], v[200:203], v[118:121]
	v_mfma_f32_16x16x32_bf16 v[114:117], v[164:167], v[200:203], v[114:117]
	v_mfma_f32_16x16x32_bf16 v[102:105], v[156:159], v[208:211], v[102:105]
	v_mfma_f32_16x16x32_bf16 v[98:101], v[164:167], v[208:211], v[98:101]
	v_mfma_f32_16x16x32_bf16 v[86:89], v[156:159], v[216:219], v[86:89]
	v_mfma_f32_16x16x32_bf16 v[82:85], v[164:167], v[216:219], v[82:85]
	v_mfma_f32_16x16x32_bf16 v[110:113], v[168:171], v[184:187], v[110:113]
	v_mfma_f32_16x16x32_bf16 v[106:109], v[176:179], v[184:187], v[106:109]
	v_mfma_f32_16x16x32_bf16 v[94:97], v[168:171], v[192:195], v[94:97]
	v_mfma_f32_16x16x32_bf16 v[90:93], v[176:179], v[192:195], v[90:93]
	v_mfma_f32_16x16x32_bf16 v[78:81], v[168:171], v[204:207], v[78:81]
	v_mfma_f32_16x16x32_bf16 v[74:77], v[176:179], v[204:207], v[74:77]
	v_mfma_f32_16x16x32_bf16 v[70:73], v[168:171], v[212:215], v[70:73]
	v_mfma_f32_16x16x32_bf16 v[66:69], v[176:179], v[212:215], v[66:69]
	v_mfma_f32_16x16x32_bf16 v[110:113], v[172:175], v[188:191], v[110:113]
	v_mfma_f32_16x16x32_bf16 v[106:109], v[180:183], v[188:191], v[106:109]
	v_mfma_f32_16x16x32_bf16 v[94:97], v[172:175], v[200:203], v[94:97]
	v_mfma_f32_16x16x32_bf16 v[90:93], v[180:183], v[200:203], v[90:93]
	v_mfma_f32_16x16x32_bf16 v[78:81], v[172:175], v[208:211], v[78:81]
	v_mfma_f32_16x16x32_bf16 v[74:77], v[180:183], v[208:211], v[74:77]
	v_mfma_f32_16x16x32_bf16 v[70:73], v[172:175], v[216:219], v[70:73]
	v_mfma_f32_16x16x32_bf16 v[66:69], v[180:183], v[216:219], v[66:69]
	s_barrier
	s_add_i32 s24, s49, s38
	v_lshl_add_u64 v[196:197], s[26:27], 0, v[130:131]
	s_mov_b32 m0, s24
	ds_read_b128 v[184:187], v151 offset:17408
	ds_read_b128 v[188:191], v151 offset:18432
	ds_read_b128 v[192:195], v151 offset:19456
	ds_read_b128 v[200:203], v151 offset:20480
	ds_read_b128 v[204:207], v151 offset:21504
	ds_read_b128 v[208:211], v151 offset:22528
	ds_read_b128 v[212:215], v151 offset:23552
	ds_read_b128 v[216:219], v151 offset:24576
	global_load_lds_dwordx4 v[196:197], off
	s_add_i32 m0, s24, 0x2000
	s_add_u32 s24, s26, 0x40000
	v_lshl_add_u64 v[220:221], s[26:27], 0, v[132:133]
	s_addc_u32 s25, s27, 0
	s_add_i32 s65, s50, s38
	global_load_lds_dwordx4 v[220:221], off
	v_lshl_add_u64 v[222:223], s[24:25], 0, v[130:131]
	s_mov_b32 m0, s65
	v_lshl_add_u64 v[224:225], s[28:29], 0, v[134:135]
	global_load_lds_dwordx4 v[222:223], off
	v_lshl_add_u64 v[222:223], s[24:25], 0, v[132:133]
	s_add_i32 m0, s65, 0x2000
	s_nop 0
	global_load_lds_dwordx4 v[222:223], off
	v_lshl_add_u64 v[222:223], s[28:29], 0, v[136:137]
	s_mov_b32 m0, s40
	s_nop 0
	global_load_lds_dwordx4 v[222:223], off
	s_mov_b32 m0, s41
	s_nop 0
	global_load_lds_dwordx4 v[224:225], off
	s_waitcnt vmcnt(8)
	s_waitcnt lgkmcnt(0)
	s_barrier
	s_waitcnt lgkmcnt(0)
	v_mfma_f32_16x16x32_bf16 v[62:65], v[152:155], v[184:187], v[62:65]
	v_mfma_f32_16x16x32_bf16 v[58:61], v[160:163], v[184:187], v[58:61]
	v_mfma_f32_16x16x32_bf16 v[54:57], v[152:155], v[192:195], v[54:57]
	v_mfma_f32_16x16x32_bf16 v[50:53], v[160:163], v[192:195], v[50:53]
	v_mfma_f32_16x16x32_bf16 v[38:41], v[152:155], v[204:207], v[38:41]
	v_mfma_f32_16x16x32_bf16 v[34:37], v[160:163], v[204:207], v[34:37]
	v_mfma_f32_16x16x32_bf16 v[22:25], v[152:155], v[212:215], v[22:25]
	v_mfma_f32_16x16x32_bf16 v[18:21], v[160:163], v[212:215], v[18:21]
	v_mfma_f32_16x16x32_bf16 v[62:65], v[156:159], v[188:191], v[62:65]
	v_mfma_f32_16x16x32_bf16 v[58:61], v[164:167], v[188:191], v[58:61]
	v_mfma_f32_16x16x32_bf16 v[54:57], v[156:159], v[200:203], v[54:57]
	v_mfma_f32_16x16x32_bf16 v[50:53], v[164:167], v[200:203], v[50:53]
	v_mfma_f32_16x16x32_bf16 v[38:41], v[156:159], v[208:211], v[38:41]
	v_mfma_f32_16x16x32_bf16 v[34:37], v[164:167], v[208:211], v[34:37]
	v_mfma_f32_16x16x32_bf16 v[22:25], v[156:159], v[216:219], v[22:25]
	v_mfma_f32_16x16x32_bf16 v[18:21], v[164:167], v[216:219], v[18:21]
	v_mfma_f32_16x16x32_bf16 v[46:49], v[168:171], v[184:187], v[46:49]
	v_mfma_f32_16x16x32_bf16 v[42:45], v[176:179], v[184:187], v[42:45]
	v_mfma_f32_16x16x32_bf16 v[30:33], v[168:171], v[192:195], v[30:33]
	v_mfma_f32_16x16x32_bf16 v[26:29], v[176:179], v[192:195], v[26:29]
	v_mfma_f32_16x16x32_bf16 v[14:17], v[168:171], v[204:207], v[14:17]
	v_mfma_f32_16x16x32_bf16 v[10:13], v[176:179], v[204:207], v[10:13]
	v_mfma_f32_16x16x32_bf16 v[6:9], v[168:171], v[212:215], v[6:9]
	v_mfma_f32_16x16x32_bf16 v[2:5], v[176:179], v[212:215], v[2:5]
	v_mfma_f32_16x16x32_bf16 v[46:49], v[172:175], v[188:191], v[46:49]
	v_mfma_f32_16x16x32_bf16 v[42:45], v[180:183], v[188:191], v[42:45]
	v_mfma_f32_16x16x32_bf16 v[30:33], v[172:175], v[200:203], v[30:33]
	v_mfma_f32_16x16x32_bf16 v[26:29], v[180:183], v[200:203], v[26:29]
	v_mfma_f32_16x16x32_bf16 v[14:17], v[172:175], v[208:211], v[14:17]
	v_mfma_f32_16x16x32_bf16 v[10:13], v[180:183], v[208:211], v[10:13]
	v_mfma_f32_16x16x32_bf16 v[6:9], v[172:175], v[216:219], v[6:9]
	v_mfma_f32_16x16x32_bf16 v[2:5], v[180:183], v[216:219], v[2:5]
	s_barrier
	s_add_i32 s65, 0, 0x18400
	s_add_i32 s66, 0, 0x1c400
	v_add_u32_e32 v164, s65, v147
	v_add_u32_e32 v180, s66, v147
	ds_read_b128 v[152:155], v164
	ds_read_b128 v[156:159], v164 offset:1024
	ds_read_b128 v[160:163], v164 offset:2048
	ds_read_b128 v[164:167], v164 offset:3072
	ds_read_b128 v[168:171], v180
	ds_read_b128 v[172:175], v180 offset:1024
	ds_read_b128 v[176:179], v180 offset:2048
	ds_read_b128 v[180:183], v180 offset:3072
	s_add_u32 s24, s28, 0x40000
	s_addc_u32 s25, s29, 0
	s_mov_b32 m0, s42
	v_lshl_add_u64 v[226:227], s[24:25], 0, v[136:137]
	ds_read_b128 v[184:187], v151 offset:33792
	ds_read_b128 v[188:191], v151 offset:34816
	ds_read_b128 v[192:195], v151 offset:35840
	ds_read_b128 v[200:203], v151 offset:36864
	ds_read_b128 v[204:207], v151 offset:37888
	ds_read_b128 v[208:211], v151 offset:38912
	ds_read_b128 v[212:215], v151 offset:39936
	ds_read_b128 v[216:219], v151 offset:40960
	global_load_lds_dwordx4 v[226:227], off
	v_lshl_add_u64 v[226:227], s[24:25], 0, v[134:135]
	s_mov_b32 m0, s43
	s_nop 0
	global_load_lds_dwordx4 v[226:227], off
	s_waitcnt vmcnt(8)
	s_waitcnt lgkmcnt(0)
	s_barrier
	s_waitcnt lgkmcnt(0)
	v_mfma_f32_16x16x32_bf16 v[126:129], v[152:155], v[184:187], v[126:129]
	v_mfma_f32_16x16x32_bf16 v[122:125], v[160:163], v[184:187], v[122:125]
	v_mfma_f32_16x16x32_bf16 v[118:121], v[152:155], v[192:195], v[118:121]
	v_mfma_f32_16x16x32_bf16 v[114:117], v[160:163], v[192:195], v[114:117]
	v_mfma_f32_16x16x32_bf16 v[102:105], v[152:155], v[204:207], v[102:105]
	v_mfma_f32_16x16x32_bf16 v[98:101], v[160:163], v[204:207], v[98:101]
	v_mfma_f32_16x16x32_bf16 v[86:89], v[152:155], v[212:215], v[86:89]
	v_mfma_f32_16x16x32_bf16 v[82:85], v[160:163], v[212:215], v[82:85]
	v_mfma_f32_16x16x32_bf16 v[126:129], v[156:159], v[188:191], v[126:129]
	v_mfma_f32_16x16x32_bf16 v[122:125], v[164:167], v[188:191], v[122:125]
	v_mfma_f32_16x16x32_bf16 v[118:121], v[156:159], v[200:203], v[118:121]
	v_mfma_f32_16x16x32_bf16 v[114:117], v[164:167], v[200:203], v[114:117]
	v_mfma_f32_16x16x32_bf16 v[102:105], v[156:159], v[208:211], v[102:105]
	v_mfma_f32_16x16x32_bf16 v[98:101], v[164:167], v[208:211], v[98:101]
	v_mfma_f32_16x16x32_bf16 v[86:89], v[156:159], v[216:219], v[86:89]
	v_mfma_f32_16x16x32_bf16 v[82:85], v[164:167], v[216:219], v[82:85]
	v_mfma_f32_16x16x32_bf16 v[110:113], v[168:171], v[184:187], v[110:113]
	v_mfma_f32_16x16x32_bf16 v[106:109], v[176:179], v[184:187], v[106:109]
	v_mfma_f32_16x16x32_bf16 v[94:97], v[168:171], v[192:195], v[94:97]
	v_mfma_f32_16x16x32_bf16 v[90:93], v[176:179], v[192:195], v[90:93]
	v_mfma_f32_16x16x32_bf16 v[78:81], v[168:171], v[204:207], v[78:81]
	v_mfma_f32_16x16x32_bf16 v[74:77], v[176:179], v[204:207], v[74:77]
	v_mfma_f32_16x16x32_bf16 v[70:73], v[168:171], v[212:215], v[70:73]
	v_mfma_f32_16x16x32_bf16 v[66:69], v[176:179], v[212:215], v[66:69]
	v_mfma_f32_16x16x32_bf16 v[110:113], v[172:175], v[188:191], v[110:113]
	v_mfma_f32_16x16x32_bf16 v[106:109], v[180:183], v[188:191], v[106:109]
	v_mfma_f32_16x16x32_bf16 v[94:97], v[172:175], v[200:203], v[94:97]
	v_mfma_f32_16x16x32_bf16 v[90:93], v[180:183], v[200:203], v[90:93]
	v_mfma_f32_16x16x32_bf16 v[78:81], v[172:175], v[208:211], v[78:81]
	v_mfma_f32_16x16x32_bf16 v[74:77], v[180:183], v[208:211], v[74:77]
	v_mfma_f32_16x16x32_bf16 v[70:73], v[172:175], v[216:219], v[70:73]
	v_mfma_f32_16x16x32_bf16 v[66:69], v[180:183], v[216:219], v[66:69]
	s_barrier
	s_add_i32 s24, s65, s38
	v_lshl_add_u64 v[196:197], v[196:197], 0, s[12:13]
	s_mov_b32 m0, s24
	ds_read_b128 v[184:187], v151 offset:50176
	ds_read_b128 v[188:191], v151 offset:51200
	ds_read_b128 v[192:195], v151 offset:52224
	ds_read_b128 v[200:203], v151 offset:53248
	ds_read_b128 v[204:207], v151 offset:54272
	ds_read_b128 v[208:211], v151 offset:55296
	ds_read_b128 v[212:215], v151 offset:56320
	ds_read_b128 v[216:219], v151 offset:57344
	global_load_lds_dwordx4 v[196:197], off
	s_add_i32 m0, s24, 0x2000
	s_add_u32 s24, s26, 0x40080
	v_lshl_add_u64 v[196:197], v[220:221], 0, s[12:13]
	s_addc_u32 s25, s27, 0
	s_add_i32 s26, s66, s38
	global_load_lds_dwordx4 v[196:197], off
	v_lshl_add_u64 v[196:197], s[24:25], 0, v[130:131]
	s_mov_b32 m0, s26
	s_nop 0
	global_load_lds_dwordx4 v[196:197], off
	v_lshl_add_u64 v[196:197], s[24:25], 0, v[132:133]
	s_add_i32 m0, s26, 0x2000
	s_nop 0
	global_load_lds_dwordx4 v[196:197], off
	v_lshl_add_u64 v[196:197], v[222:223], 0, s[12:13]
	s_mov_b32 m0, s44
	s_nop 0
	global_load_lds_dwordx4 v[196:197], off
	v_lshl_add_u64 v[196:197], v[224:225], 0, s[12:13]
	s_mov_b32 m0, s45
	s_nop 0
	global_load_lds_dwordx4 v[196:197], off
	s_waitcnt vmcnt(8)
	s_waitcnt lgkmcnt(0)
	s_barrier
	s_waitcnt lgkmcnt(0)
	v_mfma_f32_16x16x32_bf16 v[62:65], v[152:155], v[184:187], v[62:65]
	v_mfma_f32_16x16x32_bf16 v[58:61], v[160:163], v[184:187], v[58:61]
	v_mfma_f32_16x16x32_bf16 v[54:57], v[152:155], v[192:195], v[54:57]
	v_mfma_f32_16x16x32_bf16 v[50:53], v[160:163], v[192:195], v[50:53]
	v_mfma_f32_16x16x32_bf16 v[38:41], v[152:155], v[204:207], v[38:41]
	v_mfma_f32_16x16x32_bf16 v[34:37], v[160:163], v[204:207], v[34:37]
	v_mfma_f32_16x16x32_bf16 v[22:25], v[152:155], v[212:215], v[22:25]
	v_mfma_f32_16x16x32_bf16 v[18:21], v[160:163], v[212:215], v[18:21]
	v_mfma_f32_16x16x32_bf16 v[62:65], v[156:159], v[188:191], v[62:65]
	v_mfma_f32_16x16x32_bf16 v[58:61], v[164:167], v[188:191], v[58:61]
	v_mfma_f32_16x16x32_bf16 v[54:57], v[156:159], v[200:203], v[54:57]
	v_mfma_f32_16x16x32_bf16 v[50:53], v[164:167], v[200:203], v[50:53]
	v_mfma_f32_16x16x32_bf16 v[38:41], v[156:159], v[208:211], v[38:41]
	v_mfma_f32_16x16x32_bf16 v[34:37], v[164:167], v[208:211], v[34:37]
	v_mfma_f32_16x16x32_bf16 v[22:25], v[156:159], v[216:219], v[22:25]
	v_mfma_f32_16x16x32_bf16 v[18:21], v[164:167], v[216:219], v[18:21]
	v_mfma_f32_16x16x32_bf16 v[46:49], v[168:171], v[184:187], v[46:49]
	v_mfma_f32_16x16x32_bf16 v[42:45], v[176:179], v[184:187], v[42:45]
	v_mfma_f32_16x16x32_bf16 v[30:33], v[168:171], v[192:195], v[30:33]
	v_mfma_f32_16x16x32_bf16 v[26:29], v[176:179], v[192:195], v[26:29]
	v_mfma_f32_16x16x32_bf16 v[14:17], v[168:171], v[204:207], v[14:17]
	v_mfma_f32_16x16x32_bf16 v[10:13], v[176:179], v[204:207], v[10:13]
	v_mfma_f32_16x16x32_bf16 v[6:9], v[168:171], v[212:215], v[6:9]
	v_mfma_f32_16x16x32_bf16 v[2:5], v[176:179], v[212:215], v[2:5]
	v_mfma_f32_16x16x32_bf16 v[46:49], v[172:175], v[188:191], v[46:49]
	v_mfma_f32_16x16x32_bf16 v[42:45], v[180:183], v[188:191], v[42:45]
	v_mfma_f32_16x16x32_bf16 v[30:33], v[172:175], v[200:203], v[30:33]
	v_mfma_f32_16x16x32_bf16 v[26:29], v[180:183], v[200:203], v[26:29]
	v_mfma_f32_16x16x32_bf16 v[14:17], v[172:175], v[208:211], v[14:17]
	v_mfma_f32_16x16x32_bf16 v[10:13], v[180:183], v[208:211], v[10:13]
	v_mfma_f32_16x16x32_bf16 v[6:9], v[172:175], v[216:219], v[6:9]
	v_mfma_f32_16x16x32_bf16 v[2:5], v[180:183], v[216:219], v[2:5]
	s_barrier
	s_add_i32 s64, s64, 2
	s_add_u32 s55, s55, 0x100
	s_addc_u32 s57, s57, 0
	s_cmp_gt_u32 s64, 5
	s_mov_b64 s[24:25], s[4:5]
	s_cbranch_scc0 .LBB0_1174
	s_and_b64 vcc, exec, s[14:15]
	s_cbranch_vccz .LBB0_1177
	s_barrier

.LBB0_1285:
	s_cmp_lt_i32 s59, 10
	s_waitcnt vmcnt(0)
	s_barrier
	s_cbranch_scc1 .LBB0_1339
	s_waitcnt vmcnt(0)
	s_setprio 0
	s_barrier
	s_and_saveexec_b64 s[2:3], s[0:1]
	s_cbranch_execz .LBB0_1338
	s_waitcnt vmcnt(0) lgkmcnt(0)
	v_mov_b32_e32 v241, 0
	v_lshlrev_b32_e64 v254, 8, s31
	v_mov_b32_e32 v247, 1
	v_mov_b32_e32 v246, 0x3600
	global_atomic_add v248, v246, v247, s[60:61] sc0

.Lprio9:
.LBB0_1401:
	s_cmp_gt_i32 s58, 10
	s_cselect_b64 s[2:3], -1, 0
	s_cmp_lt_i32 s59, 11
	s_cselect_b64 s[4:5], -1, 0
	s_or_b64 s[2:3], s[2:3], s[4:5]
	s_and_b64 vcc, exec, s[2:3]
	s_cbranch_vccnz .LBB0_1612
	s_waitcnt vmcnt(0)
	v_mov_b32_e32 v2, 0
	ds_read_b64 v[8:9], v2 offset:416
	ds_read_b128 v[4:7], v2 offset:192
	v_lshlrev_b32_e32 v227, 2, v0
	v_lshlrev_b32_e32 v3, 4, v0
	s_movk_i32 s3, 0x70
	s_waitcnt lgkmcnt(1)
	v_readfirstlane_b32 s6, v8
	v_readfirstlane_b32 s7, v9
	s_add_u32 s53, s6, 0x8c8000
	s_addc_u32 s54, s7, 0
	s_add_u32 s55, s6, 0x3128000
	s_addc_u32 s57, s7, 0
	s_add_u32 s12, s6, 0x8b28000
	s_waitcnt lgkmcnt(0)
	v_readfirstlane_b32 s9, v5
	v_readfirstlane_b32 s11, v7
	s_addc_u32 s13, s7, 0
	s_lshr_b32 s2, s33, 8
	v_and_b32_e32 v5, 15, v0
	v_and_b32_e32 v7, 48, v0
	v_readfirstlane_b32 s8, v4
	v_and_b32_e32 v4, 32, v0
	s_lshl_b32 s5, s2, 13
	v_lshl_or_b32 v7, v5, 6, v7
	v_and_b32_e32 v9, 32, v227
	v_bitop3_b32 v11, v3, v4, 48 bitop3:0x6c
	v_or_b32_e32 v3, 0x2000, v3
	v_bitop3_b32 v12, v7, s5, v9 bitop3:0xde
	s_lshl_b32 s5, s68, 5
	v_bfe_u32 v8, v0, 2, 4
	v_lshrrev_b32_e32 v4, 7, v3
	s_and_b32 s5, s5, 0x60
	v_and_or_b32 v230, v4, s3, v8
	s_lshl_b32 s4, s68, 10
	s_lshl_b32 s3, s2, 6
	s_lshl_b32 s14, s5, 7
	s_cmp_eq_u32 s2, 1
	v_bitop3_b32 v13, s14, v7, v9 bitop3:0xf6
	s_cselect_b64 s[14:15], -1, 0
	s_cmpk_lt_u32 s33, 0x100
	v_readfirstlane_b32 s10, v6
	v_or_b32_e32 v6, s3, v5
	s_cselect_b64 s[16:17], -1, 0
	s_addk_i32 s3, 0x80
	s_lshl_b32 s5, s5, 1
	s_add_u32 s18, s8, 0x5800
	s_addc_u32 s19, s9, 0
	s_add_u32 s20, s8, 0xb000
	v_lshrrev_b32_e32 v231, 1, v0
	s_addc_u32 s21, s9, 0
	v_and_b32_e32 v4, 24, v231
	s_cmpk_eq_i32 s56, 0x100
	v_add_u32_e32 v4, 0, v4
	v_or_b32_e32 v5, s3, v5
	s_movk_i32 s26, 0x210
	s_cselect_b64 s[22:23], -1, 0
	s_ashr_i32 s65, s56, 31
	s_ashr_i32 s66, s30, 31
	v_mad_u64_u32 v[6:7], s[2:3], v6, s26, v[4:5]
	s_cmpk_lt_i32 s30, 0x78
	s_cselect_b64 s[24:25], -1, 0
	s_ashr_i32 s2, s30, 1
	s_addk_i32 s2, 0x200
	s_ashr_i32 s3, s2, 31
	s_lshr_b32 s3, s3, 29
	s_add_i32 s3, s2, s3
	s_ashr_i32 s27, s3, 3
	s_and_b32 s3, s3, -8
	s_sub_i32 s2, s2, s3
	s_mul_i32 s3, s2, 0x47
	s_add_i32 s3, s3, 4
	s_and_b32 s67, s30, 1
	s_cmp_lt_i32 s2, 4
	s_mulk_i32 s2, 0x48
	s_cselect_b32 s2, s2, s3
	s_add_i32 s2, s2, s27
	s_mul_hi_i32 s3, s2, 0x2e8ba2e9
	s_lshr_b32 s27, s3, 31
	s_ashr_i32 s3, s3, 5
	s_add_i32 s3, s3, s27
	s_lshl_b32 s70, s3, 3
	s_sub_i32 s27, 26, s70
	s_min_u32 s27, s27, 8
	s_mulk_i32 s3, 0xb0
	s_sub_i32 s28, s2, s3
	v_cvt_f32_ubyte0_e32 v9, s27
	v_cvt_f32_i32_e32 v7, s28
	v_rcp_iflag_f32_e32 v14, v9
	v_mad_u64_u32 v[4:5], s[2:3], v5, s26, v[4:5]
	s_ashr_i32 s2, s28, 30
	v_mul_f32_e32 v5, v7, v14
	v_trunc_f32_e32 v5, v5
	v_fma_f32 v7, -v5, v9, v7
	v_cvt_i32_f32_e32 v5, v5
	s_or_b32 s26, s2, 1
	v_cmp_ge_f32_e64 s[2:3], |v7|, v9
	s_and_b64 s[2:3], s[2:3], exec
	s_cselect_b32 s2, s26, 0
	v_readfirstlane_b32 s3, v5
	s_add_i32 s2, s3, s2
	s_sext_i32_i16 s69, s2
	s_mul_i32 s2, s2, s27
	s_sub_i32 s2, s28, s2
	s_sext_i32_i16 s2, s2
	s_add_i32 s70, s70, s2
	v_lshlrev_b32_e32 v3, 4, v3
	s_mov_b32 s2, 0x38000
	v_lshrrev_b32_e32 v1, 3, v0
	v_and_b32_e32 v10, 64, v0
	v_and_or_b32 v3, v3, s2, v11
	v_lshlrev_b32_e32 v5, 11, v8
	v_and_or_b32 v228, v1, 48, v8
	v_or3_b32 v8, v3, v5, v10
	v_mov_b32_e32 v9, v2
	v_lshlrev_b32_e32 v3, 8, v0
	s_mov_b32 s26, 0x18000
	v_lshl_add_u64 v[8:9], s[6:7], 0, v[8:9]
	s_mov_b64 s[2:3], 0x3168080
	v_and_or_b32 v3, v3, s26, v11
	v_lshl_add_u64 v[204:205], v[8:9], 0, s[2:3]
	v_or3_b32 v8, v3, v5, v10
	v_mov_b32_e32 v9, v2
	v_or_b32_e32 v229, v10, v11
	s_add_u32 s71, s6, 0x8c8100
	v_lshl_add_u64 v[8:9], s[6:7], 0, v[8:9]
	s_mov_b32 s52, 0
	v_lshl_or_b32 v200, v228, 11, v229
	s_movk_i32 s64, 0x2000
	v_lshl_or_b32 v202, v230, 11, v229
	v_lshlrev_b32_e32 v226, 3, v0
	v_add_u32_e32 v232, 64, v230
	v_mov_b32_e32 v201, v2
	v_mov_b32_e32 v203, v2
	s_addc_u32 s72, s7, 0
	v_lshl_add_u64 v[206:207], v[8:9], 0, s[2:3]
	s_movk_i32 s73, 0x2fa
	s_mov_b64 s[26:27], 0x80
	s_movk_i32 s74, 0xff
	s_mov_b64 s[28:29], 0x2c00
	s_movk_i32 s75, 0x1f8
	s_add_i32 s76, 0, 0x610
	s_movk_i32 s77, 0x1600
	v_mov_b64_e32 v[208:209], 0x23c
	v_mov_b64_e32 v[210:211], 0x23b
	s_add_i32 s78, s4, 0
	v_add_u32_e32 v233, 0, v13
	v_add_u32_e32 v234, 0, v12
	v_add_u32_e32 v235, s5, v6
	v_add_u32_e32 v236, s5, v4
	s_branch .LBB0_1405

.LBB0_1430:
	v_lshl_add_u64 v[4:5], v[218:219], 0, s[46:47]
	s_add_i32 m0, s78, 0xc400
	ds_read_b128 v[190:193], v234 offset:1024
	ds_read_b128 v[194:197], v234 offset:2048
	ds_read_b128 v[182:185], v234 offset:3072
	ds_read_b128 v[186:189], v234 offset:4096
	ds_read_b128 v[174:177], v234 offset:5120
	ds_read_b128 v[178:181], v234 offset:6144
	ds_read_b128 v[166:169], v234 offset:7168
	ds_read_b128 v[170:173], v234 offset:8192
	global_load_lds_dwordx4 v[4:5], off
	v_lshl_add_u64 v[4:5], v[216:217], 0, s[46:47]
	s_add_i32 m0, s78, 0xe400
	s_nop 0
	global_load_lds_dwordx4 v[4:5], off
	s_waitcnt vmcnt(8)
	s_waitcnt lgkmcnt(0)
	s_barrier
	s_waitcnt lgkmcnt(0)
	v_mfma_f32_16x16x32_bf16 v[70:73], v[150:153], v[190:193], v[70:73]
	v_mfma_f32_16x16x32_bf16 v[82:85], v[158:161], v[190:193], v[82:85]
	v_mfma_f32_16x16x32_bf16 v[74:77], v[150:153], v[182:185], v[74:77]
	v_mfma_f32_16x16x32_bf16 v[78:81], v[158:161], v[182:185], v[78:81]
	v_mfma_f32_16x16x32_bf16 v[62:65], v[150:153], v[174:177], v[62:65]
	v_mfma_f32_16x16x32_bf16 v[66:69], v[158:161], v[174:177], v[66:69]
	v_mfma_f32_16x16x32_bf16 v[54:57], v[150:153], v[166:169], v[54:57]
	v_mfma_f32_16x16x32_bf16 v[58:61], v[158:161], v[166:169], v[58:61]
	v_mfma_f32_16x16x32_bf16 v[70:73], v[154:157], v[194:197], v[70:73]
	v_mfma_f32_16x16x32_bf16 v[82:85], v[162:165], v[194:197], v[82:85]
	v_mfma_f32_16x16x32_bf16 v[74:77], v[154:157], v[186:189], v[74:77]
	v_mfma_f32_16x16x32_bf16 v[78:81], v[162:165], v[186:189], v[78:81]
	v_mfma_f32_16x16x32_bf16 v[62:65], v[154:157], v[178:181], v[62:65]
	v_mfma_f32_16x16x32_bf16 v[66:69], v[162:165], v[178:181], v[66:69]
	v_mfma_f32_16x16x32_bf16 v[54:57], v[154:157], v[170:173], v[54:57]
	v_mfma_f32_16x16x32_bf16 v[58:61], v[162:165], v[170:173], v[58:61]
	s_and_b64 vcc, exec, s[4:5]
	s_cbranch_vccnz .LBB0_1432
	v_mfma_f32_16x16x32_bf16 v[50:53], v[6:9], v[190:193], v[50:53]
	v_mfma_f32_16x16x32_bf16 v[46:49], v[14:17], v[190:193], v[46:49]
	v_mfma_f32_16x16x32_bf16 v[42:45], v[6:9], v[182:185], v[42:45]
	v_mfma_f32_16x16x32_bf16 v[38:41], v[14:17], v[182:185], v[38:41]
	v_mfma_f32_16x16x32_bf16 v[34:37], v[6:9], v[174:177], v[34:37]
	v_mfma_f32_16x16x32_bf16 v[30:33], v[14:17], v[174:177], v[30:33]
	v_mfma_f32_16x16x32_bf16 v[26:29], v[6:9], v[166:169], v[26:29]
	v_mfma_f32_16x16x32_bf16 v[22:25], v[14:17], v[166:169], v[22:25]
	v_mfma_f32_16x16x32_bf16 v[50:53], v[10:13], v[194:197], v[50:53]
	v_mfma_f32_16x16x32_bf16 v[46:49], v[18:21], v[194:197], v[46:49]
	v_mfma_f32_16x16x32_bf16 v[42:45], v[10:13], v[186:189], v[42:45]
	v_mfma_f32_16x16x32_bf16 v[38:41], v[18:21], v[186:189], v[38:41]
	v_mfma_f32_16x16x32_bf16 v[34:37], v[10:13], v[178:181], v[34:37]
	v_mfma_f32_16x16x32_bf16 v[30:33], v[18:21], v[178:181], v[30:33]
	v_mfma_f32_16x16x32_bf16 v[26:29], v[10:13], v[170:173], v[26:29]
	v_mfma_f32_16x16x32_bf16 v[22:25], v[18:21], v[170:173], v[22:25]
.LBB0_1432:
	s_add_u32 s48, s95, s46
	s_addc_u32 s49, s96, s47
	s_add_u32 s48, s48, 0x3128100
	s_addc_u32 s49, s49, 0
	s_add_u32 vcc_lo, s93, s46
	s_addc_u32 vcc_hi, s94, s47
	s_cmpk_eq_i32 s46, 0x700
	s_cselect_b32 s51, s45, s49
	s_cselect_b32 s50, s44, s48
	s_cselect_b32 s49, s43, vcc_hi
	s_cselect_b32 s48, s42, vcc_lo
	s_barrier
	s_mov_b32 m0, s35
	v_lshl_add_u64 v[4:5], s[48:49], 0, v[212:213]
	s_add_u32 vcc_lo, s48, 0x40000
	ds_read_b128 v[190:193], v234 offset:17408
	ds_read_b128 v[194:197], v234 offset:18432
	ds_read_b128 v[182:185], v234 offset:19456
	ds_read_b128 v[186:189], v234 offset:20480
	ds_read_b128 v[174:177], v234 offset:21504
	ds_read_b128 v[178:181], v234 offset:22528
	ds_read_b128 v[166:169], v234 offset:23552
	ds_read_b128 v[170:173], v234 offset:24576
	global_load_lds_dwordx4 v[4:5], off
	v_lshl_add_u64 v[220:221], s[48:49], 0, v[214:215]
	s_mov_b32 m0, s39
	s_addc_u32 vcc_hi, s49, 0
	global_load_lds_dwordx4 v[220:221], off
	v_lshl_add_u64 v[222:223], vcc, 0, v[200:201]
	s_mov_b32 m0, s81
	v_lshl_add_u64 v[224:225], s[50:51], 0, v[202:203]
	global_load_lds_dwordx4 v[222:223], off
	v_lshl_add_u64 v[222:223], vcc, 0, v[202:203]
	s_mov_b32 m0, s82
	s_nop 0
	global_load_lds_dwordx4 v[222:223], off
	v_lshl_add_u64 v[222:223], s[50:51], 0, v[200:201]
	s_mov_b32 m0, s83
	s_nop 0
	global_load_lds_dwordx4 v[222:223], off
	s_mov_b32 m0, s84
	s_nop 0
	global_load_lds_dwordx4 v[224:225], off
	s_waitcnt vmcnt(8)
	s_waitcnt lgkmcnt(0)
	s_barrier
	s_waitcnt lgkmcnt(0)
	v_mfma_f32_16x16x32_bf16 v[142:145], v[150:153], v[190:193], v[142:145]
	v_mfma_f32_16x16x32_bf16 v[146:149], v[158:161], v[190:193], v[146:149]
	v_mfma_f32_16x16x32_bf16 v[134:137], v[150:153], v[182:185], v[134:137]
	v_mfma_f32_16x16x32_bf16 v[138:141], v[158:161], v[182:185], v[138:141]
	v_mfma_f32_16x16x32_bf16 v[126:129], v[150:153], v[174:177], v[126:129]
	v_mfma_f32_16x16x32_bf16 v[130:133], v[158:161], v[174:177], v[130:133]
	v_mfma_f32_16x16x32_bf16 v[118:121], v[150:153], v[166:169], v[118:121]
	v_mfma_f32_16x16x32_bf16 v[122:125], v[158:161], v[166:169], v[122:125]
	v_mfma_f32_16x16x32_bf16 v[142:145], v[154:157], v[194:197], v[142:145]
	v_mfma_f32_16x16x32_bf16 v[146:149], v[162:165], v[194:197], v[146:149]
	v_mfma_f32_16x16x32_bf16 v[134:137], v[154:157], v[186:189], v[134:137]
	v_mfma_f32_16x16x32_bf16 v[138:141], v[162:165], v[186:189], v[138:141]
	v_mfma_f32_16x16x32_bf16 v[126:129], v[154:157], v[178:181], v[126:129]
	v_mfma_f32_16x16x32_bf16 v[130:133], v[162:165], v[178:181], v[130:133]
	v_mfma_f32_16x16x32_bf16 v[118:121], v[154:157], v[170:173], v[118:121]
	v_mfma_f32_16x16x32_bf16 v[122:125], v[162:165], v[170:173], v[122:125]
	s_and_b64 vcc, exec, s[4:5]
	s_cbranch_vccnz .LBB0_1434
	v_mfma_f32_16x16x32_bf16 v[114:117], v[6:9], v[190:193], v[114:117]
	v_mfma_f32_16x16x32_bf16 v[110:113], v[14:17], v[190:193], v[110:113]
	v_mfma_f32_16x16x32_bf16 v[106:109], v[6:9], v[182:185], v[106:109]
	v_mfma_f32_16x16x32_bf16 v[102:105], v[14:17], v[182:185], v[102:105]
	v_mfma_f32_16x16x32_bf16 v[98:101], v[6:9], v[174:177], v[98:101]
	v_mfma_f32_16x16x32_bf16 v[94:97], v[14:17], v[174:177], v[94:97]
	v_mfma_f32_16x16x32_bf16 v[90:93], v[6:9], v[166:169], v[90:93]
	v_mfma_f32_16x16x32_bf16 v[86:89], v[14:17], v[166:169], v[86:89]
	v_mfma_f32_16x16x32_bf16 v[114:117], v[10:13], v[194:197], v[114:117]
	v_mfma_f32_16x16x32_bf16 v[110:113], v[18:21], v[194:197], v[110:113]
	v_mfma_f32_16x16x32_bf16 v[106:109], v[10:13], v[186:189], v[106:109]
	v_mfma_f32_16x16x32_bf16 v[102:105], v[18:21], v[186:189], v[102:105]
	v_mfma_f32_16x16x32_bf16 v[98:101], v[10:13], v[178:181], v[98:101]
	v_mfma_f32_16x16x32_bf16 v[94:97], v[18:21], v[178:181], v[94:97]
	v_mfma_f32_16x16x32_bf16 v[90:93], v[10:13], v[170:173], v[90:93]
	v_mfma_f32_16x16x32_bf16 v[86:89], v[18:21], v[170:173], v[86:89]

.LBB0_1436:
	s_add_u32 s50, s50, 0x40000
	s_addc_u32 s51, s51, 0
	s_mov_b32 m0, s85
	v_lshl_add_u64 v[238:239], s[50:51], 0, v[200:201]
	ds_read_b128 v[190:193], v234 offset:33792
	ds_read_b128 v[194:197], v234 offset:34816
	ds_read_b128 v[182:185], v234 offset:35840
	ds_read_b128 v[186:189], v234 offset:36864
	ds_read_b128 v[174:177], v234 offset:37888
	ds_read_b128 v[178:181], v234 offset:38912
	ds_read_b128 v[166:169], v234 offset:39936
	ds_read_b128 v[170:173], v234 offset:40960
	global_load_lds_dwordx4 v[238:239], off
	v_lshl_add_u64 v[238:239], s[50:51], 0, v[202:203]
	s_mov_b32 m0, s86
	s_nop 0
	global_load_lds_dwordx4 v[238:239], off
	s_waitcnt vmcnt(8)
	s_waitcnt lgkmcnt(0)
	s_barrier
	s_waitcnt lgkmcnt(0)
	v_mfma_f32_16x16x32_bf16 v[70:73], v[150:153], v[190:193], v[70:73]
	v_mfma_f32_16x16x32_bf16 v[82:85], v[158:161], v[190:193], v[82:85]
	v_mfma_f32_16x16x32_bf16 v[74:77], v[150:153], v[182:185], v[74:77]
	v_mfma_f32_16x16x32_bf16 v[78:81], v[158:161], v[182:185], v[78:81]
	v_mfma_f32_16x16x32_bf16 v[62:65], v[150:153], v[174:177], v[62:65]
	v_mfma_f32_16x16x32_bf16 v[66:69], v[158:161], v[174:177], v[66:69]
	v_mfma_f32_16x16x32_bf16 v[54:57], v[150:153], v[166:169], v[54:57]
	v_mfma_f32_16x16x32_bf16 v[58:61], v[158:161], v[166:169], v[58:61]
	v_mfma_f32_16x16x32_bf16 v[70:73], v[154:157], v[194:197], v[70:73]
	v_mfma_f32_16x16x32_bf16 v[82:85], v[162:165], v[194:197], v[82:85]
	v_mfma_f32_16x16x32_bf16 v[74:77], v[154:157], v[186:189], v[74:77]
	v_mfma_f32_16x16x32_bf16 v[78:81], v[162:165], v[186:189], v[78:81]
	v_mfma_f32_16x16x32_bf16 v[62:65], v[154:157], v[178:181], v[62:65]
	v_mfma_f32_16x16x32_bf16 v[66:69], v[162:165], v[178:181], v[66:69]
	v_mfma_f32_16x16x32_bf16 v[54:57], v[154:157], v[170:173], v[54:57]
	v_mfma_f32_16x16x32_bf16 v[58:61], v[162:165], v[170:173], v[58:61]
	s_and_b64 vcc, exec, s[4:5]
	s_cbranch_vccnz .LBB0_1438
	v_mfma_f32_16x16x32_bf16 v[50:53], v[6:9], v[190:193], v[50:53]
	v_mfma_f32_16x16x32_bf16 v[46:49], v[14:17], v[190:193], v[46:49]
	v_mfma_f32_16x16x32_bf16 v[42:45], v[6:9], v[182:185], v[42:45]
	v_mfma_f32_16x16x32_bf16 v[38:41], v[14:17], v[182:185], v[38:41]
	v_mfma_f32_16x16x32_bf16 v[34:37], v[6:9], v[174:177], v[34:37]
	v_mfma_f32_16x16x32_bf16 v[30:33], v[14:17], v[174:177], v[30:33]
	v_mfma_f32_16x16x32_bf16 v[26:29], v[6:9], v[166:169], v[26:29]
	v_mfma_f32_16x16x32_bf16 v[22:25], v[14:17], v[166:169], v[22:25]
	v_mfma_f32_16x16x32_bf16 v[50:53], v[10:13], v[194:197], v[50:53]
	v_mfma_f32_16x16x32_bf16 v[46:49], v[18:21], v[194:197], v[46:49]
	v_mfma_f32_16x16x32_bf16 v[42:45], v[10:13], v[186:189], v[42:45]
	v_mfma_f32_16x16x32_bf16 v[38:41], v[18:21], v[186:189], v[38:41]
	v_mfma_f32_16x16x32_bf16 v[34:37], v[10:13], v[178:181], v[34:37]
	v_mfma_f32_16x16x32_bf16 v[30:33], v[18:21], v[178:181], v[30:33]
	v_mfma_f32_16x16x32_bf16 v[26:29], v[10:13], v[170:173], v[26:29]
	v_mfma_f32_16x16x32_bf16 v[22:25], v[18:21], v[170:173], v[22:25]
.LBB0_1438:
	s_barrier
	s_mov_b32 m0, s87
	v_lshl_add_u64 v[4:5], v[4:5], 0, s[26:27]
	s_add_u32 s48, s48, 0x40080
	ds_read_b128 v[190:193], v234 offset:50176
	ds_read_b128 v[194:197], v234 offset:51200
	ds_read_b128 v[182:185], v234 offset:52224
	ds_read_b128 v[186:189], v234 offset:53248
	ds_read_b128 v[174:177], v234 offset:54272
	ds_read_b128 v[178:181], v234 offset:55296
	ds_read_b128 v[166:169], v234 offset:56320
	ds_read_b128 v[170:173], v234 offset:57344
	global_load_lds_dwordx4 v[4:5], off
	v_lshl_add_u64 v[4:5], v[220:221], 0, s[26:27]
	s_mov_b32 m0, s88
	s_addc_u32 s49, s49, 0
	global_load_lds_dwordx4 v[4:5], off
	v_lshl_add_u64 v[4:5], s[48:49], 0, v[200:201]
	s_mov_b32 m0, s91
	s_nop 0
	global_load_lds_dwordx4 v[4:5], off
	v_lshl_add_u64 v[4:5], s[48:49], 0, v[202:203]
	s_mov_b32 m0, s92
	s_nop 0
	global_load_lds_dwordx4 v[4:5], off
	v_lshl_add_u64 v[4:5], v[222:223], 0, s[26:27]
	s_mov_b32 m0, s89
	s_nop 0
	global_load_lds_dwordx4 v[4:5], off
	v_lshl_add_u64 v[4:5], v[224:225], 0, s[26:27]
	s_mov_b32 m0, s90
	s_nop 0
	global_load_lds_dwordx4 v[4:5], off
	s_waitcnt vmcnt(8)
	s_waitcnt lgkmcnt(0)
	s_barrier
	s_waitcnt lgkmcnt(0)
	v_mfma_f32_16x16x32_bf16 v[142:145], v[150:153], v[190:193], v[142:145]
	v_mfma_f32_16x16x32_bf16 v[146:149], v[158:161], v[190:193], v[146:149]
	v_mfma_f32_16x16x32_bf16 v[134:137], v[150:153], v[182:185], v[134:137]
	v_mfma_f32_16x16x32_bf16 v[138:141], v[158:161], v[182:185], v[138:141]
	v_mfma_f32_16x16x32_bf16 v[126:129], v[150:153], v[174:177], v[126:129]
	v_mfma_f32_16x16x32_bf16 v[130:133], v[158:161], v[174:177], v[130:133]
	v_mfma_f32_16x16x32_bf16 v[118:121], v[150:153], v[166:169], v[118:121]
	v_mfma_f32_16x16x32_bf16 v[122:125], v[158:161], v[166:169], v[122:125]
	v_mfma_f32_16x16x32_bf16 v[142:145], v[154:157], v[194:197], v[142:145]
	v_mfma_f32_16x16x32_bf16 v[146:149], v[162:165], v[194:197], v[146:149]
	v_mfma_f32_16x16x32_bf16 v[134:137], v[154:157], v[186:189], v[134:137]
	v_mfma_f32_16x16x32_bf16 v[138:141], v[162:165], v[186:189], v[138:141]
	v_mfma_f32_16x16x32_bf16 v[126:129], v[154:157], v[178:181], v[126:129]
	v_mfma_f32_16x16x32_bf16 v[130:133], v[162:165], v[178:181], v[130:133]
	v_mfma_f32_16x16x32_bf16 v[118:121], v[154:157], v[170:173], v[118:121]
	v_mfma_f32_16x16x32_bf16 v[122:125], v[162:165], v[170:173], v[122:125]
	s_and_b64 vcc, exec, s[4:5]
	s_cbranch_vccnz .LBB0_1427
	v_mfma_f32_16x16x32_bf16 v[114:117], v[6:9], v[190:193], v[114:117]
	v_mfma_f32_16x16x32_bf16 v[110:113], v[14:17], v[190:193], v[110:113]
	v_mfma_f32_16x16x32_bf16 v[106:109], v[6:9], v[182:185], v[106:109]
	v_mfma_f32_16x16x32_bf16 v[102:105], v[14:17], v[182:185], v[102:105]
	v_mfma_f32_16x16x32_bf16 v[98:101], v[6:9], v[174:177], v[98:101]
	v_mfma_f32_16x16x32_bf16 v[94:97], v[14:17], v[174:177], v[94:97]
	v_mfma_f32_16x16x32_bf16 v[90:93], v[6:9], v[166:169], v[90:93]
	v_mfma_f32_16x16x32_bf16 v[86:89], v[14:17], v[166:169], v[86:89]
	v_mfma_f32_16x16x32_bf16 v[114:117], v[10:13], v[194:197], v[114:117]
	v_mfma_f32_16x16x32_bf16 v[110:113], v[18:21], v[194:197], v[110:113]
	v_mfma_f32_16x16x32_bf16 v[106:109], v[10:13], v[186:189], v[106:109]
	v_mfma_f32_16x16x32_bf16 v[102:105], v[18:21], v[186:189], v[102:105]
	v_mfma_f32_16x16x32_bf16 v[98:101], v[10:13], v[178:181], v[98:101]
	v_mfma_f32_16x16x32_bf16 v[94:97], v[18:21], v[178:181], v[94:97]
	v_mfma_f32_16x16x32_bf16 v[90:93], v[10:13], v[170:173], v[90:93]
	v_mfma_f32_16x16x32_bf16 v[86:89], v[18:21], v[170:173], v[86:89]
	s_branch .LBB0_1427

.Lcv4_2:
.LBB0_1558:
	s_cmp_lt_i32 s59, 12
	s_waitcnt lgkmcnt(0)
	s_barrier
	s_cbranch_scc1 .LBB0_1612
	s_waitcnt vmcnt(0)
	s_setprio 0
	s_barrier
	s_and_saveexec_b64 s[2:3], s[0:1]
	s_cbranch_execz .LBB0_1611
	s_waitcnt vmcnt(0) lgkmcnt(0)
	v_mov_b32_e32 v241, 0
	v_lshlrev_b32_e64 v254, 8, s31
	v_mov_b32_e32 v247, 1
	v_mov_b32_e32 v246, 0x3600
	global_atomic_add v248, v246, v247, s[60:61] sc0

.Lprio10:
.LBB0_1612:
	s_cmp_gt_i32 s58, 12
	s_cselect_b64 s[2:3], -1, 0
	s_cmp_lt_i32 s59, 13
	s_cselect_b64 s[4:5], -1, 0
	s_or_b64 s[2:3], s[2:3], s[4:5]
	s_and_b64 vcc, exec, s[2:3]
	s_cbranch_vccnz .LBB0_2454
	v_mov_b32_e32 v131, 0
	s_waitcnt vmcnt(0)
	ds_read_b64 v[2:3], v131 offset:416
	s_cmpk_gt_i32 s30, 0xbf
	v_lshlrev_b32_e32 v1, 2, v0
	s_waitcnt lgkmcnt(0)
	v_readfirstlane_b32 s3, v2
	v_readfirstlane_b32 s4, v3
	s_cbranch_scc0 .LBB0_1616
	s_cmpk_lg_i32 s56, 0x100
	s_mov_b64 s[2:3], -1
	s_cbranch_scc1 .LBB0_1635

.LBB0_1628:
	ds_read_b128 v[152:155], v149
	ds_read_b128 v[156:159], v149 offset:1024
	ds_read_b128 v[160:163], v149 offset:2048
	ds_read_b128 v[164:167], v149 offset:3072
	ds_read_b128 v[168:171], v150
	ds_read_b128 v[172:175], v150 offset:1024
	ds_read_b128 v[176:179], v150 offset:2048
	ds_read_b128 v[180:183], v150 offset:3072
	s_add_u32 s20, s18, 0x100
	s_addc_u32 s21, s19, 0
	s_cmp_eq_u32 s55, 18
	s_cselect_b32 s25, s5, s21
	s_cselect_b32 s24, s4, s20
	s_cselect_b32 s23, s17, s54
	s_cselect_b32 s22, s16, s53
	v_lshl_add_u64 v[196:197], s[18:19], 0, v[140:141]
	s_add_i32 m0, s36, 0xc400
	ds_read_b128 v[184:187], v151 offset:1024
	ds_read_b128 v[188:191], v151 offset:2048
	ds_read_b128 v[192:195], v151 offset:3072
	ds_read_b128 v[200:203], v151 offset:4096
	ds_read_b128 v[204:207], v151 offset:5120
	ds_read_b128 v[208:211], v151 offset:6144
	ds_read_b128 v[212:215], v151 offset:7168
	ds_read_b128 v[216:219], v151 offset:8192
	global_load_lds_dwordx4 v[196:197], off
	v_lshl_add_u64 v[196:197], s[18:19], 0, v[138:139]
	s_add_i32 m0, s36, 0xe400
	s_nop 0
	global_load_lds_dwordx4 v[196:197], off
	s_waitcnt vmcnt(8)
	s_waitcnt lgkmcnt(0)
	s_barrier
	s_waitcnt lgkmcnt(0)
	v_mfma_f32_16x16x32_bf16 v[126:129], v[152:155], v[184:187], v[126:129]
	v_mfma_f32_16x16x32_bf16 v[122:125], v[160:163], v[184:187], v[122:125]
	v_mfma_f32_16x16x32_bf16 v[118:121], v[152:155], v[192:195], v[118:121]
	v_mfma_f32_16x16x32_bf16 v[114:117], v[160:163], v[192:195], v[114:117]
	v_mfma_f32_16x16x32_bf16 v[102:105], v[152:155], v[204:207], v[102:105]
	v_mfma_f32_16x16x32_bf16 v[98:101], v[160:163], v[204:207], v[98:101]
	v_mfma_f32_16x16x32_bf16 v[86:89], v[152:155], v[212:215], v[86:89]
	v_mfma_f32_16x16x32_bf16 v[82:85], v[160:163], v[212:215], v[82:85]
	v_mfma_f32_16x16x32_bf16 v[126:129], v[156:159], v[188:191], v[126:129]
	v_mfma_f32_16x16x32_bf16 v[122:125], v[164:167], v[188:191], v[122:125]
	v_mfma_f32_16x16x32_bf16 v[118:121], v[156:159], v[200:203], v[118:121]
	v_mfma_f32_16x16x32_bf16 v[114:117], v[164:167], v[200:203], v[114:117]
	v_mfma_f32_16x16x32_bf16 v[102:105], v[156:159], v[208:211], v[102:105]
	v_mfma_f32_16x16x32_bf16 v[98:101], v[164:167], v[208:211], v[98:101]
	v_mfma_f32_16x16x32_bf16 v[86:89], v[156:159], v[216:219], v[86:89]
	v_mfma_f32_16x16x32_bf16 v[82:85], v[164:167], v[216:219], v[82:85]
	v_mfma_f32_16x16x32_bf16 v[110:113], v[168:171], v[184:187], v[110:113]
	v_mfma_f32_16x16x32_bf16 v[106:109], v[176:179], v[184:187], v[106:109]
	v_mfma_f32_16x16x32_bf16 v[94:97], v[168:171], v[192:195], v[94:97]
	v_mfma_f32_16x16x32_bf16 v[90:93], v[176:179], v[192:195], v[90:93]
	v_mfma_f32_16x16x32_bf16 v[78:81], v[168:171], v[204:207], v[78:81]
	v_mfma_f32_16x16x32_bf16 v[74:77], v[176:179], v[204:207], v[74:77]
	v_mfma_f32_16x16x32_bf16 v[70:73], v[168:171], v[212:215], v[70:73]
	v_mfma_f32_16x16x32_bf16 v[66:69], v[176:179], v[212:215], v[66:69]
	v_mfma_f32_16x16x32_bf16 v[110:113], v[172:175], v[188:191], v[110:113]
	v_mfma_f32_16x16x32_bf16 v[106:109], v[180:183], v[188:191], v[106:109]
	v_mfma_f32_16x16x32_bf16 v[94:97], v[172:175], v[200:203], v[94:97]
	v_mfma_f32_16x16x32_bf16 v[90:93], v[180:183], v[200:203], v[90:93]
	v_mfma_f32_16x16x32_bf16 v[78:81], v[172:175], v[208:211], v[78:81]
	v_mfma_f32_16x16x32_bf16 v[74:77], v[180:183], v[208:211], v[74:77]
	v_mfma_f32_16x16x32_bf16 v[70:73], v[172:175], v[216:219], v[70:73]
	v_mfma_f32_16x16x32_bf16 v[66:69], v[180:183], v[216:219], v[66:69]
	s_barrier
	s_add_i32 s18, s45, s34
	v_lshl_add_u64 v[196:197], s[22:23], 0, v[130:131]
	s_mov_b32 m0, s18
	ds_read_b128 v[184:187], v151 offset:17408
	ds_read_b128 v[188:191], v151 offset:18432
	ds_read_b128 v[192:195], v151 offset:19456
	ds_read_b128 v[200:203], v151 offset:20480
	ds_read_b128 v[204:207], v151 offset:21504
	ds_read_b128 v[208:211], v151 offset:22528
	ds_read_b128 v[212:215], v151 offset:23552
	ds_read_b128 v[216:219], v151 offset:24576
	global_load_lds_dwordx4 v[196:197], off
	s_add_i32 m0, s18, 0x2000
	s_add_u32 s18, s22, 0xb0000
	v_lshl_add_u64 v[220:221], s[22:23], 0, v[132:133]
	s_addc_u32 s19, s23, 0
	s_add_i32 s57, s46, s34
	global_load_lds_dwordx4 v[220:221], off
	v_lshl_add_u64 v[222:223], s[18:19], 0, v[130:131]
	s_mov_b32 m0, s57
	v_lshl_add_u64 v[224:225], s[24:25], 0, v[134:135]
	global_load_lds_dwordx4 v[222:223], off
	v_lshl_add_u64 v[222:223], s[18:19], 0, v[132:133]
	s_add_i32 m0, s57, 0x2000
	s_nop 0
	global_load_lds_dwordx4 v[222:223], off
	v_lshl_add_u64 v[222:223], s[24:25], 0, v[136:137]
	s_mov_b32 m0, s37
	s_nop 0
	global_load_lds_dwordx4 v[222:223], off
	s_mov_b32 m0, s38
	s_nop 0
	global_load_lds_dwordx4 v[224:225], off
	s_waitcnt vmcnt(8)
	s_waitcnt lgkmcnt(0)
	s_barrier
	s_waitcnt lgkmcnt(0)
	v_mfma_f32_16x16x32_bf16 v[62:65], v[152:155], v[184:187], v[62:65]
	v_mfma_f32_16x16x32_bf16 v[58:61], v[160:163], v[184:187], v[58:61]
	v_mfma_f32_16x16x32_bf16 v[54:57], v[152:155], v[192:195], v[54:57]
	v_mfma_f32_16x16x32_bf16 v[50:53], v[160:163], v[192:195], v[50:53]
	v_mfma_f32_16x16x32_bf16 v[38:41], v[152:155], v[204:207], v[38:41]
	v_mfma_f32_16x16x32_bf16 v[34:37], v[160:163], v[204:207], v[34:37]
	v_mfma_f32_16x16x32_bf16 v[22:25], v[152:155], v[212:215], v[22:25]
	v_mfma_f32_16x16x32_bf16 v[18:21], v[160:163], v[212:215], v[18:21]
	v_mfma_f32_16x16x32_bf16 v[62:65], v[156:159], v[188:191], v[62:65]
	v_mfma_f32_16x16x32_bf16 v[58:61], v[164:167], v[188:191], v[58:61]
	v_mfma_f32_16x16x32_bf16 v[54:57], v[156:159], v[200:203], v[54:57]
	v_mfma_f32_16x16x32_bf16 v[50:53], v[164:167], v[200:203], v[50:53]
	v_mfma_f32_16x16x32_bf16 v[38:41], v[156:159], v[208:211], v[38:41]
	v_mfma_f32_16x16x32_bf16 v[34:37], v[164:167], v[208:211], v[34:37]
	v_mfma_f32_16x16x32_bf16 v[22:25], v[156:159], v[216:219], v[22:25]
	v_mfma_f32_16x16x32_bf16 v[18:21], v[164:167], v[216:219], v[18:21]
	v_mfma_f32_16x16x32_bf16 v[46:49], v[168:171], v[184:187], v[46:49]
	v_mfma_f32_16x16x32_bf16 v[42:45], v[176:179], v[184:187], v[42:45]
	v_mfma_f32_16x16x32_bf16 v[30:33], v[168:171], v[192:195], v[30:33]
	v_mfma_f32_16x16x32_bf16 v[26:29], v[176:179], v[192:195], v[26:29]
	v_mfma_f32_16x16x32_bf16 v[14:17], v[168:171], v[204:207], v[14:17]
	v_mfma_f32_16x16x32_bf16 v[10:13], v[176:179], v[204:207], v[10:13]
	v_mfma_f32_16x16x32_bf16 v[6:9], v[168:171], v[212:215], v[6:9]
	v_mfma_f32_16x16x32_bf16 v[2:5], v[176:179], v[212:215], v[2:5]
	v_mfma_f32_16x16x32_bf16 v[46:49], v[172:175], v[188:191], v[46:49]
	v_mfma_f32_16x16x32_bf16 v[42:45], v[180:183], v[188:191], v[42:45]
	v_mfma_f32_16x16x32_bf16 v[30:33], v[172:175], v[200:203], v[30:33]
	v_mfma_f32_16x16x32_bf16 v[26:29], v[180:183], v[200:203], v[26:29]
	v_mfma_f32_16x16x32_bf16 v[14:17], v[172:175], v[208:211], v[14:17]
	v_mfma_f32_16x16x32_bf16 v[10:13], v[180:183], v[208:211], v[10:13]
	v_mfma_f32_16x16x32_bf16 v[6:9], v[172:175], v[216:219], v[6:9]
	v_mfma_f32_16x16x32_bf16 v[2:5], v[180:183], v[216:219], v[2:5]
	s_barrier
	s_add_i32 s57, 0, 0x18400
	s_add_i32 s64, 0, 0x1c400
	v_add_u32_e32 v164, s57, v147
	v_add_u32_e32 v180, s64, v147
	ds_read_b128 v[152:155], v164
	ds_read_b128 v[156:159], v164 offset:1024
	ds_read_b128 v[160:163], v164 offset:2048
	ds_read_b128 v[164:167], v164 offset:3072
	ds_read_b128 v[168:171], v180
	ds_read_b128 v[172:175], v180 offset:1024
	ds_read_b128 v[176:179], v180 offset:2048
	ds_read_b128 v[180:183], v180 offset:3072
	s_add_u32 s18, s24, 0xb0000
	s_addc_u32 s19, s25, 0
	s_mov_b32 m0, s39
	v_lshl_add_u64 v[226:227], s[18:19], 0, v[136:137]
	ds_read_b128 v[184:187], v151 offset:33792
	ds_read_b128 v[188:191], v151 offset:34816
	ds_read_b128 v[192:195], v151 offset:35840
	ds_read_b128 v[200:203], v151 offset:36864
	ds_read_b128 v[204:207], v151 offset:37888
	ds_read_b128 v[208:211], v151 offset:38912
	ds_read_b128 v[212:215], v151 offset:39936
	ds_read_b128 v[216:219], v151 offset:40960
	global_load_lds_dwordx4 v[226:227], off
	v_lshl_add_u64 v[226:227], s[18:19], 0, v[134:135]
	s_mov_b32 m0, s40
	s_nop 0
	global_load_lds_dwordx4 v[226:227], off
	s_waitcnt vmcnt(8)
	s_waitcnt lgkmcnt(0)
	s_barrier
	s_waitcnt lgkmcnt(0)
	v_mfma_f32_16x16x32_bf16 v[126:129], v[152:155], v[184:187], v[126:129]
	v_mfma_f32_16x16x32_bf16 v[122:125], v[160:163], v[184:187], v[122:125]
	v_mfma_f32_16x16x32_bf16 v[118:121], v[152:155], v[192:195], v[118:121]
	v_mfma_f32_16x16x32_bf16 v[114:117], v[160:163], v[192:195], v[114:117]
	v_mfma_f32_16x16x32_bf16 v[102:105], v[152:155], v[204:207], v[102:105]
	v_mfma_f32_16x16x32_bf16 v[98:101], v[160:163], v[204:207], v[98:101]
	v_mfma_f32_16x16x32_bf16 v[86:89], v[152:155], v[212:215], v[86:89]
	v_mfma_f32_16x16x32_bf16 v[82:85], v[160:163], v[212:215], v[82:85]
	v_mfma_f32_16x16x32_bf16 v[126:129], v[156:159], v[188:191], v[126:129]
	v_mfma_f32_16x16x32_bf16 v[122:125], v[164:167], v[188:191], v[122:125]
	v_mfma_f32_16x16x32_bf16 v[118:121], v[156:159], v[200:203], v[118:121]
	v_mfma_f32_16x16x32_bf16 v[114:117], v[164:167], v[200:203], v[114:117]
	v_mfma_f32_16x16x32_bf16 v[102:105], v[156:159], v[208:211], v[102:105]
	v_mfma_f32_16x16x32_bf16 v[98:101], v[164:167], v[208:211], v[98:101]
	v_mfma_f32_16x16x32_bf16 v[86:89], v[156:159], v[216:219], v[86:89]
	v_mfma_f32_16x16x32_bf16 v[82:85], v[164:167], v[216:219], v[82:85]
	v_mfma_f32_16x16x32_bf16 v[110:113], v[168:171], v[184:187], v[110:113]
	v_mfma_f32_16x16x32_bf16 v[106:109], v[176:179], v[184:187], v[106:109]
	v_mfma_f32_16x16x32_bf16 v[94:97], v[168:171], v[192:195], v[94:97]
	v_mfma_f32_16x16x32_bf16 v[90:93], v[176:179], v[192:195], v[90:93]
	v_mfma_f32_16x16x32_bf16 v[78:81], v[168:171], v[204:207], v[78:81]
	v_mfma_f32_16x16x32_bf16 v[74:77], v[176:179], v[204:207], v[74:77]
	v_mfma_f32_16x16x32_bf16 v[70:73], v[168:171], v[212:215], v[70:73]
	v_mfma_f32_16x16x32_bf16 v[66:69], v[176:179], v[212:215], v[66:69]
	v_mfma_f32_16x16x32_bf16 v[110:113], v[172:175], v[188:191], v[110:113]
	v_mfma_f32_16x16x32_bf16 v[106:109], v[180:183], v[188:191], v[106:109]
	v_mfma_f32_16x16x32_bf16 v[94:97], v[172:175], v[200:203], v[94:97]
	v_mfma_f32_16x16x32_bf16 v[90:93], v[180:183], v[200:203], v[90:93]
	v_mfma_f32_16x16x32_bf16 v[78:81], v[172:175], v[208:211], v[78:81]
	v_mfma_f32_16x16x32_bf16 v[74:77], v[180:183], v[208:211], v[74:77]
	v_mfma_f32_16x16x32_bf16 v[70:73], v[172:175], v[216:219], v[70:73]
	v_mfma_f32_16x16x32_bf16 v[66:69], v[180:183], v[216:219], v[66:69]
	s_barrier
	s_add_i32 s18, s57, s34
	v_lshl_add_u64 v[196:197], v[196:197], 0, s[12:13]
	s_mov_b32 m0, s18
	ds_read_b128 v[184:187], v151 offset:50176
	ds_read_b128 v[188:191], v151 offset:51200
	ds_read_b128 v[192:195], v151 offset:52224
	ds_read_b128 v[200:203], v151 offset:53248
	ds_read_b128 v[204:207], v151 offset:54272
	ds_read_b128 v[208:211], v151 offset:55296
	ds_read_b128 v[212:215], v151 offset:56320
	ds_read_b128 v[216:219], v151 offset:57344
	global_load_lds_dwordx4 v[196:197], off
	s_add_i32 m0, s18, 0x2000
	s_add_u32 s18, s22, 0xb0080
	v_lshl_add_u64 v[196:197], v[220:221], 0, s[12:13]
	s_addc_u32 s19, s23, 0
	s_add_i32 s22, s64, s34
	global_load_lds_dwordx4 v[196:197], off
	v_lshl_add_u64 v[196:197], s[18:19], 0, v[130:131]
	s_mov_b32 m0, s22
	s_nop 0
	global_load_lds_dwordx4 v[196:197], off
	v_lshl_add_u64 v[196:197], s[18:19], 0, v[132:133]
	s_add_i32 m0, s22, 0x2000
	s_nop 0
	global_load_lds_dwordx4 v[196:197], off
	v_lshl_add_u64 v[196:197], v[222:223], 0, s[12:13]
	s_mov_b32 m0, s41
	s_nop 0
	global_load_lds_dwordx4 v[196:197], off
	v_lshl_add_u64 v[196:197], v[224:225], 0, s[12:13]
	s_mov_b32 m0, s42
	s_nop 0
	global_load_lds_dwordx4 v[196:197], off
	s_waitcnt vmcnt(8)
	s_waitcnt lgkmcnt(0)
	s_barrier
	s_waitcnt lgkmcnt(0)
	v_mfma_f32_16x16x32_bf16 v[62:65], v[152:155], v[184:187], v[62:65]
	v_mfma_f32_16x16x32_bf16 v[58:61], v[160:163], v[184:187], v[58:61]
	v_mfma_f32_16x16x32_bf16 v[54:57], v[152:155], v[192:195], v[54:57]
	v_mfma_f32_16x16x32_bf16 v[50:53], v[160:163], v[192:195], v[50:53]
	v_mfma_f32_16x16x32_bf16 v[38:41], v[152:155], v[204:207], v[38:41]
	v_mfma_f32_16x16x32_bf16 v[34:37], v[160:163], v[204:207], v[34:37]
	v_mfma_f32_16x16x32_bf16 v[22:25], v[152:155], v[212:215], v[22:25]
	v_mfma_f32_16x16x32_bf16 v[18:21], v[160:163], v[212:215], v[18:21]
	v_mfma_f32_16x16x32_bf16 v[62:65], v[156:159], v[188:191], v[62:65]
	v_mfma_f32_16x16x32_bf16 v[58:61], v[164:167], v[188:191], v[58:61]
	v_mfma_f32_16x16x32_bf16 v[54:57], v[156:159], v[200:203], v[54:57]
	v_mfma_f32_16x16x32_bf16 v[50:53], v[164:167], v[200:203], v[50:53]
	v_mfma_f32_16x16x32_bf16 v[38:41], v[156:159], v[208:211], v[38:41]
	v_mfma_f32_16x16x32_bf16 v[34:37], v[164:167], v[208:211], v[34:37]
	v_mfma_f32_16x16x32_bf16 v[22:25], v[156:159], v[216:219], v[22:25]
	v_mfma_f32_16x16x32_bf16 v[18:21], v[164:167], v[216:219], v[18:21]
	v_mfma_f32_16x16x32_bf16 v[46:49], v[168:171], v[184:187], v[46:49]
	v_mfma_f32_16x16x32_bf16 v[42:45], v[176:179], v[184:187], v[42:45]
	v_mfma_f32_16x16x32_bf16 v[30:33], v[168:171], v[192:195], v[30:33]
	v_mfma_f32_16x16x32_bf16 v[26:29], v[176:179], v[192:195], v[26:29]
	v_mfma_f32_16x16x32_bf16 v[14:17], v[168:171], v[204:207], v[14:17]
	v_mfma_f32_16x16x32_bf16 v[10:13], v[176:179], v[204:207], v[10:13]
	v_mfma_f32_16x16x32_bf16 v[6:9], v[168:171], v[212:215], v[6:9]
	v_mfma_f32_16x16x32_bf16 v[2:5], v[176:179], v[212:215], v[2:5]
	v_mfma_f32_16x16x32_bf16 v[46:49], v[172:175], v[188:191], v[46:49]
	v_mfma_f32_16x16x32_bf16 v[42:45], v[180:183], v[188:191], v[42:45]
	v_mfma_f32_16x16x32_bf16 v[30:33], v[172:175], v[200:203], v[30:33]
	v_mfma_f32_16x16x32_bf16 v[26:29], v[180:183], v[200:203], v[26:29]
	v_mfma_f32_16x16x32_bf16 v[14:17], v[172:175], v[208:211], v[14:17]
	v_mfma_f32_16x16x32_bf16 v[10:13], v[180:183], v[208:211], v[10:13]
	v_mfma_f32_16x16x32_bf16 v[6:9], v[172:175], v[216:219], v[6:9]
	v_mfma_f32_16x16x32_bf16 v[2:5], v[180:183], v[216:219], v[2:5]
	s_barrier
	s_add_i32 s55, s55, 2
	s_add_u32 s53, s53, 0x100
	s_addc_u32 s54, s54, 0
	s_cmp_gt_u32 s55, 19
	s_mov_b64 s[18:19], s[20:21]
	s_cbranch_scc0 .LBB0_1628
	s_and_b64 vcc, exec, s[14:15]
	s_cbranch_vccz .LBB0_1631
	s_barrier

.LBB0_2400:
	s_cmp_lt_i32 s59, 14
	s_waitcnt vmcnt(0)
	s_barrier
	s_cbranch_scc1 .LBB0_2454
	s_waitcnt vmcnt(0)
	s_setprio 0
	s_barrier
	s_and_saveexec_b64 s[2:3], s[0:1]
	s_cbranch_execz .LBB0_2453
	s_waitcnt vmcnt(0) lgkmcnt(0)
	v_mov_b32_e32 v241, 0
	v_lshlrev_b32_e64 v254, 8, s31
	v_mov_b32_e32 v247, 1
	v_mov_b32_e32 v246, 0x3600
	global_atomic_add v248, v246, v247, s[60:61] sc0

.Lprio12:
.LBB0_2516:
	s_cmp_gt_i32 s58, 14
	s_cselect_b64 s[2:3], -1, 0
	s_cmp_lt_i32 s59, 15
	s_cselect_b64 s[4:5], -1, 0
	s_or_b64 s[2:3], s[2:3], s[4:5]
	s_and_b64 vcc, exec, s[2:3]
	s_cbranch_vccnz .LBB0_2634
	s_abs_i32 s2, s56
	v_cvt_f32_u32_e32 v1, s2
	s_sub_i32 s3, 0, s2
	s_ashr_i32 s46, s56, 31
	s_waitcnt vmcnt(0)
	v_mov_b32_e32 v2, 0
	v_rcp_iflag_f32_e32 v1, v1
	ds_read_b64 v[2:3], v2 offset:416
	v_mul_f32_e32 v1, 0x4f7ffffe, v1
	v_cvt_u32_f32_e32 v1, v1
	s_waitcnt lgkmcnt(0)
	v_readfirstlane_b32 s8, v2
	v_readfirstlane_b32 s9, v3
	v_readfirstlane_b32 s4, v1
	s_mul_i32 s3, s3, s4
	s_mul_hi_u32 s3, s4, s3
	s_add_i32 s4, s4, s3
	s_mul_hi_u32 s3, s4, 0x150
	s_mul_i32 s4, s3, s2
	s_sub_i32 s4, 0x150, s4
	s_add_i32 s5, s3, 1
	s_sub_i32 s6, s4, s2
	s_cmp_ge_u32 s4, s2
	s_cselect_b32 s3, s5, s3
	s_cselect_b32 s4, s6, s4
	s_add_i32 s5, s3, 1
	s_cmp_ge_u32 s4, s2
	s_cselect_b32 s2, s5, s3
	s_xor_b32 s2, s2, s46
	s_sub_i32 s47, s2, s46
	s_cmp_gt_i32 s47, 0
	s_cselect_b64 s[2:3], -1, 0
	s_and_b64 vcc, exec, s[2:3]
	s_mul_i32 s22, s56, s47
	s_cbranch_vccnz .LBB0_2524
	s_lshl_b32 s2, s22, 1
	s_sub_i32 s2, 0x2a0, s2
	s_cmp_le_i32 s2, s56
	s_cbranch_scc0 .LBB0_2523
	s_cmp_lg_u32 s47, 0
	s_cselect_b64 s[4:5], -1, 0
	s_cmp_ge_i32 s30, s2
	s_cselect_b64 s[6:7], -1, 0
	s_or_b64 s[4:5], s[4:5], s[6:7]
	s_mov_b64 s[2:3], 0
	s_and_b64 vcc, exec, s[4:5]
	s_mov_b64 s[4:5], 0
	s_cbranch_vccnz .LBB0_2525
	s_ashr_i32 s4, s30, 1
	s_cmpk_gt_i32 s4, 0x14f
	s_cbranch_scc1 .LBB0_2522
	s_ashr_i32 s5, s4, 31
	s_lshr_b32 s5, s5, 29
	s_add_i32 s5, s4, s5
	s_ashr_i32 s6, s5, 3
	s_and_b32 s5, s5, -8
	s_sub_i32 s4, s4, s5
	s_cmp_lt_i32 s4, 0
	s_cselect_b32 s5, 43, 42
	s_mul_i32 s4, s5, s4
	s_add_i32 s4, s4, s6
	s_mul_hi_i32 s5, s4, 0x92492493
	s_add_i32 s5, s5, s4
	s_lshr_b32 s6, s5, 31
	s_ashr_i32 s5, s5, 6
	s_add_i32 s5, s5, s6
	s_lshl_b32 s6, s5, 3
	s_mulk_i32 s5, 0x70
	s_sub_i32 s4, s4, s5
	s_bfe_i32 s5, s4, 0x80000
	s_bfe_u32 s5, s5, 0x3000c
	s_add_i32 s5, s4, s5
	s_bfe_i32 s7, s5, 0x80000
	s_and_b32 s5, s5, 0xf8
	s_sub_i32 s4, s4, s5
	s_sext_i32_i16 s7, s7
	s_sext_i32_i8 s4, s4
	s_add_i32 s12, s6, s4
	s_ashr_i32 s67, s7, 3

.LBB0_2547:
	v_lshl_add_u64 v[4:5], s[24:25], 0, v[206:207]
	s_add_i32 m0, s13, 0xc400
	ds_read_b128 v[190:193], v223 offset:1024
	ds_read_b128 v[194:197], v223 offset:2048
	ds_read_b128 v[182:185], v223 offset:3072
	ds_read_b128 v[186:189], v223 offset:4096
	ds_read_b128 v[174:177], v223 offset:5120
	ds_read_b128 v[178:181], v223 offset:6144
	ds_read_b128 v[166:169], v223 offset:7168
	ds_read_b128 v[170:173], v223 offset:8192
	global_load_lds_dwordx4 v[4:5], off
	v_lshl_add_u64 v[4:5], s[24:25], 0, v[204:205]
	s_add_i32 m0, s13, 0xe400
	s_nop 0
	global_load_lds_dwordx4 v[4:5], off
	s_waitcnt vmcnt(8)
	s_waitcnt lgkmcnt(0)
	s_barrier
	s_waitcnt lgkmcnt(0)
	v_mfma_f32_16x16x32_bf16 v[146:149], v[150:153], v[190:193], v[146:149]
	v_mfma_f32_16x16x32_bf16 v[142:145], v[158:161], v[190:193], v[142:145]
	v_mfma_f32_16x16x32_bf16 v[138:141], v[150:153], v[182:185], v[138:141]
	v_mfma_f32_16x16x32_bf16 v[134:137], v[158:161], v[182:185], v[134:137]
	v_mfma_f32_16x16x32_bf16 v[130:133], v[150:153], v[174:177], v[130:133]
	v_mfma_f32_16x16x32_bf16 v[126:129], v[158:161], v[174:177], v[126:129]
	v_mfma_f32_16x16x32_bf16 v[122:125], v[150:153], v[166:169], v[122:125]
	v_mfma_f32_16x16x32_bf16 v[118:121], v[158:161], v[166:169], v[118:121]
	v_mfma_f32_16x16x32_bf16 v[146:149], v[154:157], v[194:197], v[146:149]
	v_mfma_f32_16x16x32_bf16 v[142:145], v[162:165], v[194:197], v[142:145]
	v_mfma_f32_16x16x32_bf16 v[138:141], v[154:157], v[186:189], v[138:141]
	v_mfma_f32_16x16x32_bf16 v[134:137], v[162:165], v[186:189], v[134:137]
	v_mfma_f32_16x16x32_bf16 v[130:133], v[154:157], v[178:181], v[130:133]
	v_mfma_f32_16x16x32_bf16 v[126:129], v[162:165], v[178:181], v[126:129]
	v_mfma_f32_16x16x32_bf16 v[122:125], v[154:157], v[170:173], v[122:125]
	v_mfma_f32_16x16x32_bf16 v[118:121], v[162:165], v[170:173], v[118:121]
	s_and_b64 vcc, exec, s[4:5]
	s_cbranch_vccnz .LBB0_2549
	v_mfma_f32_16x16x32_bf16 v[82:85], v[6:9], v[190:193], v[82:85]
	v_mfma_f32_16x16x32_bf16 v[78:81], v[14:17], v[190:193], v[78:81]
	v_mfma_f32_16x16x32_bf16 v[74:77], v[6:9], v[182:185], v[74:77]
	v_mfma_f32_16x16x32_bf16 v[70:73], v[14:17], v[182:185], v[70:73]
	v_mfma_f32_16x16x32_bf16 v[66:69], v[6:9], v[174:177], v[66:69]
	v_mfma_f32_16x16x32_bf16 v[62:65], v[14:17], v[174:177], v[62:65]
	v_mfma_f32_16x16x32_bf16 v[58:61], v[6:9], v[166:169], v[58:61]
	v_mfma_f32_16x16x32_bf16 v[54:57], v[14:17], v[166:169], v[54:57]
	v_mfma_f32_16x16x32_bf16 v[82:85], v[10:13], v[194:197], v[82:85]
	v_mfma_f32_16x16x32_bf16 v[78:81], v[18:21], v[194:197], v[78:81]
	v_mfma_f32_16x16x32_bf16 v[74:77], v[10:13], v[186:189], v[74:77]
	v_mfma_f32_16x16x32_bf16 v[70:73], v[18:21], v[186:189], v[70:73]
	v_mfma_f32_16x16x32_bf16 v[66:69], v[10:13], v[178:181], v[66:69]
	v_mfma_f32_16x16x32_bf16 v[62:65], v[18:21], v[178:181], v[62:65]
	v_mfma_f32_16x16x32_bf16 v[58:61], v[10:13], v[170:173], v[58:61]
	v_mfma_f32_16x16x32_bf16 v[54:57], v[18:21], v[170:173], v[54:57]
.LBB0_2549:
	s_add_u32 s24, s24, 0x100
	s_addc_u32 s25, s25, 0
	s_cmp_eq_u32 s90, 12
	s_cselect_b64 s[92:93], -1, 0
	s_and_b64 s[44:45], s[92:93], exec
	s_cselect_b32 s45, s27, s25
	s_cselect_b32 s44, s85, s24
	s_cselect_b32 s95, s86, s89
	s_cselect_b32 s94, s87, s88
	s_and_b64 s[92:93], s[28:29], s[92:93]
	s_and_b64 s[92:93], s[92:93], exec
	s_cselect_b32 s91, 0, s37
	s_cselect_b32 s92, s6, s36
	s_barrier
	s_mov_b32 m0, s52
	v_lshl_add_u64 v[4:5], s[94:95], 0, v[200:201]
	s_add_u32 s92, s94, s92
	ds_read_b128 v[190:193], v223 offset:17408
	ds_read_b128 v[194:197], v223 offset:18432
	ds_read_b128 v[182:185], v223 offset:19456
	ds_read_b128 v[186:189], v223 offset:20480
	ds_read_b128 v[174:177], v223 offset:21504
	ds_read_b128 v[178:181], v223 offset:22528
	ds_read_b128 v[166:169], v223 offset:23552
	ds_read_b128 v[170:173], v223 offset:24576
	global_load_lds_dwordx4 v[4:5], off
	v_lshl_add_u64 v[210:211], s[94:95], 0, v[202:203]
	s_mov_b32 m0, s53
	s_addc_u32 s93, s95, s91
	global_load_lds_dwordx4 v[210:211], off
	v_lshl_add_u64 v[212:213], s[92:93], 0, v[200:201]
	s_mov_b32 m0, s54
	v_lshl_add_u64 v[214:215], s[92:93], 0, v[202:203]
	global_load_lds_dwordx4 v[212:213], off
	s_mov_b32 m0, s55
	v_lshl_add_u64 v[216:217], s[44:45], 0, v[200:201]
	global_load_lds_dwordx4 v[214:215], off
	s_mov_b32 m0, s57
	v_lshl_add_u64 v[218:219], s[44:45], 0, v[202:203]
	global_load_lds_dwordx4 v[216:217], off
	s_mov_b32 m0, s64
	s_nop 0
	global_load_lds_dwordx4 v[218:219], off
	s_waitcnt vmcnt(8)
	s_waitcnt lgkmcnt(0)
	s_barrier
	s_waitcnt lgkmcnt(0)
	v_mfma_f32_16x16x32_bf16 v[114:117], v[150:153], v[190:193], v[114:117]
	v_mfma_f32_16x16x32_bf16 v[110:113], v[158:161], v[190:193], v[110:113]
	v_mfma_f32_16x16x32_bf16 v[106:109], v[150:153], v[182:185], v[106:109]
	v_mfma_f32_16x16x32_bf16 v[102:105], v[158:161], v[182:185], v[102:105]
	v_mfma_f32_16x16x32_bf16 v[98:101], v[150:153], v[174:177], v[98:101]
	v_mfma_f32_16x16x32_bf16 v[94:97], v[158:161], v[174:177], v[94:97]
	v_mfma_f32_16x16x32_bf16 v[90:93], v[150:153], v[166:169], v[90:93]
	v_mfma_f32_16x16x32_bf16 v[86:89], v[158:161], v[166:169], v[86:89]
	v_mfma_f32_16x16x32_bf16 v[114:117], v[154:157], v[194:197], v[114:117]
	v_mfma_f32_16x16x32_bf16 v[110:113], v[162:165], v[194:197], v[110:113]
	v_mfma_f32_16x16x32_bf16 v[106:109], v[154:157], v[186:189], v[106:109]
	v_mfma_f32_16x16x32_bf16 v[102:105], v[162:165], v[186:189], v[102:105]
	v_mfma_f32_16x16x32_bf16 v[98:101], v[154:157], v[178:181], v[98:101]
	v_mfma_f32_16x16x32_bf16 v[94:97], v[162:165], v[178:181], v[94:97]
	v_mfma_f32_16x16x32_bf16 v[90:93], v[154:157], v[170:173], v[90:93]
	v_mfma_f32_16x16x32_bf16 v[86:89], v[162:165], v[170:173], v[86:89]
	s_and_b64 vcc, exec, s[4:5]
	s_cbranch_vccnz .LBB0_2551
	v_mfma_f32_16x16x32_bf16 v[50:53], v[6:9], v[190:193], v[50:53]
	v_mfma_f32_16x16x32_bf16 v[46:49], v[14:17], v[190:193], v[46:49]
	v_mfma_f32_16x16x32_bf16 v[42:45], v[6:9], v[182:185], v[42:45]
	v_mfma_f32_16x16x32_bf16 v[38:41], v[14:17], v[182:185], v[38:41]
	v_mfma_f32_16x16x32_bf16 v[34:37], v[6:9], v[174:177], v[34:37]
	v_mfma_f32_16x16x32_bf16 v[30:33], v[14:17], v[174:177], v[30:33]
	v_mfma_f32_16x16x32_bf16 v[26:29], v[6:9], v[166:169], v[26:29]
	v_mfma_f32_16x16x32_bf16 v[22:25], v[14:17], v[166:169], v[22:25]
	v_mfma_f32_16x16x32_bf16 v[50:53], v[10:13], v[194:197], v[50:53]
	v_mfma_f32_16x16x32_bf16 v[46:49], v[18:21], v[194:197], v[46:49]
	v_mfma_f32_16x16x32_bf16 v[42:45], v[10:13], v[186:189], v[42:45]
	v_mfma_f32_16x16x32_bf16 v[38:41], v[18:21], v[186:189], v[38:41]
	v_mfma_f32_16x16x32_bf16 v[34:37], v[10:13], v[178:181], v[34:37]
	v_mfma_f32_16x16x32_bf16 v[30:33], v[18:21], v[178:181], v[30:33]
	v_mfma_f32_16x16x32_bf16 v[26:29], v[10:13], v[170:173], v[26:29]
	v_mfma_f32_16x16x32_bf16 v[22:25], v[18:21], v[170:173], v[22:25]

.LBB0_2553:
	s_add_u32 s44, s44, 0x40000
	s_addc_u32 s45, s45, 0
	s_mov_b32 m0, s65
	v_lshl_add_u64 v[232:233], s[44:45], 0, v[200:201]
	ds_read_b128 v[190:193], v223 offset:33792
	ds_read_b128 v[194:197], v223 offset:34816
	ds_read_b128 v[182:185], v223 offset:35840
	ds_read_b128 v[186:189], v223 offset:36864
	ds_read_b128 v[174:177], v223 offset:37888
	ds_read_b128 v[178:181], v223 offset:38912
	ds_read_b128 v[166:169], v223 offset:39936
	ds_read_b128 v[170:173], v223 offset:40960
	global_load_lds_dwordx4 v[232:233], off
	v_lshl_add_u64 v[232:233], s[44:45], 0, v[202:203]
	s_mov_b32 m0, s66
	s_nop 0
	global_load_lds_dwordx4 v[232:233], off
	s_waitcnt vmcnt(8)
	s_waitcnt lgkmcnt(0)
	s_barrier
	s_waitcnt lgkmcnt(0)
	v_mfma_f32_16x16x32_bf16 v[146:149], v[150:153], v[190:193], v[146:149]
	v_mfma_f32_16x16x32_bf16 v[142:145], v[158:161], v[190:193], v[142:145]
	v_mfma_f32_16x16x32_bf16 v[138:141], v[150:153], v[182:185], v[138:141]
	v_mfma_f32_16x16x32_bf16 v[134:137], v[158:161], v[182:185], v[134:137]
	v_mfma_f32_16x16x32_bf16 v[130:133], v[150:153], v[174:177], v[130:133]
	v_mfma_f32_16x16x32_bf16 v[126:129], v[158:161], v[174:177], v[126:129]
	v_mfma_f32_16x16x32_bf16 v[122:125], v[150:153], v[166:169], v[122:125]
	v_mfma_f32_16x16x32_bf16 v[118:121], v[158:161], v[166:169], v[118:121]
	v_mfma_f32_16x16x32_bf16 v[146:149], v[154:157], v[194:197], v[146:149]
	v_mfma_f32_16x16x32_bf16 v[142:145], v[162:165], v[194:197], v[142:145]
	v_mfma_f32_16x16x32_bf16 v[138:141], v[154:157], v[186:189], v[138:141]
	v_mfma_f32_16x16x32_bf16 v[134:137], v[162:165], v[186:189], v[134:137]
	v_mfma_f32_16x16x32_bf16 v[130:133], v[154:157], v[178:181], v[130:133]
	v_mfma_f32_16x16x32_bf16 v[126:129], v[162:165], v[178:181], v[126:129]
	v_mfma_f32_16x16x32_bf16 v[122:125], v[154:157], v[170:173], v[122:125]
	v_mfma_f32_16x16x32_bf16 v[118:121], v[162:165], v[170:173], v[118:121]
	s_and_b64 vcc, exec, s[4:5]
	s_cbranch_vccnz .LBB0_2555
	v_mfma_f32_16x16x32_bf16 v[82:85], v[6:9], v[190:193], v[82:85]
	v_mfma_f32_16x16x32_bf16 v[78:81], v[14:17], v[190:193], v[78:81]
	v_mfma_f32_16x16x32_bf16 v[74:77], v[6:9], v[182:185], v[74:77]
	v_mfma_f32_16x16x32_bf16 v[70:73], v[14:17], v[182:185], v[70:73]
	v_mfma_f32_16x16x32_bf16 v[66:69], v[6:9], v[174:177], v[66:69]
	v_mfma_f32_16x16x32_bf16 v[62:65], v[14:17], v[174:177], v[62:65]
	v_mfma_f32_16x16x32_bf16 v[58:61], v[6:9], v[166:169], v[58:61]
	v_mfma_f32_16x16x32_bf16 v[54:57], v[14:17], v[166:169], v[54:57]
	v_mfma_f32_16x16x32_bf16 v[82:85], v[10:13], v[194:197], v[82:85]
	v_mfma_f32_16x16x32_bf16 v[78:81], v[18:21], v[194:197], v[78:81]
	v_mfma_f32_16x16x32_bf16 v[74:77], v[10:13], v[186:189], v[74:77]
	v_mfma_f32_16x16x32_bf16 v[70:73], v[18:21], v[186:189], v[70:73]
	v_mfma_f32_16x16x32_bf16 v[66:69], v[10:13], v[178:181], v[66:69]
	v_mfma_f32_16x16x32_bf16 v[62:65], v[18:21], v[178:181], v[62:65]
	v_mfma_f32_16x16x32_bf16 v[58:61], v[10:13], v[170:173], v[58:61]
	v_mfma_f32_16x16x32_bf16 v[54:57], v[18:21], v[170:173], v[54:57]
.LBB0_2555:
	s_barrier
	s_mov_b32 m0, s71
	v_lshl_add_u64 v[4:5], v[4:5], 0, s[16:17]
	ds_read_b128 v[190:193], v223 offset:50176
	ds_read_b128 v[194:197], v223 offset:51200
	ds_read_b128 v[182:185], v223 offset:52224
	ds_read_b128 v[186:189], v223 offset:53248
	ds_read_b128 v[174:177], v223 offset:54272
	ds_read_b128 v[178:181], v223 offset:55296
	ds_read_b128 v[166:169], v223 offset:56320
	ds_read_b128 v[170:173], v223 offset:57344
	global_load_lds_dwordx4 v[4:5], off
	v_lshl_add_u64 v[4:5], v[210:211], 0, s[16:17]
	s_mov_b32 m0, s72
	s_nop 0
	global_load_lds_dwordx4 v[4:5], off
	v_lshl_add_u64 v[4:5], v[212:213], 0, s[16:17]
	s_mov_b32 m0, s75
	s_nop 0
	global_load_lds_dwordx4 v[4:5], off
	v_lshl_add_u64 v[4:5], v[214:215], 0, s[16:17]
	s_mov_b32 m0, s76
	s_nop 0
	global_load_lds_dwordx4 v[4:5], off
	v_lshl_add_u64 v[4:5], v[216:217], 0, s[16:17]
	s_mov_b32 m0, s73
	s_nop 0
	global_load_lds_dwordx4 v[4:5], off
	v_lshl_add_u64 v[4:5], v[218:219], 0, s[16:17]
	s_mov_b32 m0, s74
	s_nop 0
	global_load_lds_dwordx4 v[4:5], off
	s_waitcnt vmcnt(8)
	s_waitcnt lgkmcnt(0)
	s_barrier
	s_waitcnt lgkmcnt(0)
	v_mfma_f32_16x16x32_bf16 v[114:117], v[150:153], v[190:193], v[114:117]
	v_mfma_f32_16x16x32_bf16 v[110:113], v[158:161], v[190:193], v[110:113]
	v_mfma_f32_16x16x32_bf16 v[106:109], v[150:153], v[182:185], v[106:109]
	v_mfma_f32_16x16x32_bf16 v[102:105], v[158:161], v[182:185], v[102:105]
	v_mfma_f32_16x16x32_bf16 v[98:101], v[150:153], v[174:177], v[98:101]
	v_mfma_f32_16x16x32_bf16 v[94:97], v[158:161], v[174:177], v[94:97]
	v_mfma_f32_16x16x32_bf16 v[90:93], v[150:153], v[166:169], v[90:93]
	v_mfma_f32_16x16x32_bf16 v[86:89], v[158:161], v[166:169], v[86:89]
	v_mfma_f32_16x16x32_bf16 v[114:117], v[154:157], v[194:197], v[114:117]
	v_mfma_f32_16x16x32_bf16 v[110:113], v[162:165], v[194:197], v[110:113]
	v_mfma_f32_16x16x32_bf16 v[106:109], v[154:157], v[186:189], v[106:109]
	v_mfma_f32_16x16x32_bf16 v[102:105], v[162:165], v[186:189], v[102:105]
	v_mfma_f32_16x16x32_bf16 v[98:101], v[154:157], v[178:181], v[98:101]
	v_mfma_f32_16x16x32_bf16 v[94:97], v[162:165], v[178:181], v[94:97]
	v_mfma_f32_16x16x32_bf16 v[90:93], v[154:157], v[170:173], v[90:93]
	v_mfma_f32_16x16x32_bf16 v[86:89], v[162:165], v[170:173], v[86:89]
	s_and_b64 vcc, exec, s[4:5]
	s_cbranch_vccnz .LBB0_2544
	v_mfma_f32_16x16x32_bf16 v[50:53], v[6:9], v[190:193], v[50:53]
	v_mfma_f32_16x16x32_bf16 v[46:49], v[14:17], v[190:193], v[46:49]
	v_mfma_f32_16x16x32_bf16 v[42:45], v[6:9], v[182:185], v[42:45]
	v_mfma_f32_16x16x32_bf16 v[38:41], v[14:17], v[182:185], v[38:41]
	v_mfma_f32_16x16x32_bf16 v[34:37], v[6:9], v[174:177], v[34:37]
	v_mfma_f32_16x16x32_bf16 v[30:33], v[14:17], v[174:177], v[30:33]
	v_mfma_f32_16x16x32_bf16 v[26:29], v[6:9], v[166:169], v[26:29]
	v_mfma_f32_16x16x32_bf16 v[22:25], v[14:17], v[166:169], v[22:25]
	v_mfma_f32_16x16x32_bf16 v[50:53], v[10:13], v[194:197], v[50:53]
	v_mfma_f32_16x16x32_bf16 v[46:49], v[18:21], v[194:197], v[46:49]
	v_mfma_f32_16x16x32_bf16 v[42:45], v[10:13], v[186:189], v[42:45]
	v_mfma_f32_16x16x32_bf16 v[38:41], v[18:21], v[186:189], v[38:41]
	v_mfma_f32_16x16x32_bf16 v[34:37], v[10:13], v[178:181], v[34:37]
	v_mfma_f32_16x16x32_bf16 v[30:33], v[18:21], v[178:181], v[30:33]
	v_mfma_f32_16x16x32_bf16 v[26:29], v[10:13], v[170:173], v[26:29]
	v_mfma_f32_16x16x32_bf16 v[22:25], v[18:21], v[170:173], v[22:25]
	s_branch .LBB0_2544

.LBB0_2579:
	s_cmp_lt_i32 s59, 16
	s_waitcnt vmcnt(0)
	s_barrier
	s_cbranch_scc1 .LBB0_2634
	s_waitcnt vmcnt(0)
	s_setprio 0
	s_barrier
	s_and_saveexec_b64 s[2:3], s[0:1]
	s_cbranch_execz .LBB0_2633
	s_waitcnt vmcnt(0) lgkmcnt(0)
	v_mov_b32_e32 v241, 0
	v_lshlrev_b32_e64 v254, 8, s31
	v_mov_b32_e32 v247, 1
	v_mov_b32_e32 v246, 0x3600
	global_atomic_add v248, v246, v247, s[60:61] sc0

.Lprio17:
.LBB0_3136:
	s_cmp_gt_i32 s58, 20
	s_cselect_b64 s[2:3], -1, 0
	s_cmp_lt_i32 s59, 21
	s_cselect_b64 s[4:5], -1, 0
	s_or_b64 s[2:3], s[2:3], s[4:5]
	s_and_b64 vcc, exec, s[2:3]
	s_cbranch_vccnz .LBB0_3209
	v_mov_b32_e32 v131, 0
	s_waitcnt vmcnt(0)
	ds_read_b64 v[2:3], v131 offset:416
	s_cmpk_gt_i32 s30, 0xbf
	s_waitcnt lgkmcnt(0)
	v_readfirstlane_b32 s3, v2
	v_readfirstlane_b32 s4, v3
	s_cbranch_scc1 .LBB0_3155
	s_add_u32 s34, s3, 0x3d28000
	v_lshlrev_b32_e32 v1, 4, v0
	s_addc_u32 s35, s4, 0
	v_or_b32_e32 v10, 0x2000, v1
	s_add_u32 s36, s3, 0x6c8000
	v_bfe_u32 v11, v0, 2, 4
	v_lshrrev_b32_e32 v3, 7, v10
	s_movk_i32 s5, 0x70
	s_addc_u32 s37, s4, 0
	v_and_b32_e32 v4, 0x60, v3
	v_and_or_b32 v3, v3, s5, v11
	v_lshrrev_b32_e32 v7, 5, v0
	s_movk_i32 s5, 0x64
	s_ashr_i32 s39, s30, 31
	v_bitop3_b32 v4, v4, s5, v7 bitop3:0xc8
	s_lshr_b32 s5, s39, 29
	s_add_i32 s5, s30, s5
	s_ashr_i32 s6, s5, 3
	s_and_b32 s5, s5, -8
	s_lshr_b32 s2, s33, 8
	s_lshl_b32 s38, s68, 10
	s_sub_i32 s5, s30, s5
	s_cmp_lt_i32 s5, 0
	s_cselect_b32 s7, 25, 24
	s_mul_i32 s5, s7, s5
	s_add_i32 s5, s5, s6
	s_ashr_i32 s6, s5, 31
	s_lshr_b32 s6, s6, 26
	s_add_i32 s6, s5, s6
	s_ashr_i32 s7, s6, 6
	s_andn2_b32 s6, s6, 63
	s_sub_i32 s5, s5, s6
	s_bfe_i32 s6, s5, 0x80000
	s_lshr_b32 s6, s6, 7
	s_bfe_u32 s8, s6, 0x30005
	s_add_i32 s8, s5, s8
	s_and_b32 s10, s8, 0xf8
	s_bfe_u32 s6, s6, 0x40004
	s_sub_i32 s10, s5, s10
	s_add_i32 s5, s5, s6
	s_bfe_i32 s9, s8, 0x80000
	s_bfe_i32 s5, s5, 0x80000
	s_sext_i32_i16 s9, s9
	s_sext_i32_i16 s5, s5
	s_ashr_i32 s9, s9, 3
	s_ashr_i32 s48, s5, 4
	s_bfe_u32 s5, s8, 0x10007
	s_add_i32 s5, s9, s5
	s_and_b32 s5, s5, 0xfffe
	s_sub_i32 s5, s9, s5
	s_lshl_b32 s7, s7, 3
	s_sext_i32_i8 s10, s10
	s_sext_i32_i16 s51, s5
	s_add_i32 s16, s7, s10
	s_lshl_b32 s8, s51, 9
	s_lshl_b32 s10, s48, 1
	v_and_b32_e32 v2, 32, v0
	s_ashr_i32 s17, s16, 31
	s_ashr_i32 s9, s8, 31
	s_ashr_i32 s11, s10, 31
	v_and_b32_e32 v12, 64, v0
	v_bitop3_b32 v13, v1, v2, 48 bitop3:0x6c
	s_lshl_b64 s[6:7], s[16:17], 19
	s_lshl_b64 s[8:9], s[8:9], 1
	s_lshl_b64 s[10:11], s[10:11], 18
	v_or_b32_e32 v1, v12, v13
	v_lshrrev_b32_e32 v2, 3, v0
	s_add_u32 s5, s36, s10
	v_lshrrev_b32_e32 v14, 1, v0
	v_lshl_or_b32 v134, v3, 11, v1
	v_and_b32_e32 v3, 32, v2
	s_addc_u32 s10, s37, s11
	v_bfe_u32 v5, v0, 2, 2
	v_and_b32_e32 v6, 24, v14
	v_bitop3_b32 v3, v3, 36, v7 bitop3:0xc8
	s_add_u32 s26, s5, s8
	v_or3_b32 v3, v3, v5, v6
	s_addc_u32 s27, s10, s9
	s_add_i32 s17, s38, 0
	v_lshl_or_b32 v130, v3, 11, v1
	s_add_i32 m0, s17, 0x10400
	v_or3_b32 v4, v4, v5, v6
	global_load_lds_dwordx4 v130, s[26:27]
	s_add_i32 m0, s17, 0x12400
	s_add_u32 s5, s34, s6
	s_addc_u32 s10, s35, s7
	v_lshl_or_b32 v132, v4, 11, v1
	s_add_u32 s6, s26, 0x40000
	global_load_lds_dwordx4 v132, s[26:27]
	s_addc_u32 s7, s27, 0
	s_add_i32 m0, s17, 0x14400
	v_and_or_b32 v2, v2, 48, v11
	global_load_lds_dwordx4 v130, s[6:7]
	s_add_i32 m0, s17, 0x16400
	s_add_u32 s24, s5, s8
	s_addc_u32 s25, s10, s9
	s_add_i32 s40, s17, 0x400
	s_add_i32 s41, s17, 0x2400
	v_lshl_or_b32 v136, v2, 11, v1
	global_load_lds_dwordx4 v132, s[6:7]
	s_mov_b32 m0, s40
	s_add_u32 s6, s24, 0x40000
	global_load_lds_dwordx4 v136, s[24:25]
	s_mov_b32 m0, s41
	s_addc_u32 s7, s25, 0
	s_add_i32 s42, s17, 0x4400
	global_load_lds_dwordx4 v134, s[24:25]
	s_mov_b32 m0, s42
	s_add_i32 s43, s17, 0x6400
	global_load_lds_dwordx4 v136, s[6:7]
	s_mov_b32 m0, s43
	v_mov_b32_e32 v133, v131
	global_load_lds_dwordx4 v134, s[6:7]
	v_mov_b32_e32 v137, v131
	v_mov_b32_e32 v135, v131
	s_cmp_eq_u32 s2, 1
	v_lshl_add_u64 v[8:9], s[26:27], 0, v[130:131]
	v_lshl_add_u64 v[6:7], s[26:27], 0, v[132:133]
	v_lshl_add_u64 v[2:3], s[24:25], 0, v[136:137]
	s_cselect_b64 s[6:7], -1, 0
	s_cmp_lg_u32 s2, 1
	v_lshl_add_u64 v[4:5], s[24:25], 0, v[134:135]
	s_cbranch_scc1 .LBB0_3140
	s_barrier

.LBB0_3148:
	ds_read_b128 v[152:155], v148
	ds_read_b128 v[156:159], v148 offset:1024
	ds_read_b128 v[160:163], v148 offset:2048
	ds_read_b128 v[164:167], v148 offset:3072
	ds_read_b128 v[168:171], v149
	ds_read_b128 v[172:175], v149 offset:1024
	ds_read_b128 v[176:179], v149 offset:2048
	ds_read_b128 v[180:183], v149 offset:3072
	s_add_u32 s4, s24, 0x100
	s_addc_u32 s5, s25, 0
	s_cmp_eq_u32 s64, 4
	s_cselect_b32 s29, s19, s5
	s_cselect_b32 s28, s54, s4
	s_cselect_b32 s27, s21, s57
	s_cselect_b32 s26, s20, s55
	v_lshl_add_u64 v[196:197], s[24:25], 0, v[140:141]
	s_add_i32 m0, s17, 0xc400
	ds_read_b128 v[184:187], v150 offset:1024
	ds_read_b128 v[188:191], v150 offset:2048
	ds_read_b128 v[192:195], v150 offset:3072
	ds_read_b128 v[200:203], v150 offset:4096
	ds_read_b128 v[204:207], v150 offset:5120
	ds_read_b128 v[208:211], v150 offset:6144
	ds_read_b128 v[212:215], v150 offset:7168
	ds_read_b128 v[216:219], v150 offset:8192
	global_load_lds_dwordx4 v[196:197], off
	v_lshl_add_u64 v[196:197], s[24:25], 0, v[138:139]
	s_add_i32 m0, s17, 0xe400
	s_nop 0
	global_load_lds_dwordx4 v[196:197], off
	s_waitcnt vmcnt(8)
	s_waitcnt lgkmcnt(0)
	s_barrier
	s_waitcnt lgkmcnt(0)
	v_mfma_f32_16x16x32_bf16 v[126:129], v[152:155], v[184:187], v[126:129]
	v_mfma_f32_16x16x32_bf16 v[122:125], v[160:163], v[184:187], v[122:125]
	v_mfma_f32_16x16x32_bf16 v[118:121], v[152:155], v[192:195], v[118:121]
	v_mfma_f32_16x16x32_bf16 v[114:117], v[160:163], v[192:195], v[114:117]
	v_mfma_f32_16x16x32_bf16 v[102:105], v[152:155], v[204:207], v[102:105]
	v_mfma_f32_16x16x32_bf16 v[98:101], v[160:163], v[204:207], v[98:101]
	v_mfma_f32_16x16x32_bf16 v[86:89], v[152:155], v[212:215], v[86:89]
	v_mfma_f32_16x16x32_bf16 v[82:85], v[160:163], v[212:215], v[82:85]
	v_mfma_f32_16x16x32_bf16 v[126:129], v[156:159], v[188:191], v[126:129]
	v_mfma_f32_16x16x32_bf16 v[122:125], v[164:167], v[188:191], v[122:125]
	v_mfma_f32_16x16x32_bf16 v[118:121], v[156:159], v[200:203], v[118:121]
	v_mfma_f32_16x16x32_bf16 v[114:117], v[164:167], v[200:203], v[114:117]
	v_mfma_f32_16x16x32_bf16 v[102:105], v[156:159], v[208:211], v[102:105]
	v_mfma_f32_16x16x32_bf16 v[98:101], v[164:167], v[208:211], v[98:101]
	v_mfma_f32_16x16x32_bf16 v[86:89], v[156:159], v[216:219], v[86:89]
	v_mfma_f32_16x16x32_bf16 v[82:85], v[164:167], v[216:219], v[82:85]
	v_mfma_f32_16x16x32_bf16 v[110:113], v[168:171], v[184:187], v[110:113]
	v_mfma_f32_16x16x32_bf16 v[106:109], v[176:179], v[184:187], v[106:109]
	v_mfma_f32_16x16x32_bf16 v[94:97], v[168:171], v[192:195], v[94:97]
	v_mfma_f32_16x16x32_bf16 v[90:93], v[176:179], v[192:195], v[90:93]
	v_mfma_f32_16x16x32_bf16 v[78:81], v[168:171], v[204:207], v[78:81]
	v_mfma_f32_16x16x32_bf16 v[74:77], v[176:179], v[204:207], v[74:77]
	v_mfma_f32_16x16x32_bf16 v[70:73], v[168:171], v[212:215], v[70:73]
	v_mfma_f32_16x16x32_bf16 v[66:69], v[176:179], v[212:215], v[66:69]
	v_mfma_f32_16x16x32_bf16 v[110:113], v[172:175], v[188:191], v[110:113]
	v_mfma_f32_16x16x32_bf16 v[106:109], v[180:183], v[188:191], v[106:109]
	v_mfma_f32_16x16x32_bf16 v[94:97], v[172:175], v[200:203], v[94:97]
	v_mfma_f32_16x16x32_bf16 v[90:93], v[180:183], v[200:203], v[90:93]
	v_mfma_f32_16x16x32_bf16 v[78:81], v[172:175], v[208:211], v[78:81]
	v_mfma_f32_16x16x32_bf16 v[74:77], v[180:183], v[208:211], v[74:77]
	v_mfma_f32_16x16x32_bf16 v[70:73], v[172:175], v[216:219], v[70:73]
	v_mfma_f32_16x16x32_bf16 v[66:69], v[180:183], v[216:219], v[66:69]
	s_barrier
	s_add_i32 s24, s49, s38
	v_lshl_add_u64 v[196:197], s[26:27], 0, v[130:131]
	s_mov_b32 m0, s24
	ds_read_b128 v[184:187], v150 offset:17408
	ds_read_b128 v[188:191], v150 offset:18432
	ds_read_b128 v[192:195], v150 offset:19456
	ds_read_b128 v[200:203], v150 offset:20480
	ds_read_b128 v[204:207], v150 offset:21504
	ds_read_b128 v[208:211], v150 offset:22528
	ds_read_b128 v[212:215], v150 offset:23552
	ds_read_b128 v[216:219], v150 offset:24576
	global_load_lds_dwordx4 v[196:197], off
	s_add_i32 m0, s24, 0x2000
	s_add_u32 s24, s26, 0x40000
	v_lshl_add_u64 v[220:221], s[26:27], 0, v[132:133]
	s_addc_u32 s25, s27, 0
	s_add_i32 s65, s50, s38
	global_load_lds_dwordx4 v[220:221], off
	v_lshl_add_u64 v[222:223], s[24:25], 0, v[130:131]
	s_mov_b32 m0, s65
	v_lshl_add_u64 v[224:225], s[28:29], 0, v[134:135]
	global_load_lds_dwordx4 v[222:223], off
	v_lshl_add_u64 v[222:223], s[24:25], 0, v[132:133]
	s_add_i32 m0, s65, 0x2000
	s_nop 0
	global_load_lds_dwordx4 v[222:223], off
	v_lshl_add_u64 v[222:223], s[28:29], 0, v[136:137]
	s_mov_b32 m0, s40
	s_nop 0
	global_load_lds_dwordx4 v[222:223], off
	s_mov_b32 m0, s41
	s_nop 0
	global_load_lds_dwordx4 v[224:225], off
	s_waitcnt vmcnt(8)
	s_waitcnt lgkmcnt(0)
	s_barrier
	s_waitcnt lgkmcnt(0)
	v_mfma_f32_16x16x32_bf16 v[62:65], v[152:155], v[184:187], v[62:65]
	v_mfma_f32_16x16x32_bf16 v[58:61], v[160:163], v[184:187], v[58:61]
	v_mfma_f32_16x16x32_bf16 v[54:57], v[152:155], v[192:195], v[54:57]
	v_mfma_f32_16x16x32_bf16 v[50:53], v[160:163], v[192:195], v[50:53]
	v_mfma_f32_16x16x32_bf16 v[38:41], v[152:155], v[204:207], v[38:41]
	v_mfma_f32_16x16x32_bf16 v[34:37], v[160:163], v[204:207], v[34:37]
	v_mfma_f32_16x16x32_bf16 v[22:25], v[152:155], v[212:215], v[22:25]
	v_mfma_f32_16x16x32_bf16 v[18:21], v[160:163], v[212:215], v[18:21]
	v_mfma_f32_16x16x32_bf16 v[62:65], v[156:159], v[188:191], v[62:65]
	v_mfma_f32_16x16x32_bf16 v[58:61], v[164:167], v[188:191], v[58:61]
	v_mfma_f32_16x16x32_bf16 v[54:57], v[156:159], v[200:203], v[54:57]
	v_mfma_f32_16x16x32_bf16 v[50:53], v[164:167], v[200:203], v[50:53]
	v_mfma_f32_16x16x32_bf16 v[38:41], v[156:159], v[208:211], v[38:41]
	v_mfma_f32_16x16x32_bf16 v[34:37], v[164:167], v[208:211], v[34:37]
	v_mfma_f32_16x16x32_bf16 v[22:25], v[156:159], v[216:219], v[22:25]
	v_mfma_f32_16x16x32_bf16 v[18:21], v[164:167], v[216:219], v[18:21]
	v_mfma_f32_16x16x32_bf16 v[46:49], v[168:171], v[184:187], v[46:49]
	v_mfma_f32_16x16x32_bf16 v[42:45], v[176:179], v[184:187], v[42:45]
	v_mfma_f32_16x16x32_bf16 v[30:33], v[168:171], v[192:195], v[30:33]
	v_mfma_f32_16x16x32_bf16 v[26:29], v[176:179], v[192:195], v[26:29]
	v_mfma_f32_16x16x32_bf16 v[14:17], v[168:171], v[204:207], v[14:17]
	v_mfma_f32_16x16x32_bf16 v[10:13], v[176:179], v[204:207], v[10:13]
	v_mfma_f32_16x16x32_bf16 v[6:9], v[168:171], v[212:215], v[6:9]
	v_mfma_f32_16x16x32_bf16 v[2:5], v[176:179], v[212:215], v[2:5]
	v_mfma_f32_16x16x32_bf16 v[46:49], v[172:175], v[188:191], v[46:49]
	v_mfma_f32_16x16x32_bf16 v[42:45], v[180:183], v[188:191], v[42:45]
	v_mfma_f32_16x16x32_bf16 v[30:33], v[172:175], v[200:203], v[30:33]
	v_mfma_f32_16x16x32_bf16 v[26:29], v[180:183], v[200:203], v[26:29]
	v_mfma_f32_16x16x32_bf16 v[14:17], v[172:175], v[208:211], v[14:17]
	v_mfma_f32_16x16x32_bf16 v[10:13], v[180:183], v[208:211], v[10:13]
	v_mfma_f32_16x16x32_bf16 v[6:9], v[172:175], v[216:219], v[6:9]
	v_mfma_f32_16x16x32_bf16 v[2:5], v[180:183], v[216:219], v[2:5]
	s_barrier
	s_add_i32 s65, 0, 0x18400
	v_add_u32_e32 v151, s65, v146
	s_add_i32 s66, 0, 0x1c400
	ds_read_b128 v[152:155], v151
	ds_read_b128 v[156:159], v151 offset:1024
	ds_read_b128 v[160:163], v151 offset:2048
	ds_read_b128 v[164:167], v151 offset:3072
	v_add_u32_e32 v151, s66, v146
	ds_read_b128 v[168:171], v151
	ds_read_b128 v[172:175], v151 offset:1024
	ds_read_b128 v[176:179], v151 offset:2048
	ds_read_b128 v[180:183], v151 offset:3072
	s_add_u32 s24, s28, 0x40000
	s_addc_u32 s25, s29, 0
	s_mov_b32 m0, s42
	v_lshl_add_u64 v[226:227], s[24:25], 0, v[136:137]
	ds_read_b128 v[184:187], v150 offset:33792
	ds_read_b128 v[188:191], v150 offset:34816
	ds_read_b128 v[192:195], v150 offset:35840
	ds_read_b128 v[200:203], v150 offset:36864
	ds_read_b128 v[204:207], v150 offset:37888
	ds_read_b128 v[208:211], v150 offset:38912
	ds_read_b128 v[212:215], v150 offset:39936
	ds_read_b128 v[216:219], v150 offset:40960
	global_load_lds_dwordx4 v[226:227], off
	v_lshl_add_u64 v[226:227], s[24:25], 0, v[134:135]
	s_mov_b32 m0, s43
	s_nop 0
	global_load_lds_dwordx4 v[226:227], off
	s_waitcnt vmcnt(8)
	s_waitcnt lgkmcnt(0)
	s_barrier
	s_waitcnt lgkmcnt(0)
	v_mfma_f32_16x16x32_bf16 v[126:129], v[152:155], v[184:187], v[126:129]
	v_mfma_f32_16x16x32_bf16 v[122:125], v[160:163], v[184:187], v[122:125]
	v_mfma_f32_16x16x32_bf16 v[118:121], v[152:155], v[192:195], v[118:121]
	v_mfma_f32_16x16x32_bf16 v[114:117], v[160:163], v[192:195], v[114:117]
	v_mfma_f32_16x16x32_bf16 v[102:105], v[152:155], v[204:207], v[102:105]
	v_mfma_f32_16x16x32_bf16 v[98:101], v[160:163], v[204:207], v[98:101]
	v_mfma_f32_16x16x32_bf16 v[86:89], v[152:155], v[212:215], v[86:89]
	v_mfma_f32_16x16x32_bf16 v[82:85], v[160:163], v[212:215], v[82:85]
	v_mfma_f32_16x16x32_bf16 v[126:129], v[156:159], v[188:191], v[126:129]
	v_mfma_f32_16x16x32_bf16 v[122:125], v[164:167], v[188:191], v[122:125]
	v_mfma_f32_16x16x32_bf16 v[118:121], v[156:159], v[200:203], v[118:121]
	v_mfma_f32_16x16x32_bf16 v[114:117], v[164:167], v[200:203], v[114:117]
	v_mfma_f32_16x16x32_bf16 v[102:105], v[156:159], v[208:211], v[102:105]
	v_mfma_f32_16x16x32_bf16 v[98:101], v[164:167], v[208:211], v[98:101]
	v_mfma_f32_16x16x32_bf16 v[86:89], v[156:159], v[216:219], v[86:89]
	v_mfma_f32_16x16x32_bf16 v[82:85], v[164:167], v[216:219], v[82:85]
	v_mfma_f32_16x16x32_bf16 v[110:113], v[168:171], v[184:187], v[110:113]
	v_mfma_f32_16x16x32_bf16 v[106:109], v[176:179], v[184:187], v[106:109]
	v_mfma_f32_16x16x32_bf16 v[94:97], v[168:171], v[192:195], v[94:97]
	v_mfma_f32_16x16x32_bf16 v[90:93], v[176:179], v[192:195], v[90:93]
	v_mfma_f32_16x16x32_bf16 v[78:81], v[168:171], v[204:207], v[78:81]
	v_mfma_f32_16x16x32_bf16 v[74:77], v[176:179], v[204:207], v[74:77]
	v_mfma_f32_16x16x32_bf16 v[70:73], v[168:171], v[212:215], v[70:73]
	v_mfma_f32_16x16x32_bf16 v[66:69], v[176:179], v[212:215], v[66:69]
	v_mfma_f32_16x16x32_bf16 v[110:113], v[172:175], v[188:191], v[110:113]
	v_mfma_f32_16x16x32_bf16 v[106:109], v[180:183], v[188:191], v[106:109]
	v_mfma_f32_16x16x32_bf16 v[94:97], v[172:175], v[200:203], v[94:97]
	v_mfma_f32_16x16x32_bf16 v[90:93], v[180:183], v[200:203], v[90:93]
	v_mfma_f32_16x16x32_bf16 v[78:81], v[172:175], v[208:211], v[78:81]
	v_mfma_f32_16x16x32_bf16 v[74:77], v[180:183], v[208:211], v[74:77]
	v_mfma_f32_16x16x32_bf16 v[70:73], v[172:175], v[216:219], v[70:73]
	v_mfma_f32_16x16x32_bf16 v[66:69], v[180:183], v[216:219], v[66:69]
	s_barrier
	s_add_i32 s24, s65, s38
	v_lshl_add_u64 v[196:197], v[196:197], 0, s[12:13]
	s_mov_b32 m0, s24
	ds_read_b128 v[184:187], v150 offset:50176
	ds_read_b128 v[188:191], v150 offset:51200
	ds_read_b128 v[192:195], v150 offset:52224
	ds_read_b128 v[200:203], v150 offset:53248
	ds_read_b128 v[204:207], v150 offset:54272
	ds_read_b128 v[208:211], v150 offset:55296
	ds_read_b128 v[212:215], v150 offset:56320
	ds_read_b128 v[216:219], v150 offset:57344
	global_load_lds_dwordx4 v[196:197], off
	s_add_i32 m0, s24, 0x2000
	s_add_u32 s24, s26, 0x40080
	v_lshl_add_u64 v[196:197], v[220:221], 0, s[12:13]
	s_addc_u32 s25, s27, 0
	s_add_i32 s26, s66, s38
	global_load_lds_dwordx4 v[196:197], off
	v_lshl_add_u64 v[196:197], s[24:25], 0, v[130:131]
	s_mov_b32 m0, s26
	s_nop 0
	global_load_lds_dwordx4 v[196:197], off
	v_lshl_add_u64 v[196:197], s[24:25], 0, v[132:133]
	s_add_i32 m0, s26, 0x2000
	s_nop 0
	global_load_lds_dwordx4 v[196:197], off
	v_lshl_add_u64 v[196:197], v[222:223], 0, s[12:13]
	s_mov_b32 m0, s44
	s_nop 0
	global_load_lds_dwordx4 v[196:197], off
	v_lshl_add_u64 v[196:197], v[224:225], 0, s[12:13]
	s_mov_b32 m0, s45
	s_nop 0
	global_load_lds_dwordx4 v[196:197], off
	s_waitcnt vmcnt(8)
	s_waitcnt lgkmcnt(0)
	s_barrier
	s_waitcnt lgkmcnt(0)
	v_mfma_f32_16x16x32_bf16 v[62:65], v[152:155], v[184:187], v[62:65]
	v_mfma_f32_16x16x32_bf16 v[58:61], v[160:163], v[184:187], v[58:61]
	v_mfma_f32_16x16x32_bf16 v[54:57], v[152:155], v[192:195], v[54:57]
	v_mfma_f32_16x16x32_bf16 v[50:53], v[160:163], v[192:195], v[50:53]
	v_mfma_f32_16x16x32_bf16 v[38:41], v[152:155], v[204:207], v[38:41]
	v_mfma_f32_16x16x32_bf16 v[34:37], v[160:163], v[204:207], v[34:37]
	v_mfma_f32_16x16x32_bf16 v[22:25], v[152:155], v[212:215], v[22:25]
	v_mfma_f32_16x16x32_bf16 v[18:21], v[160:163], v[212:215], v[18:21]
	v_mfma_f32_16x16x32_bf16 v[62:65], v[156:159], v[188:191], v[62:65]
	v_mfma_f32_16x16x32_bf16 v[58:61], v[164:167], v[188:191], v[58:61]
	v_mfma_f32_16x16x32_bf16 v[54:57], v[156:159], v[200:203], v[54:57]
	v_mfma_f32_16x16x32_bf16 v[50:53], v[164:167], v[200:203], v[50:53]
	v_mfma_f32_16x16x32_bf16 v[38:41], v[156:159], v[208:211], v[38:41]
	v_mfma_f32_16x16x32_bf16 v[34:37], v[164:167], v[208:211], v[34:37]
	v_mfma_f32_16x16x32_bf16 v[22:25], v[156:159], v[216:219], v[22:25]
	v_mfma_f32_16x16x32_bf16 v[18:21], v[164:167], v[216:219], v[18:21]
	v_mfma_f32_16x16x32_bf16 v[46:49], v[168:171], v[184:187], v[46:49]
	v_mfma_f32_16x16x32_bf16 v[42:45], v[176:179], v[184:187], v[42:45]
	v_mfma_f32_16x16x32_bf16 v[30:33], v[168:171], v[192:195], v[30:33]
	v_mfma_f32_16x16x32_bf16 v[26:29], v[176:179], v[192:195], v[26:29]
	v_mfma_f32_16x16x32_bf16 v[14:17], v[168:171], v[204:207], v[14:17]
	v_mfma_f32_16x16x32_bf16 v[10:13], v[176:179], v[204:207], v[10:13]
	v_mfma_f32_16x16x32_bf16 v[6:9], v[168:171], v[212:215], v[6:9]
	v_mfma_f32_16x16x32_bf16 v[2:5], v[176:179], v[212:215], v[2:5]
	v_mfma_f32_16x16x32_bf16 v[46:49], v[172:175], v[188:191], v[46:49]
	v_mfma_f32_16x16x32_bf16 v[42:45], v[180:183], v[188:191], v[42:45]
	v_mfma_f32_16x16x32_bf16 v[30:33], v[172:175], v[200:203], v[30:33]
	v_mfma_f32_16x16x32_bf16 v[26:29], v[180:183], v[200:203], v[26:29]
	v_mfma_f32_16x16x32_bf16 v[14:17], v[172:175], v[208:211], v[14:17]
	v_mfma_f32_16x16x32_bf16 v[10:13], v[180:183], v[208:211], v[10:13]
	v_mfma_f32_16x16x32_bf16 v[6:9], v[172:175], v[216:219], v[6:9]
	v_mfma_f32_16x16x32_bf16 v[2:5], v[180:183], v[216:219], v[2:5]
	s_barrier
	s_add_i32 s64, s64, 2
	s_add_u32 s55, s55, 0x100
	s_addc_u32 s57, s57, 0
	s_cmp_gt_u32 s64, 5
	s_mov_b64 s[24:25], s[4:5]
	s_cbranch_scc0 .LBB0_3148
	s_and_b64 vcc, exec, s[14:15]
	s_cbranch_vccz .LBB0_3151
	s_barrier

.LBB0_3155:
	s_cmp_lt_i32 s59, 22
	s_waitcnt vmcnt(0)
	s_barrier
	s_cbranch_scc1 .LBB0_3209
	s_waitcnt vmcnt(0)
	s_setprio 0
	s_barrier
	s_and_saveexec_b64 s[2:3], s[0:1]
	s_cbranch_execz .LBB0_3208
	s_waitcnt vmcnt(0) lgkmcnt(0)
	v_mov_b32_e32 v241, 0
	v_lshlrev_b32_e64 v254, 8, s31
	v_mov_b32_e32 v247, 1
	v_mov_b32_e32 v246, 0x3600
	global_atomic_add v248, v246, v247, s[60:61] sc0

.Lprio19:
.LBB0_3271:
	s_cmp_gt_i32 s58, 22
	s_cselect_b64 s[2:3], -1, 0
	s_cmp_lt_i32 s59, 23
	s_cselect_b64 s[4:5], -1, 0
	s_or_b64 s[2:3], s[2:3], s[4:5]
	s_and_b64 vcc, exec, s[2:3]
	s_cbranch_vccnz .LBB0_3395
	s_waitcnt vmcnt(0)
	v_mov_b32_e32 v2, 0
	ds_read_b64 v[8:9], v2 offset:416
	ds_read_b128 v[4:7], v2 offset:192
	v_lshlrev_b32_e32 v1, 4, v0
	v_and_b32_e32 v3, 32, v0
	v_bitop3_b32 v3, v1, v3, 48 bitop3:0x6c
	s_waitcnt lgkmcnt(1)
	v_readfirstlane_b32 s8, v8
	v_readfirstlane_b32 s9, v9
	s_add_u32 s47, s8, 0x13c8000
	s_addc_u32 s48, s9, 0
	s_add_u32 s49, s8, 0x3128000
	s_waitcnt lgkmcnt(0)
	v_readfirstlane_b32 s6, v4
	s_addc_u32 s50, s9, 0
	v_readfirstlane_b32 s7, v5
	s_add_u32 s10, s6, 0x10800
	s_addc_u32 s11, s7, 0
	v_readfirstlane_b32 s2, v6
	v_readfirstlane_b32 s3, v7
	s_add_u32 s12, s2, 0x5800
	s_addc_u32 s13, s3, 0
	v_or_b32_e32 v9, 0x2000, v1
	s_add_u32 s14, s8, 0x8b28000
	v_bfe_u32 v8, v0, 2, 4
	v_lshrrev_b32_e32 v1, 7, v9
	s_movk_i32 s3, 0x70
	s_addc_u32 s15, s9, 0
	v_and_or_b32 v1, v1, s3, v8
	s_cmpk_lg_i32 s56, 0x100
	v_and_b32_e32 v10, 64, v0
	v_lshlrev_b32_e32 v1, 11, v1
	s_cselect_b64 s[4:5], -1, 0
	s_lshr_b32 s2, s33, 8
	v_or3_b32 v136, v10, v1, v3
	v_and_b32_e32 v5, 15, v0
	v_and_b32_e32 v1, 48, v0
	v_lshlrev_b32_e32 v7, 2, v0
	s_lshl_b32 s16, s2, 13
	v_lshl_or_b32 v1, v5, 6, v1
	v_and_b32_e32 v7, 32, v7
	v_bitop3_b32 v12, v1, s16, v7 bitop3:0xde
	s_lshl_b32 s16, s68, 5
	s_and_b32 s20, s16, 0x60
	s_lshl_b32 s52, s68, 10
	s_lshl_b32 s3, s2, 6
	s_lshl_b32 s16, s20, 7
	s_cmp_eq_u32 s2, 1
	v_bitop3_b32 v1, s16, v1, v7 bitop3:0xf6
	s_cselect_b64 s[16:17], -1, 0
	s_cmpk_lt_u32 s33, 0x100
	v_or_b32_e32 v6, s3, v5
	s_cselect_b64 s[18:19], -1, 0
	s_addk_i32 s3, 0x80
	s_lshl_b32 s28, s20, 1
	v_lshrrev_b32_e32 v4, 3, v0
	s_add_u32 s20, s6, 0x16000
	v_and_or_b32 v4, v4, 48, v8
	s_addc_u32 s21, s7, 0
	v_lshlrev_b32_e32 v4, 11, v4
	v_lshrrev_b32_e32 v11, 1, v0
	s_add_u32 s22, s6, 0x1b800
	v_lshlrev_b32_e32 v9, 4, v9
	s_mov_b32 s6, 0x38000
	v_or3_b32 v134, v10, v4, v3
	v_and_b32_e32 v4, 24, v11
	v_and_b32_e32 v153, 0xf8, v11
	v_and_or_b32 v9, v9, s6, v3
	v_lshlrev_b32_e32 v11, 11, v8
	v_add_u32_e32 v4, 0, v4
	v_or_b32_e32 v5, s3, v5
	s_movk_i32 s24, 0x210
	v_or3_b32 v8, v9, v11, v10
	v_mov_b32_e32 v9, v2
	v_mad_u64_u32 v[6:7], s[2:3], v6, s24, v[4:5]
	s_addc_u32 s23, s7, 0
	v_mad_u64_u32 v[4:5], s[2:3], v5, s24, v[4:5]
	v_lshl_add_u64 v[8:9], s[8:9], 0, v[8:9]
	s_mov_b64 s[6:7], 0x3168080
	v_lshlrev_b32_e32 v13, 3, v0
	v_mad_u32_u24 v5, v153, s24, 0
	v_lshl_add_u64 v[138:139], v[8:9], 0, s[6:7]
	v_lshlrev_b32_e32 v8, 8, v0
	s_mov_b32 s24, 0x18000
	v_and_b32_e32 v152, 0x78, v13
	v_and_or_b32 v3, v8, s24, v3
	v_lshlrev_b32_e32 v7, 1, v152
	v_or3_b32 v8, v3, v11, v10
	v_mul_u32_u24_e32 v3, 0x1080, v199
	s_ashr_i32 s53, s56, 31
	s_ashr_i32 s54, s30, 31
	s_add_i32 s55, s30, 0xfffffe06
	v_mov_b32_e32 v9, v2
	v_add3_u32 v3, v3, v7, 0
	s_add_u32 s57, s8, 0x13c8100
	v_lshl_add_u64 v[8:9], s[8:9], 0, v[8:9]
	v_add_u32_e32 v154, 0x610, v3
	v_cndmask_b32_e64 v3, 0, 1, s[4:5]
	s_mov_b32 s46, 0
	s_movk_i32 s51, 0x2000
	v_mov_b32_e32 v135, v2
	v_mov_b32_e32 v137, v2
	v_cmp_ne_u32_e64 s[2:3], 0, v153
	s_addc_u32 s64, s9, 0
	v_lshl_add_u64 v[140:141], v[8:9], 0, s[6:7]
	s_movk_i32 s65, 0x2fa
	s_mov_b64 s[24:25], 0x80
	v_add_u32_e32 v155, 0, v12
	s_movk_i32 s66, 0xff
	v_add_u32_e32 v156, s28, v6
	s_mov_b64 s[26:27], 0x2c00
	v_add_u32_e32 v157, s28, v4
	s_movk_i32 s67, 0x1600
	v_cmp_ne_u32_e64 s[4:5], 1, v3
	v_mov_b64_e32 v[142:143], 0x23c
	v_mov_b64_e32 v[144:145], 0x23b
	v_mov_b64_e32 v[146:147], 0x1f9
	v_mov_b64_e32 v[148:149], 0x1fa
	v_add_u32_e32 v158, v5, v7
	s_branch .LBB0_3275

.LBB0_3305:
	s_add_u32 s42, s77, s40
	s_addc_u32 s43, s78, s41
	s_add_u32 s42, s42, 0x3128100
	s_addc_u32 s43, s43, 0
	s_add_u32 s80, s75, s40
	s_addc_u32 s81, s76, s41
	s_add_i32 s82, 0, 0x10400
	s_cmpk_eq_i32 s40, 0x700
	s_cselect_b32 s45, s39, s43
	s_cselect_b32 s44, s38, s42
	v_add_u32_e32 v3, s82, v1
	s_cselect_b32 s43, s37, s81
	s_cselect_b32 s42, s36, s80
	s_add_i32 s83, 0, 0x14400
	ds_read_b128 v[160:163], v3
	ds_read_b128 v[164:167], v3 offset:1024
	ds_read_b128 v[168:171], v3 offset:2048
	ds_read_b128 v[172:175], v3 offset:3072
	v_add_u32_e32 v3, s83, v1
	ds_read_b128 v[176:179], v3
	ds_read_b128 v[180:183], v3 offset:1024
	ds_read_b128 v[184:187], v3 offset:2048
	ds_read_b128 v[188:191], v3 offset:3072
	v_lshl_add_u64 v[196:197], v[150:151], 0, s[40:41]
	s_add_i32 m0, s7, 0xc400
	ds_read_b128 v[192:195], v155 offset:1024
	ds_read_b128 v[200:203], v155 offset:2048
	ds_read_b128 v[204:207], v155 offset:3072
	ds_read_b128 v[208:211], v155 offset:4096
	ds_read_b128 v[212:215], v155 offset:5120
	ds_read_b128 v[216:219], v155 offset:6144
	ds_read_b128 v[220:223], v155 offset:7168
	ds_read_b128 v[224:227], v155 offset:8192
	global_load_lds_dwordx4 v[196:197], off
	v_lshl_add_u64 v[196:197], v[68:69], 0, s[40:41]
	s_add_i32 m0, s7, 0xe400
	s_nop 0
	global_load_lds_dwordx4 v[196:197], off
	s_waitcnt vmcnt(8)
	s_waitcnt lgkmcnt(0)
	s_barrier
	s_waitcnt lgkmcnt(0)
	v_mfma_f32_16x16x32_bf16 v[36:39], v[160:163], v[192:195], v[36:39]
	v_mfma_f32_16x16x32_bf16 v[40:43], v[168:171], v[192:195], v[40:43]
	v_mfma_f32_16x16x32_bf16 v[20:23], v[160:163], v[204:207], v[20:23]
	v_mfma_f32_16x16x32_bf16 v[24:27], v[168:171], v[204:207], v[24:27]
	v_mfma_f32_16x16x32_bf16 v[12:15], v[160:163], v[212:215], v[12:15]
	v_mfma_f32_16x16x32_bf16 v[16:19], v[168:171], v[212:215], v[16:19]
	v_mfma_f32_16x16x32_bf16 v[4:7], v[160:163], v[220:223], v[4:7]
	v_mfma_f32_16x16x32_bf16 v[8:11], v[168:171], v[220:223], v[8:11]
	v_mfma_f32_16x16x32_bf16 v[36:39], v[164:167], v[200:203], v[36:39]
	v_mfma_f32_16x16x32_bf16 v[40:43], v[172:175], v[200:203], v[40:43]
	v_mfma_f32_16x16x32_bf16 v[20:23], v[164:167], v[208:211], v[20:23]
	v_mfma_f32_16x16x32_bf16 v[24:27], v[172:175], v[208:211], v[24:27]
	v_mfma_f32_16x16x32_bf16 v[12:15], v[164:167], v[216:219], v[12:15]
	v_mfma_f32_16x16x32_bf16 v[16:19], v[172:175], v[216:219], v[16:19]
	v_mfma_f32_16x16x32_bf16 v[4:7], v[164:167], v[224:227], v[4:7]
	v_mfma_f32_16x16x32_bf16 v[8:11], v[172:175], v[224:227], v[8:11]
	v_mfma_f32_16x16x32_bf16 v[60:63], v[176:179], v[192:195], v[60:63]
	v_mfma_f32_16x16x32_bf16 v[64:67], v[184:187], v[192:195], v[64:67]
	v_mfma_f32_16x16x32_bf16 v[52:55], v[176:179], v[204:207], v[52:55]
	v_mfma_f32_16x16x32_bf16 v[56:59], v[184:187], v[204:207], v[56:59]
	v_mfma_f32_16x16x32_bf16 v[44:47], v[176:179], v[212:215], v[44:47]
	v_mfma_f32_16x16x32_bf16 v[48:51], v[184:187], v[212:215], v[48:51]
	v_mfma_f32_16x16x32_bf16 v[28:31], v[176:179], v[220:223], v[28:31]
	v_mfma_f32_16x16x32_bf16 v[32:35], v[184:187], v[220:223], v[32:35]
	v_mfma_f32_16x16x32_bf16 v[60:63], v[180:183], v[200:203], v[60:63]
	v_mfma_f32_16x16x32_bf16 v[64:67], v[188:191], v[200:203], v[64:67]
	v_mfma_f32_16x16x32_bf16 v[52:55], v[180:183], v[208:211], v[52:55]
	v_mfma_f32_16x16x32_bf16 v[56:59], v[188:191], v[208:211], v[56:59]
	v_mfma_f32_16x16x32_bf16 v[44:47], v[180:183], v[216:219], v[44:47]
	v_mfma_f32_16x16x32_bf16 v[48:51], v[188:191], v[216:219], v[48:51]
	v_mfma_f32_16x16x32_bf16 v[28:31], v[180:183], v[224:227], v[28:31]
	v_mfma_f32_16x16x32_bf16 v[32:35], v[188:191], v[224:227], v[32:35]
	s_barrier
	s_add_i32 s80, s82, s52
	v_lshl_add_u64 v[196:197], s[42:43], 0, v[134:135]
	s_mov_b32 m0, s80
	ds_read_b128 v[192:195], v155 offset:17408
	ds_read_b128 v[200:203], v155 offset:18432
	ds_read_b128 v[204:207], v155 offset:19456
	ds_read_b128 v[208:211], v155 offset:20480
	ds_read_b128 v[212:215], v155 offset:21504
	ds_read_b128 v[216:219], v155 offset:22528
	ds_read_b128 v[220:223], v155 offset:23552
	ds_read_b128 v[224:227], v155 offset:24576
	global_load_lds_dwordx4 v[196:197], off
	s_add_i32 m0, s80, 0x2000
	s_add_u32 s80, s42, 0x40000
	v_lshl_add_u64 v[228:229], s[42:43], 0, v[136:137]
	s_addc_u32 s81, s43, 0
	s_add_i32 s82, s83, s52
	global_load_lds_dwordx4 v[228:229], off
	v_lshl_add_u64 v[230:231], s[80:81], 0, v[134:135]
	s_mov_b32 m0, s82
	v_lshl_add_u64 v[232:233], s[44:45], 0, v[136:137]
	global_load_lds_dwordx4 v[230:231], off
	v_lshl_add_u64 v[230:231], s[80:81], 0, v[136:137]
	s_add_i32 m0, s82, 0x2000
	s_nop 0
	global_load_lds_dwordx4 v[230:231], off
	v_lshl_add_u64 v[230:231], s[44:45], 0, v[134:135]
	s_mov_b32 m0, s29
	s_nop 0
	global_load_lds_dwordx4 v[230:231], off
	s_mov_b32 m0, s70
	s_nop 0
	global_load_lds_dwordx4 v[232:233], off
	s_waitcnt vmcnt(8)
	s_waitcnt lgkmcnt(0)
	s_barrier
	s_waitcnt lgkmcnt(0)
	v_mfma_f32_16x16x32_bf16 v[102:105], v[160:163], v[192:195], v[102:105]
	v_mfma_f32_16x16x32_bf16 v[106:109], v[168:171], v[192:195], v[106:109]
	v_mfma_f32_16x16x32_bf16 v[86:89], v[160:163], v[204:207], v[86:89]
	v_mfma_f32_16x16x32_bf16 v[90:93], v[168:171], v[204:207], v[90:93]
	v_mfma_f32_16x16x32_bf16 v[78:81], v[160:163], v[212:215], v[78:81]
	v_mfma_f32_16x16x32_bf16 v[82:85], v[168:171], v[212:215], v[82:85]
	v_mfma_f32_16x16x32_bf16 v[70:73], v[160:163], v[220:223], v[70:73]
	v_mfma_f32_16x16x32_bf16 v[74:77], v[168:171], v[220:223], v[74:77]
	v_mfma_f32_16x16x32_bf16 v[102:105], v[164:167], v[200:203], v[102:105]
	v_mfma_f32_16x16x32_bf16 v[106:109], v[172:175], v[200:203], v[106:109]
	v_mfma_f32_16x16x32_bf16 v[86:89], v[164:167], v[208:211], v[86:89]
	v_mfma_f32_16x16x32_bf16 v[90:93], v[172:175], v[208:211], v[90:93]
	v_mfma_f32_16x16x32_bf16 v[78:81], v[164:167], v[216:219], v[78:81]
	v_mfma_f32_16x16x32_bf16 v[82:85], v[172:175], v[216:219], v[82:85]
	v_mfma_f32_16x16x32_bf16 v[70:73], v[164:167], v[224:227], v[70:73]
	v_mfma_f32_16x16x32_bf16 v[74:77], v[172:175], v[224:227], v[74:77]
	v_mfma_f32_16x16x32_bf16 v[126:129], v[176:179], v[192:195], v[126:129]
	v_mfma_f32_16x16x32_bf16 v[130:133], v[184:187], v[192:195], v[130:133]
	v_mfma_f32_16x16x32_bf16 v[118:121], v[176:179], v[204:207], v[118:121]
	v_mfma_f32_16x16x32_bf16 v[122:125], v[184:187], v[204:207], v[122:125]
	v_mfma_f32_16x16x32_bf16 v[110:113], v[176:179], v[212:215], v[110:113]
	v_mfma_f32_16x16x32_bf16 v[114:117], v[184:187], v[212:215], v[114:117]
	v_mfma_f32_16x16x32_bf16 v[94:97], v[176:179], v[220:223], v[94:97]
	v_mfma_f32_16x16x32_bf16 v[98:101], v[184:187], v[220:223], v[98:101]
	v_mfma_f32_16x16x32_bf16 v[126:129], v[180:183], v[200:203], v[126:129]
	v_mfma_f32_16x16x32_bf16 v[130:133], v[188:191], v[200:203], v[130:133]
	v_mfma_f32_16x16x32_bf16 v[118:121], v[180:183], v[208:211], v[118:121]
	v_mfma_f32_16x16x32_bf16 v[122:125], v[188:191], v[208:211], v[122:125]
	v_mfma_f32_16x16x32_bf16 v[110:113], v[180:183], v[216:219], v[110:113]
	v_mfma_f32_16x16x32_bf16 v[114:117], v[188:191], v[216:219], v[114:117]
	v_mfma_f32_16x16x32_bf16 v[94:97], v[180:183], v[224:227], v[94:97]
	v_mfma_f32_16x16x32_bf16 v[98:101], v[188:191], v[224:227], v[98:101]
	s_barrier
	s_add_i32 s80, 0, 0x18400
	v_add_u32_e32 v3, s80, v1
	s_add_i32 s81, 0, 0x1c400
	ds_read_b128 v[160:163], v3
	ds_read_b128 v[164:167], v3 offset:1024
	ds_read_b128 v[168:171], v3 offset:2048
	ds_read_b128 v[172:175], v3 offset:3072
	v_add_u32_e32 v3, s81, v1
	ds_read_b128 v[176:179], v3
	ds_read_b128 v[180:183], v3 offset:1024
	ds_read_b128 v[184:187], v3 offset:2048
	ds_read_b128 v[188:191], v3 offset:3072
	s_add_u32 s44, s44, 0x40000
	s_addc_u32 s45, s45, 0
	s_mov_b32 m0, s71
	v_lshl_add_u64 v[234:235], s[44:45], 0, v[134:135]
	ds_read_b128 v[192:195], v155 offset:33792
	ds_read_b128 v[200:203], v155 offset:34816
	ds_read_b128 v[204:207], v155 offset:35840
	ds_read_b128 v[208:211], v155 offset:36864
	ds_read_b128 v[212:215], v155 offset:37888
	ds_read_b128 v[216:219], v155 offset:38912
	ds_read_b128 v[220:223], v155 offset:39936
	ds_read_b128 v[224:227], v155 offset:40960
	global_load_lds_dwordx4 v[234:235], off
	v_lshl_add_u64 v[234:235], s[44:45], 0, v[136:137]
	s_mov_b32 m0, s72
	s_nop 0
	global_load_lds_dwordx4 v[234:235], off
	s_waitcnt vmcnt(8)
	s_waitcnt lgkmcnt(0)
	s_barrier
	s_waitcnt lgkmcnt(0)
	v_mfma_f32_16x16x32_bf16 v[36:39], v[160:163], v[192:195], v[36:39]
	v_mfma_f32_16x16x32_bf16 v[40:43], v[168:171], v[192:195], v[40:43]
	v_mfma_f32_16x16x32_bf16 v[20:23], v[160:163], v[204:207], v[20:23]
	v_mfma_f32_16x16x32_bf16 v[24:27], v[168:171], v[204:207], v[24:27]
	v_mfma_f32_16x16x32_bf16 v[12:15], v[160:163], v[212:215], v[12:15]
	v_mfma_f32_16x16x32_bf16 v[16:19], v[168:171], v[212:215], v[16:19]
	v_mfma_f32_16x16x32_bf16 v[4:7], v[160:163], v[220:223], v[4:7]
	v_mfma_f32_16x16x32_bf16 v[8:11], v[168:171], v[220:223], v[8:11]
	v_mfma_f32_16x16x32_bf16 v[36:39], v[164:167], v[200:203], v[36:39]
	v_mfma_f32_16x16x32_bf16 v[40:43], v[172:175], v[200:203], v[40:43]
	v_mfma_f32_16x16x32_bf16 v[20:23], v[164:167], v[208:211], v[20:23]
	v_mfma_f32_16x16x32_bf16 v[24:27], v[172:175], v[208:211], v[24:27]
	v_mfma_f32_16x16x32_bf16 v[12:15], v[164:167], v[216:219], v[12:15]
	v_mfma_f32_16x16x32_bf16 v[16:19], v[172:175], v[216:219], v[16:19]
	v_mfma_f32_16x16x32_bf16 v[4:7], v[164:167], v[224:227], v[4:7]
	v_mfma_f32_16x16x32_bf16 v[8:11], v[172:175], v[224:227], v[8:11]
	v_mfma_f32_16x16x32_bf16 v[60:63], v[176:179], v[192:195], v[60:63]
	v_mfma_f32_16x16x32_bf16 v[64:67], v[184:187], v[192:195], v[64:67]
	v_mfma_f32_16x16x32_bf16 v[52:55], v[176:179], v[204:207], v[52:55]
	v_mfma_f32_16x16x32_bf16 v[56:59], v[184:187], v[204:207], v[56:59]
	v_mfma_f32_16x16x32_bf16 v[44:47], v[176:179], v[212:215], v[44:47]
	v_mfma_f32_16x16x32_bf16 v[48:51], v[184:187], v[212:215], v[48:51]
	v_mfma_f32_16x16x32_bf16 v[28:31], v[176:179], v[220:223], v[28:31]
	v_mfma_f32_16x16x32_bf16 v[32:35], v[184:187], v[220:223], v[32:35]
	v_mfma_f32_16x16x32_bf16 v[60:63], v[180:183], v[200:203], v[60:63]
	v_mfma_f32_16x16x32_bf16 v[64:67], v[188:191], v[200:203], v[64:67]
	v_mfma_f32_16x16x32_bf16 v[52:55], v[180:183], v[208:211], v[52:55]
	v_mfma_f32_16x16x32_bf16 v[56:59], v[188:191], v[208:211], v[56:59]
	v_mfma_f32_16x16x32_bf16 v[44:47], v[180:183], v[216:219], v[44:47]
	v_mfma_f32_16x16x32_bf16 v[48:51], v[188:191], v[216:219], v[48:51]
	v_mfma_f32_16x16x32_bf16 v[28:31], v[180:183], v[224:227], v[28:31]
	v_mfma_f32_16x16x32_bf16 v[32:35], v[188:191], v[224:227], v[32:35]
	s_barrier
	s_add_i32 s44, s80, s52
	v_lshl_add_u64 v[196:197], v[196:197], 0, s[24:25]
	s_mov_b32 m0, s44
	ds_read_b128 v[192:195], v155 offset:50176
	ds_read_b128 v[200:203], v155 offset:51200
	ds_read_b128 v[204:207], v155 offset:52224
	ds_read_b128 v[208:211], v155 offset:53248
	ds_read_b128 v[212:215], v155 offset:54272
	ds_read_b128 v[216:219], v155 offset:55296
	ds_read_b128 v[220:223], v155 offset:56320
	ds_read_b128 v[224:227], v155 offset:57344
	global_load_lds_dwordx4 v[196:197], off
	s_add_i32 m0, s44, 0x2000
	s_add_u32 s42, s42, 0x40080
	v_lshl_add_u64 v[196:197], v[228:229], 0, s[24:25]
	s_addc_u32 s43, s43, 0
	s_add_i32 s44, s81, s52
	global_load_lds_dwordx4 v[196:197], off
	v_lshl_add_u64 v[196:197], s[42:43], 0, v[134:135]
	s_mov_b32 m0, s44
	s_nop 0
	global_load_lds_dwordx4 v[196:197], off
	v_lshl_add_u64 v[196:197], s[42:43], 0, v[136:137]
	s_add_i32 m0, s44, 0x2000
	s_nop 0
	global_load_lds_dwordx4 v[196:197], off
	v_lshl_add_u64 v[196:197], v[230:231], 0, s[24:25]
	s_mov_b32 m0, s73
	s_nop 0
	global_load_lds_dwordx4 v[196:197], off
	v_lshl_add_u64 v[196:197], v[232:233], 0, s[24:25]
	s_mov_b32 m0, s74
	s_nop 0
	global_load_lds_dwordx4 v[196:197], off
	s_waitcnt vmcnt(8)
	s_waitcnt lgkmcnt(0)
	s_barrier
	s_waitcnt lgkmcnt(0)
	v_mfma_f32_16x16x32_bf16 v[102:105], v[160:163], v[192:195], v[102:105]
	v_mfma_f32_16x16x32_bf16 v[106:109], v[168:171], v[192:195], v[106:109]
	v_mfma_f32_16x16x32_bf16 v[86:89], v[160:163], v[204:207], v[86:89]
	v_mfma_f32_16x16x32_bf16 v[90:93], v[168:171], v[204:207], v[90:93]
	v_mfma_f32_16x16x32_bf16 v[78:81], v[160:163], v[212:215], v[78:81]
	v_mfma_f32_16x16x32_bf16 v[82:85], v[168:171], v[212:215], v[82:85]
	v_mfma_f32_16x16x32_bf16 v[70:73], v[160:163], v[220:223], v[70:73]
	v_mfma_f32_16x16x32_bf16 v[74:77], v[168:171], v[220:223], v[74:77]
	v_mfma_f32_16x16x32_bf16 v[102:105], v[164:167], v[200:203], v[102:105]
	v_mfma_f32_16x16x32_bf16 v[106:109], v[172:175], v[200:203], v[106:109]
	v_mfma_f32_16x16x32_bf16 v[86:89], v[164:167], v[208:211], v[86:89]
	v_mfma_f32_16x16x32_bf16 v[90:93], v[172:175], v[208:211], v[90:93]
	v_mfma_f32_16x16x32_bf16 v[78:81], v[164:167], v[216:219], v[78:81]
	v_mfma_f32_16x16x32_bf16 v[82:85], v[172:175], v[216:219], v[82:85]
	v_mfma_f32_16x16x32_bf16 v[70:73], v[164:167], v[224:227], v[70:73]
	v_mfma_f32_16x16x32_bf16 v[74:77], v[172:175], v[224:227], v[74:77]
	v_mfma_f32_16x16x32_bf16 v[126:129], v[176:179], v[192:195], v[126:129]
	v_mfma_f32_16x16x32_bf16 v[130:133], v[184:187], v[192:195], v[130:133]
	v_mfma_f32_16x16x32_bf16 v[118:121], v[176:179], v[204:207], v[118:121]
	v_mfma_f32_16x16x32_bf16 v[122:125], v[184:187], v[204:207], v[122:125]
	v_mfma_f32_16x16x32_bf16 v[110:113], v[176:179], v[212:215], v[110:113]
	v_mfma_f32_16x16x32_bf16 v[114:117], v[184:187], v[212:215], v[114:117]
	v_mfma_f32_16x16x32_bf16 v[94:97], v[176:179], v[220:223], v[94:97]
	v_mfma_f32_16x16x32_bf16 v[98:101], v[184:187], v[220:223], v[98:101]
	v_mfma_f32_16x16x32_bf16 v[126:129], v[180:183], v[200:203], v[126:129]
	v_mfma_f32_16x16x32_bf16 v[130:133], v[188:191], v[200:203], v[130:133]
	v_mfma_f32_16x16x32_bf16 v[118:121], v[180:183], v[208:211], v[118:121]
	v_mfma_f32_16x16x32_bf16 v[122:125], v[188:191], v[208:211], v[122:125]
	v_mfma_f32_16x16x32_bf16 v[110:113], v[180:183], v[216:219], v[110:113]
	v_mfma_f32_16x16x32_bf16 v[114:117], v[188:191], v[216:219], v[114:117]
	v_mfma_f32_16x16x32_bf16 v[94:97], v[180:183], v[224:227], v[94:97]
	v_mfma_f32_16x16x32_bf16 v[98:101], v[188:191], v[224:227], v[98:101]
	s_barrier
	s_add_i32 s79, s79, 2
	s_add_u32 s40, s40, 0x100
	s_addc_u32 s41, s41, 0
	s_cmp_gt_u32 s79, 13
	s_cbranch_scc0 .LBB0_3305
	s_and_b64 vcc, exec, s[18:19]
	s_cbranch_vccz .LBB0_3308
	s_barrier

.LBB0_3341:
	s_cmp_lt_i32 s59, 24
	s_waitcnt lgkmcnt(0)
	s_barrier
	s_cbranch_scc1 .LBB0_3395
	s_waitcnt vmcnt(0)
	s_setprio 0
	s_barrier
	s_and_saveexec_b64 s[2:3], s[0:1]
	s_cbranch_execz .LBB0_3394
	s_waitcnt vmcnt(0) lgkmcnt(0)
	v_mov_b32_e32 v241, 0
	v_lshlrev_b32_e64 v254, 8, s31
	v_mov_b32_e32 v247, 1
	v_mov_b32_e32 v246, 0x3600
	global_atomic_add v248, v246, v247, s[60:61] sc0

.Lprio20:
.LBB0_3395:
	s_cmp_gt_i32 s58, 24
	s_cselect_b64 s[2:3], -1, 0
	s_cmp_lt_i32 s59, 25
	s_cselect_b64 s[4:5], -1, 0
	s_or_b64 s[2:3], s[2:3], s[4:5]
	s_and_b64 vcc, exec, s[2:3]
	s_cbranch_vccnz .LBB0_3571
	v_mov_b32_e32 v1, 0
	s_waitcnt vmcnt(0)
	ds_read_b64 v[2:3], v1 offset:416
	s_mov_b64 s[2:3], -1
	s_waitcnt lgkmcnt(0)
	v_readfirstlane_b32 s6, v2
	v_readfirstlane_b32 s7, v3
	s_add_u32 s12, s6, 0x8b28000
	s_addc_u32 s13, s7, 0
	s_add_u32 s34, s6, 0x2448000
	s_addc_u32 s35, s7, 0
	s_cmpk_lg_i32 s56, 0x100
	s_cbranch_scc0 .LBB0_3418
	s_cmpk_gt_i32 s30, 0xbf
	s_cbranch_scc1 .LBB0_3417
	v_bfe_u32 v4, v0, 3, 25
	s_movk_i32 s3, 0x60
	v_bfe_u32 v3, v0, 2, 4
	v_bitop3_b32 v5, v4, s3, 64 bitop3:0xc8
	v_or_b32_e32 v4, 64, v4
	s_movk_i32 s3, 0x70
	v_and_or_b32 v4, v4, s3, v3
	v_lshrrev_b32_e32 v8, 5, v0
	s_movk_i32 s3, 0x64
	s_ashr_i32 s37, s30, 31
	v_bitop3_b32 v5, v5, s3, v8 bitop3:0xc8
	s_lshr_b32 s3, s37, 29
	s_add_i32 s3, s30, s3
	s_ashr_i32 s4, s3, 3
	s_and_b32 s3, s3, -8
	s_lshr_b32 s2, s33, 8
	s_lshl_b32 s36, s68, 10
	s_sub_i32 s3, s30, s3
	s_cmp_lt_i32 s3, 0
	s_cselect_b32 s5, 25, 24
	s_mul_i32 s3, s5, s3
	s_add_i32 s3, s3, s4
	s_ashr_i32 s4, s3, 31
	s_lshr_b32 s4, s4, 26
	s_add_i32 s4, s3, s4
	s_ashr_i32 s5, s4, 6
	s_and_b32 s4, s4, 0xffc0
	s_sub_i32 s3, s3, s4
	s_bfe_i32 s4, s3, 0x80000
	s_lshr_b32 s4, s4, 7
	s_bfe_u32 s8, s4, 0x30005
	s_add_i32 s8, s3, s8
	s_and_b32 s10, s8, 0xf8
	s_bfe_u32 s4, s4, 0x40004
	s_sub_i32 s10, s3, s10
	s_add_i32 s3, s3, s4
	s_bfe_i32 s9, s8, 0x80000
	s_bfe_i32 s3, s3, 0x80000
	s_sext_i32_i16 s9, s9
	s_sext_i32_i16 s3, s3
	v_lshlrev_b32_e32 v1, 4, v0
	v_and_b32_e32 v2, 32, v0
	v_lshrrev_b32_e32 v11, 1, v0
	s_ashr_i32 s9, s9, 3
	s_ashr_i32 s50, s3, 4
	s_bfe_u32 s3, s8, 0x10007
	v_bfe_u32 v6, v0, 2, 2
	v_and_b32_e32 v7, 24, v11
	v_bitop3_b32 v1, v1, v2, 48 bitop3:0x6c
	s_add_i32 s3, s9, s3
	v_or3_b32 v5, v5, v6, v7
	v_and_b32_e32 v10, 32, v11
	v_lshrrev_b32_e32 v12, 1, v1
	s_and_b32 s3, s3, 0xfffe
	v_mul_u32_u24_e32 v5, 0xb00, v5
	v_or_b32_e32 v1, v10, v12
	s_sub_i32 s3, s9, s3
	v_or_b32_e32 v2, v5, v1
	v_mul_u32_u24_e32 v13, 0xb00, v4
	s_sext_i32_i16 s51, s3
	v_lshlrev_b32_e32 v130, 1, v2
	v_or_b32_e32 v2, v13, v1
	s_lshl_b32 s5, s5, 3
	s_sext_i32_i8 s10, s10
	s_mul_i32 s4, s51, 0x580
	v_lshlrev_b32_e32 v132, 1, v2
	v_lshrrev_b32_e32 v2, 3, v0
	s_add_i32 s49, s5, s10
	s_ashr_i32 s5, s4, 31
	s_mul_i32 s9, s50, 0x160000
	v_and_b32_e32 v4, 32, v2
	s_lshl_b64 s[4:5], s[4:5], 1
	s_ashr_i32 s10, s9, 31
	v_and_or_b32 v2, v2, 48, v3
	v_bitop3_b32 v3, v4, 36, v8 bitop3:0xc8
	s_add_u32 s9, s34, s9
	v_or3_b32 v3, v3, v6, v7
	s_addc_u32 s10, s35, s10
	v_mul_u32_u24_e32 v3, 0xb00, v3
	s_add_u32 s24, s9, s4
	v_or_b32_e32 v3, v3, v1
	s_addc_u32 s25, s10, s5
	s_add_i32 s38, s36, 0
	v_lshlrev_b32_e32 v134, 1, v3
	s_add_i32 m0, s38, 0x10400
	s_mul_i32 s8, s49, 0x160000
	global_load_lds_dwordx4 v134, s[24:25]
	s_add_i32 m0, s38, 0x12400
	s_mul_hi_i32 s3, s49, 0x160000
	s_add_u32 s10, s12, s8
	s_addc_u32 s3, s13, s3
	s_add_u32 s8, s24, 0xb0000
	global_load_lds_dwordx4 v130, s[24:25]
	s_addc_u32 s9, s25, 0
	s_add_i32 m0, s38, 0x14400
	v_mul_u32_u24_e32 v14, 0xb00, v2
	global_load_lds_dwordx4 v134, s[8:9]
	s_add_i32 m0, s38, 0x16400
	s_add_u32 s22, s10, s4
	v_or_b32_e32 v1, v1, v14
	s_addc_u32 s23, s3, s5
	s_add_i32 s39, s38, 0x400
	s_add_i32 s40, s38, 0x2400
	v_lshlrev_b32_e32 v136, 1, v1
	global_load_lds_dwordx4 v130, s[8:9]
	s_mov_b32 m0, s39
	s_add_u32 s4, s22, 0xb0000
	global_load_lds_dwordx4 v136, s[22:23]
	s_mov_b32 m0, s40
	s_addc_u32 s5, s23, 0
	s_add_i32 s41, s38, 0x4400
	global_load_lds_dwordx4 v132, s[22:23]
	s_mov_b32 m0, s41
	s_add_i32 s42, s38, 0x6400
	global_load_lds_dwordx4 v136, s[4:5]
	s_mov_b32 m0, s42
	v_mov_b32_e32 v135, 0
	global_load_lds_dwordx4 v132, s[4:5]
	v_mov_b32_e32 v131, v135
	v_mov_b32_e32 v137, v135
	v_mov_b32_e32 v133, v135
	s_cmp_eq_u32 s2, 1
	s_mov_b32 s43, 0
	v_lshl_add_u64 v[8:9], s[24:25], 0, v[134:135]
	v_lshl_add_u64 v[6:7], s[24:25], 0, v[130:131]
	v_lshl_add_u64 v[2:3], s[22:23], 0, v[136:137]
	s_cselect_b64 s[14:15], -1, 0
	s_cmp_lg_u32 s2, 1
	v_lshl_add_u64 v[4:5], s[22:23], 0, v[132:133]
	s_cbranch_scc1 .LBB0_3400
	s_barrier

.LBB0_3410:
	ds_read_b128 v[152:155], v148
	ds_read_b128 v[156:159], v148 offset:1024
	ds_read_b128 v[160:163], v148 offset:2048
	ds_read_b128 v[164:167], v148 offset:3072
	ds_read_b128 v[168:171], v149
	ds_read_b128 v[172:175], v149 offset:1024
	ds_read_b128 v[176:179], v149 offset:2048
	ds_read_b128 v[180:183], v149 offset:3072
	s_add_u32 s24, s22, 0x100
	s_addc_u32 s25, s23, 0
	s_cmp_eq_u32 s64, 18
	s_cselect_b32 s29, s5, s25
	s_cselect_b32 s28, s4, s24
	s_cselect_b32 s27, s21, s57
	s_cselect_b32 s26, s20, s55
	v_lshl_add_u64 v[196:197], s[22:23], 0, v[140:141]
	s_add_i32 m0, s38, 0xc400
	ds_read_b128 v[184:187], v150 offset:1024
	ds_read_b128 v[188:191], v150 offset:2048
	ds_read_b128 v[192:195], v150 offset:3072
	ds_read_b128 v[200:203], v150 offset:4096
	ds_read_b128 v[204:207], v150 offset:5120
	ds_read_b128 v[208:211], v150 offset:6144
	ds_read_b128 v[212:215], v150 offset:7168
	ds_read_b128 v[216:219], v150 offset:8192
	global_load_lds_dwordx4 v[196:197], off
	v_lshl_add_u64 v[196:197], s[22:23], 0, v[138:139]
	s_add_i32 m0, s38, 0xe400
	s_nop 0
	global_load_lds_dwordx4 v[196:197], off
	s_waitcnt vmcnt(8)
	s_waitcnt lgkmcnt(0)
	s_barrier
	s_waitcnt lgkmcnt(0)
	v_mfma_f32_16x16x32_bf16 v[126:129], v[152:155], v[184:187], v[126:129]
	v_mfma_f32_16x16x32_bf16 v[122:125], v[160:163], v[184:187], v[122:125]
	v_mfma_f32_16x16x32_bf16 v[118:121], v[152:155], v[192:195], v[118:121]
	v_mfma_f32_16x16x32_bf16 v[114:117], v[160:163], v[192:195], v[114:117]
	v_mfma_f32_16x16x32_bf16 v[102:105], v[152:155], v[204:207], v[102:105]
	v_mfma_f32_16x16x32_bf16 v[98:101], v[160:163], v[204:207], v[98:101]
	v_mfma_f32_16x16x32_bf16 v[86:89], v[152:155], v[212:215], v[86:89]
	v_mfma_f32_16x16x32_bf16 v[82:85], v[160:163], v[212:215], v[82:85]
	v_mfma_f32_16x16x32_bf16 v[126:129], v[156:159], v[188:191], v[126:129]
	v_mfma_f32_16x16x32_bf16 v[122:125], v[164:167], v[188:191], v[122:125]
	v_mfma_f32_16x16x32_bf16 v[118:121], v[156:159], v[200:203], v[118:121]
	v_mfma_f32_16x16x32_bf16 v[114:117], v[164:167], v[200:203], v[114:117]
	v_mfma_f32_16x16x32_bf16 v[102:105], v[156:159], v[208:211], v[102:105]
	v_mfma_f32_16x16x32_bf16 v[98:101], v[164:167], v[208:211], v[98:101]
	v_mfma_f32_16x16x32_bf16 v[86:89], v[156:159], v[216:219], v[86:89]
	v_mfma_f32_16x16x32_bf16 v[82:85], v[164:167], v[216:219], v[82:85]
	v_mfma_f32_16x16x32_bf16 v[110:113], v[168:171], v[184:187], v[110:113]
	v_mfma_f32_16x16x32_bf16 v[106:109], v[176:179], v[184:187], v[106:109]
	v_mfma_f32_16x16x32_bf16 v[94:97], v[168:171], v[192:195], v[94:97]
	v_mfma_f32_16x16x32_bf16 v[90:93], v[176:179], v[192:195], v[90:93]
	v_mfma_f32_16x16x32_bf16 v[78:81], v[168:171], v[204:207], v[78:81]
	v_mfma_f32_16x16x32_bf16 v[74:77], v[176:179], v[204:207], v[74:77]
	v_mfma_f32_16x16x32_bf16 v[70:73], v[168:171], v[212:215], v[70:73]
	v_mfma_f32_16x16x32_bf16 v[66:69], v[176:179], v[212:215], v[66:69]
	v_mfma_f32_16x16x32_bf16 v[110:113], v[172:175], v[188:191], v[110:113]
	v_mfma_f32_16x16x32_bf16 v[106:109], v[180:183], v[188:191], v[106:109]
	v_mfma_f32_16x16x32_bf16 v[94:97], v[172:175], v[200:203], v[94:97]
	v_mfma_f32_16x16x32_bf16 v[90:93], v[180:183], v[200:203], v[90:93]
	v_mfma_f32_16x16x32_bf16 v[78:81], v[172:175], v[208:211], v[78:81]
	v_mfma_f32_16x16x32_bf16 v[74:77], v[180:183], v[208:211], v[74:77]
	v_mfma_f32_16x16x32_bf16 v[70:73], v[172:175], v[216:219], v[70:73]
	v_mfma_f32_16x16x32_bf16 v[66:69], v[180:183], v[216:219], v[66:69]
	s_barrier
	s_add_i32 s22, s47, s36
	v_lshl_add_u64 v[196:197], s[26:27], 0, v[134:135]
	s_mov_b32 m0, s22
	ds_read_b128 v[184:187], v150 offset:17408
	ds_read_b128 v[188:191], v150 offset:18432
	ds_read_b128 v[192:195], v150 offset:19456
	ds_read_b128 v[200:203], v150 offset:20480
	ds_read_b128 v[204:207], v150 offset:21504
	ds_read_b128 v[208:211], v150 offset:22528
	ds_read_b128 v[212:215], v150 offset:23552
	ds_read_b128 v[216:219], v150 offset:24576
	global_load_lds_dwordx4 v[196:197], off
	s_add_i32 m0, s22, 0x2000
	s_add_u32 s22, s26, 0xb0000
	v_lshl_add_u64 v[220:221], s[26:27], 0, v[130:131]
	s_addc_u32 s23, s27, 0
	s_add_i32 s65, s48, s36
	global_load_lds_dwordx4 v[220:221], off
	v_lshl_add_u64 v[222:223], s[22:23], 0, v[134:135]
	s_mov_b32 m0, s65
	v_lshl_add_u64 v[224:225], s[28:29], 0, v[132:133]
	global_load_lds_dwordx4 v[222:223], off
	v_lshl_add_u64 v[222:223], s[22:23], 0, v[130:131]
	s_add_i32 m0, s65, 0x2000
	s_nop 0
	global_load_lds_dwordx4 v[222:223], off
	v_lshl_add_u64 v[222:223], s[28:29], 0, v[136:137]
	s_mov_b32 m0, s39
	s_nop 0
	global_load_lds_dwordx4 v[222:223], off
	s_mov_b32 m0, s40
	s_nop 0
	global_load_lds_dwordx4 v[224:225], off
	s_waitcnt vmcnt(8)
	s_waitcnt lgkmcnt(0)
	s_barrier
	s_waitcnt lgkmcnt(0)
	v_mfma_f32_16x16x32_bf16 v[62:65], v[152:155], v[184:187], v[62:65]
	v_mfma_f32_16x16x32_bf16 v[58:61], v[160:163], v[184:187], v[58:61]
	v_mfma_f32_16x16x32_bf16 v[54:57], v[152:155], v[192:195], v[54:57]
	v_mfma_f32_16x16x32_bf16 v[50:53], v[160:163], v[192:195], v[50:53]
	v_mfma_f32_16x16x32_bf16 v[38:41], v[152:155], v[204:207], v[38:41]
	v_mfma_f32_16x16x32_bf16 v[34:37], v[160:163], v[204:207], v[34:37]
	v_mfma_f32_16x16x32_bf16 v[22:25], v[152:155], v[212:215], v[22:25]
	v_mfma_f32_16x16x32_bf16 v[18:21], v[160:163], v[212:215], v[18:21]
	v_mfma_f32_16x16x32_bf16 v[62:65], v[156:159], v[188:191], v[62:65]
	v_mfma_f32_16x16x32_bf16 v[58:61], v[164:167], v[188:191], v[58:61]
	v_mfma_f32_16x16x32_bf16 v[54:57], v[156:159], v[200:203], v[54:57]
	v_mfma_f32_16x16x32_bf16 v[50:53], v[164:167], v[200:203], v[50:53]
	v_mfma_f32_16x16x32_bf16 v[38:41], v[156:159], v[208:211], v[38:41]
	v_mfma_f32_16x16x32_bf16 v[34:37], v[164:167], v[208:211], v[34:37]
	v_mfma_f32_16x16x32_bf16 v[22:25], v[156:159], v[216:219], v[22:25]
	v_mfma_f32_16x16x32_bf16 v[18:21], v[164:167], v[216:219], v[18:21]
	v_mfma_f32_16x16x32_bf16 v[46:49], v[168:171], v[184:187], v[46:49]
	v_mfma_f32_16x16x32_bf16 v[42:45], v[176:179], v[184:187], v[42:45]
	v_mfma_f32_16x16x32_bf16 v[30:33], v[168:171], v[192:195], v[30:33]
	v_mfma_f32_16x16x32_bf16 v[26:29], v[176:179], v[192:195], v[26:29]
	v_mfma_f32_16x16x32_bf16 v[14:17], v[168:171], v[204:207], v[14:17]
	v_mfma_f32_16x16x32_bf16 v[10:13], v[176:179], v[204:207], v[10:13]
	v_mfma_f32_16x16x32_bf16 v[6:9], v[168:171], v[212:215], v[6:9]
	v_mfma_f32_16x16x32_bf16 v[2:5], v[176:179], v[212:215], v[2:5]
	v_mfma_f32_16x16x32_bf16 v[46:49], v[172:175], v[188:191], v[46:49]
	v_mfma_f32_16x16x32_bf16 v[42:45], v[180:183], v[188:191], v[42:45]
	v_mfma_f32_16x16x32_bf16 v[30:33], v[172:175], v[200:203], v[30:33]
	v_mfma_f32_16x16x32_bf16 v[26:29], v[180:183], v[200:203], v[26:29]
	v_mfma_f32_16x16x32_bf16 v[14:17], v[172:175], v[208:211], v[14:17]
	v_mfma_f32_16x16x32_bf16 v[10:13], v[180:183], v[208:211], v[10:13]
	v_mfma_f32_16x16x32_bf16 v[6:9], v[172:175], v[216:219], v[6:9]
	v_mfma_f32_16x16x32_bf16 v[2:5], v[180:183], v[216:219], v[2:5]
	s_barrier
	s_add_i32 s65, 0, 0x18400
	v_add_u32_e32 v151, s65, v146
	s_add_i32 s66, 0, 0x1c400
	ds_read_b128 v[152:155], v151
	ds_read_b128 v[156:159], v151 offset:1024
	ds_read_b128 v[160:163], v151 offset:2048
	ds_read_b128 v[164:167], v151 offset:3072
	v_add_u32_e32 v151, s66, v146
	ds_read_b128 v[168:171], v151
	ds_read_b128 v[172:175], v151 offset:1024
	ds_read_b128 v[176:179], v151 offset:2048
	ds_read_b128 v[180:183], v151 offset:3072
	s_add_u32 s22, s28, 0xb0000
	s_addc_u32 s23, s29, 0
	s_mov_b32 m0, s41
	v_lshl_add_u64 v[226:227], s[22:23], 0, v[136:137]
	ds_read_b128 v[184:187], v150 offset:33792
	ds_read_b128 v[188:191], v150 offset:34816
	ds_read_b128 v[192:195], v150 offset:35840
	ds_read_b128 v[200:203], v150 offset:36864
	ds_read_b128 v[204:207], v150 offset:37888
	ds_read_b128 v[208:211], v150 offset:38912
	ds_read_b128 v[212:215], v150 offset:39936
	ds_read_b128 v[216:219], v150 offset:40960
	global_load_lds_dwordx4 v[226:227], off
	v_lshl_add_u64 v[226:227], s[22:23], 0, v[132:133]
	s_mov_b32 m0, s42
	s_nop 0
	global_load_lds_dwordx4 v[226:227], off
	s_waitcnt vmcnt(8)
	s_waitcnt lgkmcnt(0)
	s_barrier
	s_waitcnt lgkmcnt(0)
	v_mfma_f32_16x16x32_bf16 v[126:129], v[152:155], v[184:187], v[126:129]
	v_mfma_f32_16x16x32_bf16 v[122:125], v[160:163], v[184:187], v[122:125]
	v_mfma_f32_16x16x32_bf16 v[118:121], v[152:155], v[192:195], v[118:121]
	v_mfma_f32_16x16x32_bf16 v[114:117], v[160:163], v[192:195], v[114:117]
	v_mfma_f32_16x16x32_bf16 v[102:105], v[152:155], v[204:207], v[102:105]
	v_mfma_f32_16x16x32_bf16 v[98:101], v[160:163], v[204:207], v[98:101]
	v_mfma_f32_16x16x32_bf16 v[86:89], v[152:155], v[212:215], v[86:89]
	v_mfma_f32_16x16x32_bf16 v[82:85], v[160:163], v[212:215], v[82:85]
	v_mfma_f32_16x16x32_bf16 v[126:129], v[156:159], v[188:191], v[126:129]
	v_mfma_f32_16x16x32_bf16 v[122:125], v[164:167], v[188:191], v[122:125]
	v_mfma_f32_16x16x32_bf16 v[118:121], v[156:159], v[200:203], v[118:121]
	v_mfma_f32_16x16x32_bf16 v[114:117], v[164:167], v[200:203], v[114:117]
	v_mfma_f32_16x16x32_bf16 v[102:105], v[156:159], v[208:211], v[102:105]
	v_mfma_f32_16x16x32_bf16 v[98:101], v[164:167], v[208:211], v[98:101]
	v_mfma_f32_16x16x32_bf16 v[86:89], v[156:159], v[216:219], v[86:89]
	v_mfma_f32_16x16x32_bf16 v[82:85], v[164:167], v[216:219], v[82:85]
	v_mfma_f32_16x16x32_bf16 v[110:113], v[168:171], v[184:187], v[110:113]
	v_mfma_f32_16x16x32_bf16 v[106:109], v[176:179], v[184:187], v[106:109]
	v_mfma_f32_16x16x32_bf16 v[94:97], v[168:171], v[192:195], v[94:97]
	v_mfma_f32_16x16x32_bf16 v[90:93], v[176:179], v[192:195], v[90:93]
	v_mfma_f32_16x16x32_bf16 v[78:81], v[168:171], v[204:207], v[78:81]
	v_mfma_f32_16x16x32_bf16 v[74:77], v[176:179], v[204:207], v[74:77]
	v_mfma_f32_16x16x32_bf16 v[70:73], v[168:171], v[212:215], v[70:73]
	v_mfma_f32_16x16x32_bf16 v[66:69], v[176:179], v[212:215], v[66:69]
	v_mfma_f32_16x16x32_bf16 v[110:113], v[172:175], v[188:191], v[110:113]
	v_mfma_f32_16x16x32_bf16 v[106:109], v[180:183], v[188:191], v[106:109]
	v_mfma_f32_16x16x32_bf16 v[94:97], v[172:175], v[200:203], v[94:97]
	v_mfma_f32_16x16x32_bf16 v[90:93], v[180:183], v[200:203], v[90:93]
	v_mfma_f32_16x16x32_bf16 v[78:81], v[172:175], v[208:211], v[78:81]
	v_mfma_f32_16x16x32_bf16 v[74:77], v[180:183], v[208:211], v[74:77]
	v_mfma_f32_16x16x32_bf16 v[70:73], v[172:175], v[216:219], v[70:73]
	v_mfma_f32_16x16x32_bf16 v[66:69], v[180:183], v[216:219], v[66:69]
	s_barrier
	s_add_i32 s22, s65, s36
	v_lshl_add_u64 v[196:197], v[196:197], 0, s[16:17]
	s_mov_b32 m0, s22
	ds_read_b128 v[184:187], v150 offset:50176
	ds_read_b128 v[188:191], v150 offset:51200
	ds_read_b128 v[192:195], v150 offset:52224
	ds_read_b128 v[200:203], v150 offset:53248
	ds_read_b128 v[204:207], v150 offset:54272
	ds_read_b128 v[208:211], v150 offset:55296
	ds_read_b128 v[212:215], v150 offset:56320
	ds_read_b128 v[216:219], v150 offset:57344
	global_load_lds_dwordx4 v[196:197], off
	s_add_i32 m0, s22, 0x2000
	s_add_u32 s22, s26, 0xb0080
	v_lshl_add_u64 v[196:197], v[220:221], 0, s[16:17]
	s_addc_u32 s23, s27, 0
	s_add_i32 s26, s66, s36
	global_load_lds_dwordx4 v[196:197], off
	v_lshl_add_u64 v[196:197], s[22:23], 0, v[134:135]
	s_mov_b32 m0, s26
	s_nop 0
	global_load_lds_dwordx4 v[196:197], off
	v_lshl_add_u64 v[196:197], s[22:23], 0, v[130:131]
	s_add_i32 m0, s26, 0x2000
	s_nop 0
	global_load_lds_dwordx4 v[196:197], off
	v_lshl_add_u64 v[196:197], v[222:223], 0, s[16:17]
	s_mov_b32 m0, s44
	s_nop 0
	global_load_lds_dwordx4 v[196:197], off
	v_lshl_add_u64 v[196:197], v[224:225], 0, s[16:17]
	s_mov_b32 m0, s45
	s_nop 0
	global_load_lds_dwordx4 v[196:197], off
	s_waitcnt vmcnt(8)
	s_waitcnt lgkmcnt(0)
	s_barrier
	s_waitcnt lgkmcnt(0)
	v_mfma_f32_16x16x32_bf16 v[62:65], v[152:155], v[184:187], v[62:65]
	v_mfma_f32_16x16x32_bf16 v[58:61], v[160:163], v[184:187], v[58:61]
	v_mfma_f32_16x16x32_bf16 v[54:57], v[152:155], v[192:195], v[54:57]
	v_mfma_f32_16x16x32_bf16 v[50:53], v[160:163], v[192:195], v[50:53]
	v_mfma_f32_16x16x32_bf16 v[38:41], v[152:155], v[204:207], v[38:41]
	v_mfma_f32_16x16x32_bf16 v[34:37], v[160:163], v[204:207], v[34:37]
	v_mfma_f32_16x16x32_bf16 v[22:25], v[152:155], v[212:215], v[22:25]
	v_mfma_f32_16x16x32_bf16 v[18:21], v[160:163], v[212:215], v[18:21]
	v_mfma_f32_16x16x32_bf16 v[62:65], v[156:159], v[188:191], v[62:65]
	v_mfma_f32_16x16x32_bf16 v[58:61], v[164:167], v[188:191], v[58:61]
	v_mfma_f32_16x16x32_bf16 v[54:57], v[156:159], v[200:203], v[54:57]
	v_mfma_f32_16x16x32_bf16 v[50:53], v[164:167], v[200:203], v[50:53]
	v_mfma_f32_16x16x32_bf16 v[38:41], v[156:159], v[208:211], v[38:41]
	v_mfma_f32_16x16x32_bf16 v[34:37], v[164:167], v[208:211], v[34:37]
	v_mfma_f32_16x16x32_bf16 v[22:25], v[156:159], v[216:219], v[22:25]
	v_mfma_f32_16x16x32_bf16 v[18:21], v[164:167], v[216:219], v[18:21]
	v_mfma_f32_16x16x32_bf16 v[46:49], v[168:171], v[184:187], v[46:49]
	v_mfma_f32_16x16x32_bf16 v[42:45], v[176:179], v[184:187], v[42:45]
	v_mfma_f32_16x16x32_bf16 v[30:33], v[168:171], v[192:195], v[30:33]
	v_mfma_f32_16x16x32_bf16 v[26:29], v[176:179], v[192:195], v[26:29]
	v_mfma_f32_16x16x32_bf16 v[14:17], v[168:171], v[204:207], v[14:17]
	v_mfma_f32_16x16x32_bf16 v[10:13], v[176:179], v[204:207], v[10:13]
	v_mfma_f32_16x16x32_bf16 v[6:9], v[168:171], v[212:215], v[6:9]
	v_mfma_f32_16x16x32_bf16 v[2:5], v[176:179], v[212:215], v[2:5]
	v_mfma_f32_16x16x32_bf16 v[46:49], v[172:175], v[188:191], v[46:49]
	v_mfma_f32_16x16x32_bf16 v[42:45], v[180:183], v[188:191], v[42:45]
	v_mfma_f32_16x16x32_bf16 v[30:33], v[172:175], v[200:203], v[30:33]
	v_mfma_f32_16x16x32_bf16 v[26:29], v[180:183], v[200:203], v[26:29]
	v_mfma_f32_16x16x32_bf16 v[14:17], v[172:175], v[208:211], v[14:17]
	v_mfma_f32_16x16x32_bf16 v[10:13], v[180:183], v[208:211], v[10:13]
	v_mfma_f32_16x16x32_bf16 v[6:9], v[172:175], v[216:219], v[6:9]
	v_mfma_f32_16x16x32_bf16 v[2:5], v[180:183], v[216:219], v[2:5]
	s_barrier
	s_add_i32 s64, s64, 2
	s_add_u32 s55, s55, 0x100
	s_addc_u32 s57, s57, 0
	s_cmp_gt_u32 s64, 19
	s_mov_b64 s[22:23], s[24:25]
	s_cbranch_scc0 .LBB0_3410
	s_and_b64 vcc, exec, s[18:19]
	s_cbranch_vccz .LBB0_3413
	s_barrier

.LBB0_3434:
	s_add_u32 s22, s18, s20
	ds_read_b128 v[50:53], v47
	ds_read_b128 v[54:57], v47 offset:1024
	ds_read_b128 v[58:61], v47 offset:2048
	ds_read_b128 v[62:65], v47 offset:3072
	s_addc_u32 s23, s19, s21
	s_add_u32 s22, s22, 0x3128100
	s_addc_u32 s23, s23, 0
	s_add_u32 s66, s50, s20
	s_addc_u32 s67, s51, s21
	s_cmpk_eq_i32 s20, 0x700
	s_cselect_b32 s25, s15, s23
	s_cselect_b32 s24, s14, s22
	s_cselect_b32 s23, s11, s67
	s_cselect_b32 s22, s10, s66
	s_mov_b32 m0, s53
	v_lshl_add_u64 v[130:131], v[44:45], 0, s[20:21]
	ds_read_b128 v[98:101], v48 offset:1024
	ds_read_b128 v[102:105], v48 offset:2048
	ds_read_b128 v[106:109], v48 offset:3072
	ds_read_b128 v[110:113], v48 offset:4096
	ds_read_b128 v[114:117], v48 offset:5120
	ds_read_b128 v[118:121], v48 offset:6144
	ds_read_b128 v[122:125], v48 offset:7168
	ds_read_b128 v[126:129], v48 offset:8192
	global_load_lds_dwordx4 v[130:131], off
	v_lshl_add_u64 v[130:131], v[42:43], 0, s[20:21]
	s_mov_b32 m0, s54
	s_nop 0
	global_load_lds_dwordx4 v[130:131], off
	s_waitcnt vmcnt(8)
	s_waitcnt lgkmcnt(0)
	s_barrier
	s_waitcnt lgkmcnt(0)
	v_mfma_f32_16x16x32_bf16 v[30:33], v[50:53], v[98:101], v[30:33]
	v_mfma_f32_16x16x32_bf16 v[26:29], v[58:61], v[98:101], v[26:29]
	v_mfma_f32_16x16x32_bf16 v[18:21], v[50:53], v[106:109], v[18:21]
	v_mfma_f32_16x16x32_bf16 v[22:25], v[58:61], v[106:109], v[22:25]
	v_mfma_f32_16x16x32_bf16 v[10:13], v[50:53], v[114:117], v[10:13]
	v_mfma_f32_16x16x32_bf16 v[14:17], v[58:61], v[114:117], v[14:17]
	v_mfma_f32_16x16x32_bf16 v[2:5], v[50:53], v[122:125], v[2:5]
	v_mfma_f32_16x16x32_bf16 v[6:9], v[58:61], v[122:125], v[6:9]
	v_mfma_f32_16x16x32_bf16 v[30:33], v[54:57], v[102:105], v[30:33]
	v_mfma_f32_16x16x32_bf16 v[26:29], v[62:65], v[102:105], v[26:29]
	v_mfma_f32_16x16x32_bf16 v[18:21], v[54:57], v[110:113], v[18:21]
	v_mfma_f32_16x16x32_bf16 v[22:25], v[62:65], v[110:113], v[22:25]
	v_mfma_f32_16x16x32_bf16 v[10:13], v[54:57], v[118:121], v[10:13]
	v_mfma_f32_16x16x32_bf16 v[14:17], v[62:65], v[118:121], v[14:17]
	v_mfma_f32_16x16x32_bf16 v[2:5], v[54:57], v[126:129], v[2:5]
	v_mfma_f32_16x16x32_bf16 v[6:9], v[62:65], v[126:129], v[6:9]
	s_barrier
	s_mov_b32 m0, s55
	v_lshl_add_u64 v[130:131], s[22:23], 0, v[38:39]
	s_add_u32 s66, s22, 0x40000
	ds_read_b128 v[98:101], v48 offset:17408
	ds_read_b128 v[102:105], v48 offset:18432
	ds_read_b128 v[106:109], v48 offset:19456
	ds_read_b128 v[110:113], v48 offset:20480
	ds_read_b128 v[114:117], v48 offset:21504
	ds_read_b128 v[118:121], v48 offset:22528
	ds_read_b128 v[122:125], v48 offset:23552
	ds_read_b128 v[126:129], v48 offset:24576
	global_load_lds_dwordx4 v[130:131], off
	v_lshl_add_u64 v[132:133], s[22:23], 0, v[40:41]
	s_mov_b32 m0, s57
	s_addc_u32 s67, s23, 0
	global_load_lds_dwordx4 v[132:133], off
	v_lshl_add_u64 v[134:135], s[66:67], 0, v[34:35]
	s_mov_b32 m0, s5
	v_lshl_add_u64 v[136:137], s[24:25], 0, v[36:37]
	global_load_lds_dwordx4 v[134:135], off
	v_lshl_add_u64 v[134:135], s[66:67], 0, v[36:37]
	s_mov_b32 m0, s9
	s_nop 0
	global_load_lds_dwordx4 v[134:135], off
	v_lshl_add_u64 v[134:135], s[24:25], 0, v[34:35]
	s_mov_b32 m0, s41
	s_nop 0
	global_load_lds_dwordx4 v[134:135], off
	s_mov_b32 m0, s42
	s_nop 0
	global_load_lds_dwordx4 v[136:137], off
	s_waitcnt vmcnt(8)
	s_waitcnt lgkmcnt(0)
	s_barrier
	s_waitcnt lgkmcnt(0)
	v_mfma_f32_16x16x32_bf16 v[94:97], v[50:53], v[98:101], v[94:97]
	v_mfma_f32_16x16x32_bf16 v[90:93], v[58:61], v[98:101], v[90:93]
	v_mfma_f32_16x16x32_bf16 v[82:85], v[50:53], v[106:109], v[82:85]
	v_mfma_f32_16x16x32_bf16 v[86:89], v[58:61], v[106:109], v[86:89]
	v_mfma_f32_16x16x32_bf16 v[74:77], v[50:53], v[114:117], v[74:77]
	v_mfma_f32_16x16x32_bf16 v[78:81], v[58:61], v[114:117], v[78:81]
	v_mfma_f32_16x16x32_bf16 v[50:53], v[50:53], v[122:125], v[66:69]
	v_mfma_f32_16x16x32_bf16 v[94:97], v[54:57], v[102:105], v[94:97]
	v_mfma_f32_16x16x32_bf16 v[90:93], v[62:65], v[102:105], v[90:93]
	v_mfma_f32_16x16x32_bf16 v[82:85], v[54:57], v[110:113], v[82:85]
	v_mfma_f32_16x16x32_bf16 v[86:89], v[62:65], v[110:113], v[86:89]
	v_mfma_f32_16x16x32_bf16 v[74:77], v[54:57], v[118:121], v[74:77]
	v_mfma_f32_16x16x32_bf16 v[78:81], v[62:65], v[118:121], v[78:81]
	v_mfma_f32_16x16x32_bf16 v[50:53], v[54:57], v[126:129], v[50:53]
	v_mfma_f32_16x16x32_bf16 v[54:57], v[58:61], v[122:125], v[70:73]
	v_mfma_f32_16x16x32_bf16 v[54:57], v[62:65], v[126:129], v[54:57]
	s_barrier
	ds_read_b128 v[58:61], v49
	ds_read_b128 v[62:65], v49 offset:1024
	ds_read_b128 v[70:73], v49 offset:2048
	ds_read_b128 v[98:101], v49 offset:3072
	s_add_u32 s24, s24, 0x40000
	s_addc_u32 s25, s25, 0
	s_mov_b32 m0, s43
	v_lshl_add_u64 v[138:139], s[24:25], 0, v[34:35]
	ds_read_b128 v[66:69], v48 offset:33792
	ds_read_b128 v[102:105], v48 offset:34816
	ds_read_b128 v[106:109], v48 offset:35840
	ds_read_b128 v[110:113], v48 offset:36864
	ds_read_b128 v[114:117], v48 offset:37888
	ds_read_b128 v[118:121], v48 offset:38912
	ds_read_b128 v[122:125], v48 offset:39936
	ds_read_b128 v[126:129], v48 offset:40960
	global_load_lds_dwordx4 v[138:139], off
	v_lshl_add_u64 v[138:139], s[24:25], 0, v[36:37]
	s_mov_b32 m0, s44
	s_nop 0
	global_load_lds_dwordx4 v[138:139], off
	s_waitcnt vmcnt(8)
	s_waitcnt lgkmcnt(0)
	s_barrier
	s_waitcnt lgkmcnt(0)
	v_mfma_f32_16x16x32_bf16 v[30:33], v[58:61], v[66:69], v[30:33]
	v_mfma_f32_16x16x32_bf16 v[26:29], v[70:73], v[66:69], v[26:29]
	v_mfma_f32_16x16x32_bf16 v[18:21], v[58:61], v[106:109], v[18:21]
	v_mfma_f32_16x16x32_bf16 v[22:25], v[70:73], v[106:109], v[22:25]
	v_mfma_f32_16x16x32_bf16 v[10:13], v[58:61], v[114:117], v[10:13]
	v_mfma_f32_16x16x32_bf16 v[14:17], v[70:73], v[114:117], v[14:17]
	v_mfma_f32_16x16x32_bf16 v[2:5], v[58:61], v[122:125], v[2:5]
	v_mfma_f32_16x16x32_bf16 v[6:9], v[70:73], v[122:125], v[6:9]
	v_mfma_f32_16x16x32_bf16 v[30:33], v[62:65], v[102:105], v[30:33]
	v_mfma_f32_16x16x32_bf16 v[26:29], v[98:101], v[102:105], v[26:29]
	v_mfma_f32_16x16x32_bf16 v[18:21], v[62:65], v[110:113], v[18:21]
	v_mfma_f32_16x16x32_bf16 v[22:25], v[98:101], v[110:113], v[22:25]
	v_mfma_f32_16x16x32_bf16 v[10:13], v[62:65], v[118:121], v[10:13]
	v_mfma_f32_16x16x32_bf16 v[14:17], v[98:101], v[118:121], v[14:17]
	v_mfma_f32_16x16x32_bf16 v[2:5], v[62:65], v[126:129], v[2:5]
	v_mfma_f32_16x16x32_bf16 v[6:9], v[98:101], v[126:129], v[6:9]
	s_barrier
	s_mov_b32 m0, s64
	v_lshl_add_u64 v[130:131], v[130:131], 0, s[16:17]
	s_add_u32 s22, s22, 0x40080
	ds_read_b128 v[66:69], v48 offset:50176
	ds_read_b128 v[102:105], v48 offset:51200
	ds_read_b128 v[106:109], v48 offset:52224
	ds_read_b128 v[110:113], v48 offset:53248
	ds_read_b128 v[114:117], v48 offset:54272
	ds_read_b128 v[118:121], v48 offset:55296
	ds_read_b128 v[122:125], v48 offset:56320
	ds_read_b128 v[126:129], v48 offset:57344
	global_load_lds_dwordx4 v[130:131], off
	v_lshl_add_u64 v[130:131], v[132:133], 0, s[16:17]
	s_mov_b32 m0, s65
	s_addc_u32 s23, s23, 0
	global_load_lds_dwordx4 v[130:131], off
	v_lshl_add_u64 v[130:131], s[22:23], 0, v[34:35]
	s_mov_b32 m0, s48
	s_nop 0
	global_load_lds_dwordx4 v[130:131], off
	v_lshl_add_u64 v[130:131], s[22:23], 0, v[36:37]
	s_mov_b32 m0, s49
	s_nop 0
	global_load_lds_dwordx4 v[130:131], off
	v_lshl_add_u64 v[130:131], v[134:135], 0, s[16:17]
	s_mov_b32 m0, s46
	s_nop 0
	global_load_lds_dwordx4 v[130:131], off
	v_lshl_add_u64 v[130:131], v[136:137], 0, s[16:17]
	s_mov_b32 m0, s47
	s_nop 0
	global_load_lds_dwordx4 v[130:131], off
	s_waitcnt vmcnt(8)
	s_waitcnt lgkmcnt(0)
	s_barrier
	s_waitcnt lgkmcnt(0)
	v_mfma_f32_16x16x32_bf16 v[94:97], v[58:61], v[66:69], v[94:97]
	v_mfma_f32_16x16x32_bf16 v[66:69], v[70:73], v[66:69], v[90:93]
	v_mfma_f32_16x16x32_bf16 v[90:93], v[98:101], v[102:105], v[66:69]
	v_mfma_f32_16x16x32_bf16 v[66:69], v[58:61], v[106:109], v[82:85]
	v_mfma_f32_16x16x32_bf16 v[82:85], v[62:65], v[110:113], v[66:69]
	v_mfma_f32_16x16x32_bf16 v[66:69], v[70:73], v[106:109], v[86:89]
	v_mfma_f32_16x16x32_bf16 v[86:89], v[98:101], v[110:113], v[66:69]
	v_mfma_f32_16x16x32_bf16 v[66:69], v[58:61], v[114:117], v[74:77]
	v_mfma_f32_16x16x32_bf16 v[74:77], v[62:65], v[118:121], v[66:69]
	v_mfma_f32_16x16x32_bf16 v[66:69], v[70:73], v[114:117], v[78:81]
	v_mfma_f32_16x16x32_bf16 v[50:53], v[58:61], v[122:125], v[50:53]
	v_mfma_f32_16x16x32_bf16 v[78:81], v[98:101], v[118:121], v[66:69]
	v_mfma_f32_16x16x32_bf16 v[66:69], v[62:65], v[126:129], v[50:53]
	v_mfma_f32_16x16x32_bf16 v[50:53], v[70:73], v[122:125], v[54:57]
	v_mfma_f32_16x16x32_bf16 v[94:97], v[62:65], v[102:105], v[94:97]
	v_mfma_f32_16x16x32_bf16 v[70:73], v[98:101], v[126:129], v[50:53]
	s_barrier
	s_add_i32 s52, s52, 2
	s_add_u32 s20, s20, 0x100
	s_addc_u32 s21, s21, 0
	s_cmp_gt_u32 s52, 13
	s_cbranch_scc0 .LBB0_3434
	s_cmpk_lt_u32 s33, 0x100
	s_cbranch_scc0 .LBB0_3437
	s_barrier

.LBB0_3513:
	ds_read_b128 v[144:147], v136
	ds_read_b128 v[148:151], v136 offset:1024
	ds_read_b128 v[152:155], v136 offset:2048
	ds_read_b128 v[156:159], v136 offset:3072
	ds_read_b128 v[160:163], v137
	ds_read_b128 v[164:167], v137 offset:1024
	ds_read_b128 v[168:171], v137 offset:2048
	ds_read_b128 v[172:175], v137 offset:3072
	s_or_b32 s8, s12, 1
	s_lshl_b64 s[42:43], s[8:9], 7
	s_add_i32 s8, s12, 2
	s_lshl_b64 s[14:15], s[8:9], 7
	s_cmp_lg_u32 s12, s28
	s_cselect_b32 s12, s14, 0
	s_cselect_b32 s13, s15, 0
	s_add_u32 s14, s2, s12
	s_addc_u32 s15, s3, s13
	s_add_u32 s12, s4, s12
	s_addc_u32 s13, s5, s13
	s_add_u32 s42, s2, s42
	s_addc_u32 s43, s3, s43
	s_add_u32 s42, s42, 0xb0000
	s_addc_u32 s43, s43, 0
	s_mov_b32 m0, s29
	v_lshl_add_u64 v[196:197], s[42:43], 0, v[128:129]
	ds_read_b128 v[176:179], v138 offset:1024
	ds_read_b128 v[180:183], v138 offset:2048
	ds_read_b128 v[184:187], v138 offset:3072
	ds_read_b128 v[188:191], v138 offset:4096
	ds_read_b128 v[192:195], v138 offset:5120
	ds_read_b128 v[200:203], v138 offset:6144
	ds_read_b128 v[204:207], v138 offset:7168
	ds_read_b128 v[208:211], v138 offset:8192
	global_load_lds_dwordx4 v[196:197], off
	v_lshl_add_u64 v[196:197], s[42:43], 0, v[132:133]
	s_mov_b32 m0, s34
	s_nop 0
	global_load_lds_dwordx4 v[196:197], off
	s_waitcnt vmcnt(8)
	s_waitcnt lgkmcnt(0)
	s_barrier
	s_waitcnt lgkmcnt(0)
	v_mfma_f32_16x16x32_bf16 v[124:127], v[144:147], v[176:179], v[124:127]
	v_mfma_f32_16x16x32_bf16 v[120:123], v[152:155], v[176:179], v[120:123]
	v_mfma_f32_16x16x32_bf16 v[116:119], v[144:147], v[184:187], v[116:119]
	v_mfma_f32_16x16x32_bf16 v[112:115], v[152:155], v[184:187], v[112:115]
	v_mfma_f32_16x16x32_bf16 v[100:103], v[144:147], v[192:195], v[100:103]
	v_mfma_f32_16x16x32_bf16 v[96:99], v[152:155], v[192:195], v[96:99]
	v_mfma_f32_16x16x32_bf16 v[84:87], v[144:147], v[204:207], v[84:87]
	v_mfma_f32_16x16x32_bf16 v[80:83], v[152:155], v[204:207], v[80:83]
	v_mfma_f32_16x16x32_bf16 v[124:127], v[148:151], v[180:183], v[124:127]
	v_mfma_f32_16x16x32_bf16 v[120:123], v[156:159], v[180:183], v[120:123]
	v_mfma_f32_16x16x32_bf16 v[116:119], v[148:151], v[188:191], v[116:119]
	v_mfma_f32_16x16x32_bf16 v[112:115], v[156:159], v[188:191], v[112:115]
	v_mfma_f32_16x16x32_bf16 v[100:103], v[148:151], v[200:203], v[100:103]
	v_mfma_f32_16x16x32_bf16 v[96:99], v[156:159], v[200:203], v[96:99]
	v_mfma_f32_16x16x32_bf16 v[84:87], v[148:151], v[208:211], v[84:87]
	v_mfma_f32_16x16x32_bf16 v[80:83], v[156:159], v[208:211], v[80:83]
	v_mfma_f32_16x16x32_bf16 v[108:111], v[160:163], v[176:179], v[108:111]
	v_mfma_f32_16x16x32_bf16 v[104:107], v[168:171], v[176:179], v[104:107]
	v_mfma_f32_16x16x32_bf16 v[92:95], v[160:163], v[184:187], v[92:95]
	v_mfma_f32_16x16x32_bf16 v[88:91], v[168:171], v[184:187], v[88:91]
	v_mfma_f32_16x16x32_bf16 v[76:79], v[160:163], v[192:195], v[76:79]
	v_mfma_f32_16x16x32_bf16 v[72:75], v[168:171], v[192:195], v[72:75]
	v_mfma_f32_16x16x32_bf16 v[68:71], v[160:163], v[204:207], v[68:71]
	v_mfma_f32_16x16x32_bf16 v[64:67], v[168:171], v[204:207], v[64:67]
	v_mfma_f32_16x16x32_bf16 v[108:111], v[164:167], v[180:183], v[108:111]
	v_mfma_f32_16x16x32_bf16 v[104:107], v[172:175], v[180:183], v[104:107]
	v_mfma_f32_16x16x32_bf16 v[92:95], v[164:167], v[188:191], v[92:95]
	v_mfma_f32_16x16x32_bf16 v[88:91], v[172:175], v[188:191], v[88:91]
	v_mfma_f32_16x16x32_bf16 v[76:79], v[164:167], v[200:203], v[76:79]
	v_mfma_f32_16x16x32_bf16 v[72:75], v[172:175], v[200:203], v[72:75]
	v_mfma_f32_16x16x32_bf16 v[68:71], v[164:167], v[208:211], v[68:71]
	v_mfma_f32_16x16x32_bf16 v[64:67], v[172:175], v[208:211], v[64:67]
	s_barrier
	s_mov_b32 m0, s35
	v_lshl_add_u64 v[196:197], s[12:13], 0, v[130:131]
	s_add_u32 s42, s12, 0xb0000
	ds_read_b128 v[176:179], v138 offset:17408
	ds_read_b128 v[180:183], v138 offset:18432
	ds_read_b128 v[184:187], v138 offset:19456
	ds_read_b128 v[188:191], v138 offset:20480
	ds_read_b128 v[192:195], v138 offset:21504
	ds_read_b128 v[200:203], v138 offset:22528
	ds_read_b128 v[204:207], v138 offset:23552
	ds_read_b128 v[208:211], v138 offset:24576
	global_load_lds_dwordx4 v[196:197], off
	v_lshl_add_u64 v[212:213], s[12:13], 0, v[134:135]
	s_mov_b32 m0, s36
	s_addc_u32 s43, s13, 0
	global_load_lds_dwordx4 v[212:213], off
	v_lshl_add_u64 v[214:215], s[42:43], 0, v[130:131]
	s_mov_b32 m0, s37
	v_lshl_add_u64 v[216:217], s[14:15], 0, v[132:133]
	global_load_lds_dwordx4 v[214:215], off
	v_lshl_add_u64 v[214:215], s[42:43], 0, v[134:135]
	s_mov_b32 m0, s38
	s_nop 0
	global_load_lds_dwordx4 v[214:215], off
	v_lshl_add_u64 v[214:215], s[14:15], 0, v[128:129]
	s_mov_b32 m0, s19
	s_nop 0
	global_load_lds_dwordx4 v[214:215], off
	s_mov_b32 m0, s20
	s_nop 0
	global_load_lds_dwordx4 v[216:217], off
	s_waitcnt vmcnt(8)
	s_waitcnt lgkmcnt(0)
	s_barrier
	s_waitcnt lgkmcnt(0)
	v_mfma_f32_16x16x32_bf16 v[60:63], v[144:147], v[176:179], v[60:63]
	v_mfma_f32_16x16x32_bf16 v[56:59], v[152:155], v[176:179], v[56:59]
	v_mfma_f32_16x16x32_bf16 v[52:55], v[144:147], v[184:187], v[52:55]
	v_mfma_f32_16x16x32_bf16 v[48:51], v[152:155], v[184:187], v[48:51]
	v_mfma_f32_16x16x32_bf16 v[36:39], v[144:147], v[192:195], v[36:39]
	v_mfma_f32_16x16x32_bf16 v[32:35], v[152:155], v[192:195], v[32:35]
	v_mfma_f32_16x16x32_bf16 v[20:23], v[144:147], v[204:207], v[20:23]
	v_mfma_f32_16x16x32_bf16 v[16:19], v[152:155], v[204:207], v[16:19]
	v_mfma_f32_16x16x32_bf16 v[60:63], v[148:151], v[180:183], v[60:63]
	v_mfma_f32_16x16x32_bf16 v[56:59], v[156:159], v[180:183], v[56:59]
	v_mfma_f32_16x16x32_bf16 v[52:55], v[148:151], v[188:191], v[52:55]
	v_mfma_f32_16x16x32_bf16 v[48:51], v[156:159], v[188:191], v[48:51]
	v_mfma_f32_16x16x32_bf16 v[36:39], v[148:151], v[200:203], v[36:39]
	v_mfma_f32_16x16x32_bf16 v[32:35], v[156:159], v[200:203], v[32:35]
	v_mfma_f32_16x16x32_bf16 v[20:23], v[148:151], v[208:211], v[20:23]
	v_mfma_f32_16x16x32_bf16 v[16:19], v[156:159], v[208:211], v[16:19]
	v_mfma_f32_16x16x32_bf16 v[44:47], v[160:163], v[176:179], v[44:47]
	v_mfma_f32_16x16x32_bf16 v[40:43], v[168:171], v[176:179], v[40:43]
	v_mfma_f32_16x16x32_bf16 v[28:31], v[160:163], v[184:187], v[28:31]
	v_mfma_f32_16x16x32_bf16 v[24:27], v[168:171], v[184:187], v[24:27]
	v_mfma_f32_16x16x32_bf16 v[12:15], v[160:163], v[192:195], v[12:15]
	v_mfma_f32_16x16x32_bf16 v[8:11], v[168:171], v[192:195], v[8:11]
	v_mfma_f32_16x16x32_bf16 v[4:7], v[160:163], v[204:207], v[4:7]
	v_mfma_f32_16x16x32_bf16 v[0:3], v[168:171], v[204:207], v[0:3]
	v_mfma_f32_16x16x32_bf16 v[44:47], v[164:167], v[180:183], v[44:47]
	v_mfma_f32_16x16x32_bf16 v[40:43], v[172:175], v[180:183], v[40:43]
	v_mfma_f32_16x16x32_bf16 v[28:31], v[164:167], v[188:191], v[28:31]
	v_mfma_f32_16x16x32_bf16 v[24:27], v[172:175], v[188:191], v[24:27]
	v_mfma_f32_16x16x32_bf16 v[12:15], v[164:167], v[200:203], v[12:15]
	v_mfma_f32_16x16x32_bf16 v[8:11], v[172:175], v[200:203], v[8:11]
	v_mfma_f32_16x16x32_bf16 v[4:7], v[164:167], v[208:211], v[4:7]
	v_mfma_f32_16x16x32_bf16 v[0:3], v[172:175], v[208:211], v[0:3]
	s_barrier
	ds_read_b128 v[144:147], v139
	ds_read_b128 v[148:151], v139 offset:1024
	ds_read_b128 v[152:155], v139 offset:2048
	ds_read_b128 v[156:159], v139 offset:3072
	ds_read_b128 v[160:163], v142
	ds_read_b128 v[164:167], v142 offset:1024
	ds_read_b128 v[168:171], v142 offset:2048
	ds_read_b128 v[172:175], v142 offset:3072
	s_add_u32 s14, s14, 0xb0000
	s_addc_u32 s15, s15, 0
	s_mov_b32 m0, s21
	v_lshl_add_u64 v[218:219], s[14:15], 0, v[128:129]
	ds_read_b128 v[176:179], v138 offset:33792
	ds_read_b128 v[180:183], v138 offset:34816
	ds_read_b128 v[184:187], v138 offset:35840
	ds_read_b128 v[188:191], v138 offset:36864
	ds_read_b128 v[192:195], v138 offset:37888
	ds_read_b128 v[200:203], v138 offset:38912
	ds_read_b128 v[204:207], v138 offset:39936
	ds_read_b128 v[208:211], v138 offset:40960
	global_load_lds_dwordx4 v[218:219], off
	v_lshl_add_u64 v[218:219], s[14:15], 0, v[132:133]
	s_mov_b32 m0, s22
	s_nop 0
	global_load_lds_dwordx4 v[218:219], off
	s_waitcnt vmcnt(8)
	s_waitcnt lgkmcnt(0)
	s_barrier
	s_waitcnt lgkmcnt(0)
	v_mfma_f32_16x16x32_bf16 v[124:127], v[144:147], v[176:179], v[124:127]
	v_mfma_f32_16x16x32_bf16 v[120:123], v[152:155], v[176:179], v[120:123]
	v_mfma_f32_16x16x32_bf16 v[116:119], v[144:147], v[184:187], v[116:119]
	v_mfma_f32_16x16x32_bf16 v[112:115], v[152:155], v[184:187], v[112:115]
	v_mfma_f32_16x16x32_bf16 v[100:103], v[144:147], v[192:195], v[100:103]
	v_mfma_f32_16x16x32_bf16 v[96:99], v[152:155], v[192:195], v[96:99]
	v_mfma_f32_16x16x32_bf16 v[84:87], v[144:147], v[204:207], v[84:87]
	v_mfma_f32_16x16x32_bf16 v[80:83], v[152:155], v[204:207], v[80:83]
	v_mfma_f32_16x16x32_bf16 v[124:127], v[148:151], v[180:183], v[124:127]
	v_mfma_f32_16x16x32_bf16 v[120:123], v[156:159], v[180:183], v[120:123]
	v_mfma_f32_16x16x32_bf16 v[116:119], v[148:151], v[188:191], v[116:119]
	v_mfma_f32_16x16x32_bf16 v[112:115], v[156:159], v[188:191], v[112:115]
	v_mfma_f32_16x16x32_bf16 v[100:103], v[148:151], v[200:203], v[100:103]
	v_mfma_f32_16x16x32_bf16 v[96:99], v[156:159], v[200:203], v[96:99]
	v_mfma_f32_16x16x32_bf16 v[84:87], v[148:151], v[208:211], v[84:87]
	v_mfma_f32_16x16x32_bf16 v[80:83], v[156:159], v[208:211], v[80:83]
	v_mfma_f32_16x16x32_bf16 v[108:111], v[160:163], v[176:179], v[108:111]
	v_mfma_f32_16x16x32_bf16 v[104:107], v[168:171], v[176:179], v[104:107]
	v_mfma_f32_16x16x32_bf16 v[92:95], v[160:163], v[184:187], v[92:95]
	v_mfma_f32_16x16x32_bf16 v[88:91], v[168:171], v[184:187], v[88:91]
	v_mfma_f32_16x16x32_bf16 v[76:79], v[160:163], v[192:195], v[76:79]
	v_mfma_f32_16x16x32_bf16 v[72:75], v[168:171], v[192:195], v[72:75]
	v_mfma_f32_16x16x32_bf16 v[68:71], v[160:163], v[204:207], v[68:71]
	v_mfma_f32_16x16x32_bf16 v[64:67], v[168:171], v[204:207], v[64:67]
	v_mfma_f32_16x16x32_bf16 v[108:111], v[164:167], v[180:183], v[108:111]
	v_mfma_f32_16x16x32_bf16 v[104:107], v[172:175], v[180:183], v[104:107]
	v_mfma_f32_16x16x32_bf16 v[92:95], v[164:167], v[188:191], v[92:95]
	v_mfma_f32_16x16x32_bf16 v[88:91], v[172:175], v[188:191], v[88:91]
	v_mfma_f32_16x16x32_bf16 v[76:79], v[164:167], v[200:203], v[76:79]
	v_mfma_f32_16x16x32_bf16 v[72:75], v[172:175], v[200:203], v[72:75]
	v_mfma_f32_16x16x32_bf16 v[68:71], v[164:167], v[208:211], v[68:71]
	v_mfma_f32_16x16x32_bf16 v[64:67], v[172:175], v[208:211], v[64:67]
	s_barrier
	s_mov_b32 m0, s39
	v_lshl_add_u64 v[196:197], v[196:197], 0, s[10:11]
	s_add_u32 s12, s12, 0xb0080
	ds_read_b128 v[176:179], v138 offset:50176
	ds_read_b128 v[180:183], v138 offset:51200
	ds_read_b128 v[184:187], v138 offset:52224
	ds_read_b128 v[188:191], v138 offset:53248
	ds_read_b128 v[192:195], v138 offset:54272
	ds_read_b128 v[200:203], v138 offset:55296
	ds_read_b128 v[204:207], v138 offset:56320
	ds_read_b128 v[208:211], v138 offset:57344
	global_load_lds_dwordx4 v[196:197], off
	v_lshl_add_u64 v[196:197], v[212:213], 0, s[10:11]
	s_mov_b32 m0, s40
	s_addc_u32 s13, s13, 0
	global_load_lds_dwordx4 v[196:197], off
	v_lshl_add_u64 v[196:197], s[12:13], 0, v[130:131]
	s_mov_b32 m0, s27
	s_nop 0
	global_load_lds_dwordx4 v[196:197], off
	v_lshl_add_u64 v[196:197], s[12:13], 0, v[134:135]
	s_mov_b32 m0, s41
	s_nop 0
	global_load_lds_dwordx4 v[196:197], off
	v_lshl_add_u64 v[196:197], v[214:215], 0, s[10:11]
	s_mov_b32 m0, s23
	s_nop 0
	global_load_lds_dwordx4 v[196:197], off
	v_lshl_add_u64 v[196:197], v[216:217], 0, s[10:11]
	s_mov_b32 m0, s24
	s_nop 0
	global_load_lds_dwordx4 v[196:197], off
	s_waitcnt vmcnt(8)
	s_waitcnt lgkmcnt(0)
	s_barrier
	s_waitcnt lgkmcnt(0)
	v_mfma_f32_16x16x32_bf16 v[60:63], v[144:147], v[176:179], v[60:63]
	v_mfma_f32_16x16x32_bf16 v[56:59], v[152:155], v[176:179], v[56:59]
	v_mfma_f32_16x16x32_bf16 v[52:55], v[144:147], v[184:187], v[52:55]
	v_mfma_f32_16x16x32_bf16 v[48:51], v[152:155], v[184:187], v[48:51]
	v_mfma_f32_16x16x32_bf16 v[36:39], v[144:147], v[192:195], v[36:39]
	v_mfma_f32_16x16x32_bf16 v[32:35], v[152:155], v[192:195], v[32:35]
	v_mfma_f32_16x16x32_bf16 v[20:23], v[144:147], v[204:207], v[20:23]
	v_mfma_f32_16x16x32_bf16 v[16:19], v[152:155], v[204:207], v[16:19]
	v_mfma_f32_16x16x32_bf16 v[60:63], v[148:151], v[180:183], v[60:63]
	v_mfma_f32_16x16x32_bf16 v[56:59], v[156:159], v[180:183], v[56:59]
	v_mfma_f32_16x16x32_bf16 v[52:55], v[148:151], v[188:191], v[52:55]
	v_mfma_f32_16x16x32_bf16 v[48:51], v[156:159], v[188:191], v[48:51]
	v_mfma_f32_16x16x32_bf16 v[36:39], v[148:151], v[200:203], v[36:39]
	v_mfma_f32_16x16x32_bf16 v[32:35], v[156:159], v[200:203], v[32:35]
	v_mfma_f32_16x16x32_bf16 v[20:23], v[148:151], v[208:211], v[20:23]
	v_mfma_f32_16x16x32_bf16 v[16:19], v[156:159], v[208:211], v[16:19]
	v_mfma_f32_16x16x32_bf16 v[44:47], v[160:163], v[176:179], v[44:47]
	v_mfma_f32_16x16x32_bf16 v[40:43], v[168:171], v[176:179], v[40:43]
	v_mfma_f32_16x16x32_bf16 v[28:31], v[160:163], v[184:187], v[28:31]
	v_mfma_f32_16x16x32_bf16 v[24:27], v[168:171], v[184:187], v[24:27]
	v_mfma_f32_16x16x32_bf16 v[12:15], v[160:163], v[192:195], v[12:15]
	v_mfma_f32_16x16x32_bf16 v[8:11], v[168:171], v[192:195], v[8:11]
	v_mfma_f32_16x16x32_bf16 v[4:7], v[160:163], v[204:207], v[4:7]
	v_mfma_f32_16x16x32_bf16 v[0:3], v[168:171], v[204:207], v[0:3]
	v_mfma_f32_16x16x32_bf16 v[44:47], v[164:167], v[180:183], v[44:47]
	v_mfma_f32_16x16x32_bf16 v[40:43], v[172:175], v[180:183], v[40:43]
	v_mfma_f32_16x16x32_bf16 v[28:31], v[164:167], v[188:191], v[28:31]
	v_mfma_f32_16x16x32_bf16 v[24:27], v[172:175], v[188:191], v[24:27]
	v_mfma_f32_16x16x32_bf16 v[12:15], v[164:167], v[200:203], v[12:15]
	v_mfma_f32_16x16x32_bf16 v[8:11], v[172:175], v[200:203], v[8:11]
	v_mfma_f32_16x16x32_bf16 v[4:7], v[164:167], v[208:211], v[4:7]
	v_mfma_f32_16x16x32_bf16 v[0:3], v[172:175], v[208:211], v[0:3]
	s_barrier
	s_cmp_ge_u32 s8, s25
	s_mov_b32 s12, s8
	s_cbranch_scc0 .LBB0_3513
	s_cmpk_lt_u32 s33, 0x100
	s_cbranch_scc0 .LBB0_3516
	s_barrier

.LBB0_3517:
	s_cmp_lt_i32 s59, 26
	s_waitcnt vmcnt(0)
	s_barrier
	s_cbranch_scc1 .LBB0_3571
	s_waitcnt vmcnt(0)
	s_setprio 0
	s_barrier
	s_and_saveexec_b64 s[2:3], s[0:1]
	s_cbranch_execz .LBB0_3570
	s_waitcnt vmcnt(0) lgkmcnt(0)
	v_mov_b32_e32 v241, 0
	v_lshlrev_b32_e64 v254, 8, s31
	v_mov_b32_e32 v247, 1
	v_mov_b32_e32 v246, 0x3600
	global_atomic_add v248, v246, v247, s[60:61] sc0
